# K-loop compute segments: dead s_setprio flips and already-satisfied lgkmcnt waits removed (576 instructions) on top of seam + prologue edits
# baseline (speedup 1.0000x reference)
; #define PG8_STAGE(bufoff, gbase, voff) do { const unsigned long long gb_ = (unsigned long long)(gbase); _Pragma("unroll") for (int _i = 0; _i < 2; ++_i) { unsigned keep_; \
;         asm volatile("s_mov_b32 m0, %2\n\ts_nop 0\n\tglobal_load_lds_dwordx4 %0, %1" : : "v"((voff)[_i]), "s"(gb_), "s"((unsigned)(size_t)(lds + (bufoff) + ldsw + _i * 8192)) : "memory", "m0"); (void)keep_; } } while (0)
; #define PG8_LDA(dst, b, h) do { _Pragma("unroll") for (int m = 0; m < 4; ++m) _Pragma("unroll") for (int k = 0; k < 2; ++k) dst[m][k] = *(const PG8_LAS bf16x8*)(lds + PG8_SA(b, h) + aoff + m * 2048 + k * 1024); } while (0)
; #define PG8_LDB(dst, b, h) do { _Pragma("unroll") for (int n = 0; n < 2; ++n) _Pragma("unroll") for (int k = 0; k < 2; ++k) dst[n][k] = *(const PG8_LAS bf16x8*)(lds + PG8_SB(b, h) + boff + n * 2048 + k * 1024); } while (0)
; #define PG8_MMA(ai, bj, At, Bt) do { __builtin_amdgcn_s_setprio(1); _Pragma("unroll") for (int m = 0; m < 4; ++m) _Pragma("unroll") for (int n = 0; n < 2; ++n) _Pragma("unroll") for (int k = 0; k < 2; ++k) \
;         acc[ai][bj][m][n] = __builtin_amdgcn_mfma_f32_16x16x32_bf16(Bt[n][k], At[m][k], acc[ai][bj][m][n], 0, 0, 0); __builtin_amdgcn_s_setprio(0); } while (0)
; #define PG8_WAIT_V(n) asm volatile("s_waitcnt vmcnt(" #n ")" ::: "memory")
; #define PG8_BAR __builtin_amdgcn_s_barrier()
; template <class Epi, class Sched, bool ALIGN_EPI = false, bool SP2 = false>
; __device__ __forceinline__ void gemm_phase(PG8_LAS unsigned char* lds, const Gemm g, const Sched& S, const Epi& E) {
;     ...
;         for (int t = 0; t < nt; t += 2) {
;             const bool last = (t == nt - 2);
;     ...
;             const char* a1 = cA + PG8_KOFFA(t + 1);
;             const char* a2 = last ? nA : cA + PG8_KOFFA(t + 2); const char* b2 = last ? nB : cB + (size_t)(t + 2) * kstep;
;             const char* a3 = last ? nA + kstep : cA + PG8_KOFFA(t + 3); const char* b3 = b2 + kstep;
;     ...
;             if (last && has_next) S.a_ready(nxt);
;             if constexpr (SP2) {
;             PG8_LDB(B0, 0, 0); PG8_LDB(B1, 0, 1); PG8_SCHED; PG8_LDA(At, 0, 0); PG8_STAGE(PG8_SA(1, 1), a1 + hstepA, voffA);
;             PG8_WAIT_V(8); PG8_WAIT_L(0); PG8_BAR; PG8_MMA(0, 0, At, B0); PG8_MMA(0, 1, At, B1); PG8_BAR; PG8_SCHED;
;             PG8_LDA(At, 0, 1); PG8_STAGE(PG8_SB(0, 0), b2, voffB); PG8_STAGE(PG8_SB(0, 1), b2 + hstepB, voffB); PG8_STAGE(PG8_SA(0, 0), a2, voffA);
.LBB0_371:
	s_add_i32 s39, s73, 0xfffe8000
	s_and_b32 s38, s36, 0x100
	s_and_b32 s39, s39, 0xe0000
	s_or_b32 s38, s38, s39
	s_add_u32 s76, s8, s38
	s_addc_u32 s77, s9, 0
	s_add_u32 s38, s36, 0x100
	s_addc_u32 s39, s37, 0
	s_add_i32 s41, s73, 0xffff8000
	s_and_b32 s40, s38, 0x100
	s_and_b32 s41, s41, 0x1e0000
	s_or_b32 s40, s41, s40
	ds_read_b128 v[154:157], v167
	ds_read_b128 v[178:181], v167 offset:1024
	ds_read_b128 v[182:185], v167 offset:2048
	ds_read_b128 v[186:189], v167 offset:3072
	ds_read_b128 v[190:193], v169
	ds_read_b128 v[194:197], v169 offset:1024
	ds_read_b128 v[202:205], v169 offset:2048
	ds_read_b128 v[206:209], v169 offset:3072
	s_add_u32 s40, s8, s40
	s_addc_u32 s41, s9, 0
	s_add_u32 s78, s70, s36
	s_addc_u32 s37, s71, s37
	s_add_i32 s42, s36, 0x180
	s_and_b32 s42, s42, 0x180
	s_and_b32 s43, s73, 0x1e0000
	s_or_b32 s42, s43, s42
	s_add_u32 s79, s8, s42
	s_addc_u32 s80, s9, 0
	s_cmpk_eq_i32 s36, 0xf00
	s_cselect_b32 s43, s0, s41
	s_cselect_b32 s41, s23, s37
	s_cselect_b32 s37, s69, s80
	s_cselect_b32 s36, s31, s79
	s_cselect_b32 s42, s1, s40
	s_cselect_b32 s40, s25, s78
	ds_read_b128 v[210:213], v172
	ds_read_b128 v[214:217], v172 offset:1024
	ds_read_b128 v[218:221], v172 offset:2048
	ds_read_b128 v[222:225], v172 offset:3072
	ds_read_b128 v[226:229], v172 offset:4096
	ds_read_b128 v[230:233], v172 offset:5120
	ds_read_b128 v[234:237], v172 offset:6144
	ds_read_b128 v[238:241], v172 offset:7168
	s_add_u32 s76, s76, 0x10080
	s_addc_u32 s77, s77, 0
	s_mov_b32 m0, s63
	s_nop 0
	global_load_lds_dwordx4 v159, s[76:77]
	s_nop 0
	s_mov_b32 m0, s64
	s_nop 0
	global_load_lds_dwordx4 v163, s[76:77]
	s_waitcnt vmcnt(8)
	s_waitcnt lgkmcnt(0)
	s_barrier
	v_mfma_f32_16x16x32_bf16 v[124:127], v[154:157], v[210:213], v[124:127]
	v_mfma_f32_16x16x32_bf16 v[116:119], v[182:185], v[210:213], v[116:119]
	v_mfma_f32_16x16x32_bf16 v[108:111], v[154:157], v[218:221], v[108:111]
	v_mfma_f32_16x16x32_bf16 v[100:103], v[182:185], v[218:221], v[100:103]
	v_mfma_f32_16x16x32_bf16 v[92:95], v[154:157], v[226:229], v[92:95]
	v_mfma_f32_16x16x32_bf16 v[84:87], v[182:185], v[226:229], v[84:87]
	v_mfma_f32_16x16x32_bf16 v[76:79], v[154:157], v[234:237], v[76:79]
	v_mfma_f32_16x16x32_bf16 v[68:71], v[182:185], v[234:237], v[68:71]
	v_mfma_f32_16x16x32_bf16 v[124:127], v[178:181], v[214:217], v[124:127]
	v_mfma_f32_16x16x32_bf16 v[116:119], v[186:189], v[214:217], v[116:119]
	v_mfma_f32_16x16x32_bf16 v[108:111], v[178:181], v[222:225], v[108:111]
	v_mfma_f32_16x16x32_bf16 v[100:103], v[186:189], v[222:225], v[100:103]
	v_mfma_f32_16x16x32_bf16 v[92:95], v[178:181], v[230:233], v[92:95]
	v_mfma_f32_16x16x32_bf16 v[84:87], v[186:189], v[230:233], v[84:87]
	v_mfma_f32_16x16x32_bf16 v[76:79], v[178:181], v[238:241], v[76:79]
	v_mfma_f32_16x16x32_bf16 v[68:71], v[186:189], v[238:241], v[68:71]
	v_mfma_f32_16x16x32_bf16 v[120:123], v[190:193], v[210:213], v[120:123]
	v_mfma_f32_16x16x32_bf16 v[112:115], v[202:205], v[210:213], v[112:115]
	v_mfma_f32_16x16x32_bf16 v[104:107], v[190:193], v[218:221], v[104:107]
	v_mfma_f32_16x16x32_bf16 v[96:99], v[202:205], v[218:221], v[96:99]
	v_mfma_f32_16x16x32_bf16 v[88:91], v[190:193], v[226:229], v[88:91]
	v_mfma_f32_16x16x32_bf16 v[80:83], v[202:205], v[226:229], v[80:83]
	v_mfma_f32_16x16x32_bf16 v[72:75], v[190:193], v[234:237], v[72:75]
	v_mfma_f32_16x16x32_bf16 v[64:67], v[202:205], v[234:237], v[64:67]
	v_mfma_f32_16x16x32_bf16 v[120:123], v[194:197], v[214:217], v[120:123]
	v_mfma_f32_16x16x32_bf16 v[112:115], v[206:209], v[214:217], v[112:115]
	v_mfma_f32_16x16x32_bf16 v[104:107], v[194:197], v[222:225], v[104:107]
	v_mfma_f32_16x16x32_bf16 v[96:99], v[206:209], v[222:225], v[96:99]
	v_mfma_f32_16x16x32_bf16 v[88:91], v[194:197], v[230:233], v[88:91]
	v_mfma_f32_16x16x32_bf16 v[80:83], v[206:209], v[230:233], v[80:83]
	v_mfma_f32_16x16x32_bf16 v[72:75], v[194:197], v[238:241], v[72:75]
	v_mfma_f32_16x16x32_bf16 v[64:67], v[206:209], v[238:241], v[64:67]
	s_barrier
	ds_read_b128 v[210:213], v172 offset:16384
	ds_read_b128 v[214:217], v172 offset:17408
	ds_read_b128 v[218:221], v172 offset:18432
	ds_read_b128 v[222:225], v172 offset:19456
	ds_read_b128 v[226:229], v172 offset:20480
	ds_read_b128 v[230:233], v172 offset:21504
	ds_read_b128 v[234:237], v172 offset:22528
	ds_read_b128 v[238:241], v172 offset:23552
	s_mov_b32 m0, s47
	s_nop 0
	global_load_lds_dwordx4 v161, s[40:41]
	s_add_u32 s76, s40, 0x80000
	s_mov_b32 m0, s48
	s_nop 0
	global_load_lds_dwordx4 v165, s[40:41]
	s_addc_u32 s77, s41, 0
	s_mov_b32 m0, s49
	s_nop 0
	global_load_lds_dwordx4 v161, s[76:77]
	s_nop 0
	s_mov_b32 m0, s50
	s_nop 0
	global_load_lds_dwordx4 v165, s[76:77]
	s_nop 0
	s_mov_b32 m0, s35
	s_nop 0
	global_load_lds_dwordx4 v159, s[42:43]
	s_nop 0
	s_mov_b32 m0, s51
	s_nop 0
	global_load_lds_dwordx4 v163, s[42:43]
	s_waitcnt vmcnt(8)
	s_waitcnt lgkmcnt(0)
	s_barrier
; #define PG8_STAGE(bufoff, gbase, voff) do { const unsigned long long gb_ = (unsigned long long)(gbase); _Pragma("unroll") for (int _i = 0; _i < 2; ++_i) { unsigned keep_; \
;         asm volatile("s_mov_b32 m0, %2\n\ts_nop 0\n\tglobal_load_lds_dwordx4 %0, %1" : : "v"((voff)[_i]), "s"(gb_), "s"((unsigned)(size_t)(lds + (bufoff) + ldsw + _i * 8192)) : "memory", "m0"); (void)keep_; } } while (0)
; #define PG8_LDA(dst, b, h) do { _Pragma("unroll") for (int m = 0; m < 4; ++m) _Pragma("unroll") for (int k = 0; k < 2; ++k) dst[m][k] = *(const PG8_LAS bf16x8*)(lds + PG8_SA(b, h) + aoff + m * 2048 + k * 1024); } while (0)
; #define PG8_LDB(dst, b, h) do { _Pragma("unroll") for (int n = 0; n < 2; ++n) _Pragma("unroll") for (int k = 0; k < 2; ++k) dst[n][k] = *(const PG8_LAS bf16x8*)(lds + PG8_SB(b, h) + boff + n * 2048 + k * 1024); } while (0)
; #define PG8_MMA(ai, bj, At, Bt) do { __builtin_amdgcn_s_setprio(1); _Pragma("unroll") for (int m = 0; m < 4; ++m) _Pragma("unroll") for (int n = 0; n < 2; ++n) _Pragma("unroll") for (int k = 0; k < 2; ++k) \
;         acc[ai][bj][m][n] = __builtin_amdgcn_mfma_f32_16x16x32_bf16(Bt[n][k], At[m][k], acc[ai][bj][m][n], 0, 0, 0); __builtin_amdgcn_s_setprio(0); } while (0)
; #define PG8_WAIT_V(n) asm volatile("s_waitcnt vmcnt(" #n ")" ::: "memory")
; #define PG8_WAIT_L(n) asm volatile("s_waitcnt lgkmcnt(" #n ")" ::: "memory")
; #define PG8_BAR __builtin_amdgcn_s_barrier()
; #define PG8_SCHED __builtin_amdgcn_sched_barrier(0)
; template <class Epi, class Sched, bool ALIGN_EPI = false, bool SP2 = false>
; __device__ __forceinline__ void gemm_phase(PG8_LAS unsigned char* lds, const Gemm g, const Sched& S, const Epi& E) {
;     ...
;             PG8_WAIT_V(8); PG8_WAIT_L(0); PG8_BAR; PG8_MMA(1, 0, At, B0); PG8_MMA(1, 1, At, B1); PG8_BAR; PG8_SCHED;
;             PG8_LDB(B0, 1, 0); PG8_LDB(B1, 1, 1); PG8_SCHED; PG8_LDA(At, 1, 0); PG8_STAGE(PG8_SA(0, 1), a2 + hstepA, voffA);
;             PG8_WAIT_V(8); PG8_WAIT_L(0); PG8_BAR; PG8_MMA(0, 0, At, B0); PG8_MMA(0, 1, At, B1); PG8_BAR; PG8_SCHED;
	v_mfma_f32_16x16x32_bf16 v[60:63], v[154:157], v[210:213], v[60:63]
	v_mfma_f32_16x16x32_bf16 v[52:55], v[182:185], v[210:213], v[52:55]
	v_mfma_f32_16x16x32_bf16 v[44:47], v[154:157], v[218:221], v[44:47]
	v_mfma_f32_16x16x32_bf16 v[36:39], v[182:185], v[218:221], v[36:39]
	v_mfma_f32_16x16x32_bf16 v[28:31], v[154:157], v[226:229], v[28:31]
	v_mfma_f32_16x16x32_bf16 v[20:23], v[182:185], v[226:229], v[20:23]
	v_mfma_f32_16x16x32_bf16 v[12:15], v[154:157], v[234:237], v[12:15]
	v_mfma_f32_16x16x32_bf16 v[4:7], v[182:185], v[234:237], v[4:7]
	v_mfma_f32_16x16x32_bf16 v[60:63], v[178:181], v[214:217], v[60:63]
	v_mfma_f32_16x16x32_bf16 v[52:55], v[186:189], v[214:217], v[52:55]
	v_mfma_f32_16x16x32_bf16 v[44:47], v[178:181], v[222:225], v[44:47]
	v_mfma_f32_16x16x32_bf16 v[36:39], v[186:189], v[222:225], v[36:39]
	v_mfma_f32_16x16x32_bf16 v[28:31], v[178:181], v[230:233], v[28:31]
	v_mfma_f32_16x16x32_bf16 v[20:23], v[186:189], v[230:233], v[20:23]
	v_mfma_f32_16x16x32_bf16 v[12:15], v[178:181], v[238:241], v[12:15]
	v_mfma_f32_16x16x32_bf16 v[4:7], v[186:189], v[238:241], v[4:7]
	v_mfma_f32_16x16x32_bf16 v[56:59], v[190:193], v[210:213], v[56:59]
	v_mfma_f32_16x16x32_bf16 v[48:51], v[202:205], v[210:213], v[48:51]
	v_mfma_f32_16x16x32_bf16 v[40:43], v[190:193], v[218:221], v[40:43]
	v_mfma_f32_16x16x32_bf16 v[32:35], v[202:205], v[218:221], v[32:35]
	v_mfma_f32_16x16x32_bf16 v[24:27], v[190:193], v[226:229], v[24:27]
	v_mfma_f32_16x16x32_bf16 v[16:19], v[202:205], v[226:229], v[16:19]
	v_mfma_f32_16x16x32_bf16 v[8:11], v[190:193], v[234:237], v[8:11]
	v_mfma_f32_16x16x32_bf16 v[0:3], v[202:205], v[234:237], v[0:3]
	v_mfma_f32_16x16x32_bf16 v[56:59], v[194:197], v[214:217], v[56:59]
	v_mfma_f32_16x16x32_bf16 v[48:51], v[206:209], v[214:217], v[48:51]
	v_mfma_f32_16x16x32_bf16 v[40:43], v[194:197], v[222:225], v[40:43]
	v_mfma_f32_16x16x32_bf16 v[32:35], v[206:209], v[222:225], v[32:35]
	v_mfma_f32_16x16x32_bf16 v[24:27], v[194:197], v[230:233], v[24:27]
	v_mfma_f32_16x16x32_bf16 v[16:19], v[206:209], v[230:233], v[16:19]
	v_mfma_f32_16x16x32_bf16 v[8:11], v[194:197], v[238:241], v[8:11]
	v_mfma_f32_16x16x32_bf16 v[0:3], v[206:209], v[238:241], v[0:3]
	s_barrier
	ds_read_b128 v[154:157], v173
	ds_read_b128 v[178:181], v173 offset:1024
	ds_read_b128 v[182:185], v173 offset:2048
	ds_read_b128 v[186:189], v173 offset:3072
	ds_read_b128 v[190:193], v174
	ds_read_b128 v[194:197], v174 offset:1024
	ds_read_b128 v[202:205], v174 offset:2048
	ds_read_b128 v[206:209], v174 offset:3072
	ds_read_b128 v[210:213], v172 offset:32768
	ds_read_b128 v[214:217], v172 offset:33792
	ds_read_b128 v[218:221], v172 offset:34816
	ds_read_b128 v[222:225], v172 offset:35840
	ds_read_b128 v[226:229], v172 offset:36864
	ds_read_b128 v[230:233], v172 offset:37888
	ds_read_b128 v[234:237], v172 offset:38912
	ds_read_b128 v[238:241], v172 offset:39936
	s_add_u32 s42, s42, 0x10000
	s_addc_u32 s43, s43, 0
	s_mov_b32 m0, s52
	s_nop 0
	global_load_lds_dwordx4 v159, s[42:43]
	s_nop 0
	s_mov_b32 m0, s53
	s_nop 0
	global_load_lds_dwordx4 v163, s[42:43]
	s_waitcnt vmcnt(8)
	s_waitcnt lgkmcnt(0)
	s_barrier
	v_mfma_f32_16x16x32_bf16 v[124:127], v[154:157], v[210:213], v[124:127]
	v_mfma_f32_16x16x32_bf16 v[116:119], v[182:185], v[210:213], v[116:119]
	v_mfma_f32_16x16x32_bf16 v[108:111], v[154:157], v[218:221], v[108:111]
	v_mfma_f32_16x16x32_bf16 v[100:103], v[182:185], v[218:221], v[100:103]
	v_mfma_f32_16x16x32_bf16 v[92:95], v[154:157], v[226:229], v[92:95]
	v_mfma_f32_16x16x32_bf16 v[84:87], v[182:185], v[226:229], v[84:87]
	v_mfma_f32_16x16x32_bf16 v[76:79], v[154:157], v[234:237], v[76:79]
	v_mfma_f32_16x16x32_bf16 v[68:71], v[182:185], v[234:237], v[68:71]
	v_mfma_f32_16x16x32_bf16 v[124:127], v[178:181], v[214:217], v[124:127]
	v_mfma_f32_16x16x32_bf16 v[116:119], v[186:189], v[214:217], v[116:119]
	v_mfma_f32_16x16x32_bf16 v[108:111], v[178:181], v[222:225], v[108:111]
	v_mfma_f32_16x16x32_bf16 v[100:103], v[186:189], v[222:225], v[100:103]
	v_mfma_f32_16x16x32_bf16 v[92:95], v[178:181], v[230:233], v[92:95]
	v_mfma_f32_16x16x32_bf16 v[84:87], v[186:189], v[230:233], v[84:87]
	v_mfma_f32_16x16x32_bf16 v[76:79], v[178:181], v[238:241], v[76:79]
	v_mfma_f32_16x16x32_bf16 v[68:71], v[186:189], v[238:241], v[68:71]
	v_mfma_f32_16x16x32_bf16 v[120:123], v[190:193], v[210:213], v[120:123]
	v_mfma_f32_16x16x32_bf16 v[112:115], v[202:205], v[210:213], v[112:115]
	v_mfma_f32_16x16x32_bf16 v[104:107], v[190:193], v[218:221], v[104:107]
	v_mfma_f32_16x16x32_bf16 v[96:99], v[202:205], v[218:221], v[96:99]
	v_mfma_f32_16x16x32_bf16 v[88:91], v[190:193], v[226:229], v[88:91]
	v_mfma_f32_16x16x32_bf16 v[80:83], v[202:205], v[226:229], v[80:83]
	v_mfma_f32_16x16x32_bf16 v[72:75], v[190:193], v[234:237], v[72:75]
	v_mfma_f32_16x16x32_bf16 v[64:67], v[202:205], v[234:237], v[64:67]
	v_mfma_f32_16x16x32_bf16 v[120:123], v[194:197], v[214:217], v[120:123]
	v_mfma_f32_16x16x32_bf16 v[112:115], v[206:209], v[214:217], v[112:115]
	v_mfma_f32_16x16x32_bf16 v[104:107], v[194:197], v[222:225], v[104:107]
	v_mfma_f32_16x16x32_bf16 v[96:99], v[206:209], v[222:225], v[96:99]
	v_mfma_f32_16x16x32_bf16 v[88:91], v[194:197], v[230:233], v[88:91]
	v_mfma_f32_16x16x32_bf16 v[80:83], v[206:209], v[230:233], v[80:83]
	v_mfma_f32_16x16x32_bf16 v[72:75], v[194:197], v[238:241], v[72:75]
	v_mfma_f32_16x16x32_bf16 v[64:67], v[206:209], v[238:241], v[64:67]
	s_barrier
; #define PG8_STAGE(bufoff, gbase, voff) do { const unsigned long long gb_ = (unsigned long long)(gbase); _Pragma("unroll") for (int _i = 0; _i < 2; ++_i) { unsigned keep_; \
;         asm volatile("s_mov_b32 m0, %2\n\ts_nop 0\n\tglobal_load_lds_dwordx4 %0, %1" : : "v"((voff)[_i]), "s"(gb_), "s"((unsigned)(size_t)(lds + (bufoff) + ldsw + _i * 8192)) : "memory", "m0"); (void)keep_; } } while (0)
; #define PG8_LDA(dst, b, h) do { _Pragma("unroll") for (int m = 0; m < 4; ++m) _Pragma("unroll") for (int k = 0; k < 2; ++k) dst[m][k] = *(const PG8_LAS bf16x8*)(lds + PG8_SA(b, h) + aoff + m * 2048 + k * 1024); } while (0)
; #define PG8_MMA(ai, bj, At, Bt) do { __builtin_amdgcn_s_setprio(1); _Pragma("unroll") for (int m = 0; m < 4; ++m) _Pragma("unroll") for (int n = 0; n < 2; ++n) _Pragma("unroll") for (int k = 0; k < 2; ++k) \
;         acc[ai][bj][m][n] = __builtin_amdgcn_mfma_f32_16x16x32_bf16(Bt[n][k], At[m][k], acc[ai][bj][m][n], 0, 0, 0); __builtin_amdgcn_s_setprio(0); } while (0)
; #define PG8_WAIT_V(n) asm volatile("s_waitcnt vmcnt(" #n ")" ::: "memory")
; #define PG8_WAIT_L(n) asm volatile("s_waitcnt lgkmcnt(" #n ")" ::: "memory")
; #define PG8_BAR __builtin_amdgcn_s_barrier()
; #define PG8_SCHED __builtin_amdgcn_sched_barrier(0)
; template <class Epi, class Sched, bool ALIGN_EPI = false, bool SP2 = false>
; __device__ __forceinline__ void gemm_phase(PG8_LAS unsigned char* lds, const Gemm g, const Sched& S, const Epi& E) {
;     ...
;         for (int t = 0; t < nt; t += 2) {
;     ...
;             PG8_LDA(At, 1, 1); PG8_STAGE(PG8_SB(1, 0), b3, voffB); PG8_STAGE(PG8_SB(1, 1), b3 + hstepB, voffB); PG8_STAGE(PG8_SA(1, 0), a3, voffA);
;             PG8_WAIT_V(8); PG8_WAIT_L(0); PG8_BAR; PG8_MMA(1, 0, At, B0); PG8_MMA(1, 1, At, B1); PG8_BAR; PG8_SCHED;
	ds_read_b128 v[210:213], v172 offset:49152
	ds_read_b128 v[214:217], v172 offset:50176
	ds_read_b128 v[218:221], v172 offset:51200
	ds_read_b128 v[222:225], v172 offset:52224
	ds_read_b128 v[226:229], v172 offset:53248
	ds_read_b128 v[230:233], v172 offset:54272
	ds_read_b128 v[234:237], v172 offset:55296
	ds_read_b128 v[238:241], v172 offset:56320
	s_add_u32 s42, s40, 0x80
	s_addc_u32 s43, s41, 0
	s_mov_b32 m0, s57
	s_nop 0
	global_load_lds_dwordx4 v161, s[42:43]
	s_add_u32 s40, s40, 0x80080
	s_mov_b32 m0, s58
	s_nop 0
	global_load_lds_dwordx4 v165, s[42:43]
	s_addc_u32 s41, s41, 0
	s_mov_b32 m0, s61
	s_nop 0
	global_load_lds_dwordx4 v161, s[40:41]
	s_nop 0
	s_mov_b32 m0, s62
	s_nop 0
	global_load_lds_dwordx4 v165, s[40:41]
	s_nop 0
	s_mov_b32 m0, s59
	s_nop 0
	global_load_lds_dwordx4 v159, s[36:37]
	s_nop 0
	s_mov_b32 m0, s60
	s_nop 0
	global_load_lds_dwordx4 v163, s[36:37]
	s_waitcnt vmcnt(8)
	s_waitcnt lgkmcnt(0)
	s_barrier
	v_mfma_f32_16x16x32_bf16 v[60:63], v[154:157], v[210:213], v[60:63]
	v_mfma_f32_16x16x32_bf16 v[52:55], v[182:185], v[210:213], v[52:55]
	v_mfma_f32_16x16x32_bf16 v[44:47], v[154:157], v[218:221], v[44:47]
	v_mfma_f32_16x16x32_bf16 v[36:39], v[182:185], v[218:221], v[36:39]
	v_mfma_f32_16x16x32_bf16 v[28:31], v[154:157], v[226:229], v[28:31]
	v_mfma_f32_16x16x32_bf16 v[20:23], v[182:185], v[226:229], v[20:23]
	v_mfma_f32_16x16x32_bf16 v[12:15], v[154:157], v[234:237], v[12:15]
	v_mfma_f32_16x16x32_bf16 v[4:7], v[182:185], v[234:237], v[4:7]
	v_mfma_f32_16x16x32_bf16 v[60:63], v[178:181], v[214:217], v[60:63]
	v_mfma_f32_16x16x32_bf16 v[52:55], v[186:189], v[214:217], v[52:55]
	v_mfma_f32_16x16x32_bf16 v[44:47], v[178:181], v[222:225], v[44:47]
	v_mfma_f32_16x16x32_bf16 v[36:39], v[186:189], v[222:225], v[36:39]
	v_mfma_f32_16x16x32_bf16 v[28:31], v[178:181], v[230:233], v[28:31]
	v_mfma_f32_16x16x32_bf16 v[20:23], v[186:189], v[230:233], v[20:23]
	v_mfma_f32_16x16x32_bf16 v[12:15], v[178:181], v[238:241], v[12:15]
	v_mfma_f32_16x16x32_bf16 v[4:7], v[186:189], v[238:241], v[4:7]
	v_mfma_f32_16x16x32_bf16 v[56:59], v[190:193], v[210:213], v[56:59]
	v_mfma_f32_16x16x32_bf16 v[48:51], v[202:205], v[210:213], v[48:51]
	v_mfma_f32_16x16x32_bf16 v[40:43], v[190:193], v[218:221], v[40:43]
	v_mfma_f32_16x16x32_bf16 v[32:35], v[202:205], v[218:221], v[32:35]
	v_mfma_f32_16x16x32_bf16 v[24:27], v[190:193], v[226:229], v[24:27]
	v_mfma_f32_16x16x32_bf16 v[16:19], v[202:205], v[226:229], v[16:19]
	v_mfma_f32_16x16x32_bf16 v[8:11], v[190:193], v[234:237], v[8:11]
	v_mfma_f32_16x16x32_bf16 v[0:3], v[202:205], v[234:237], v[0:3]
	v_mfma_f32_16x16x32_bf16 v[56:59], v[194:197], v[214:217], v[56:59]
	v_mfma_f32_16x16x32_bf16 v[48:51], v[206:209], v[214:217], v[48:51]
	v_mfma_f32_16x16x32_bf16 v[40:43], v[194:197], v[222:225], v[40:43]
	v_mfma_f32_16x16x32_bf16 v[32:35], v[206:209], v[222:225], v[32:35]
	v_mfma_f32_16x16x32_bf16 v[24:27], v[194:197], v[230:233], v[24:27]
	v_mfma_f32_16x16x32_bf16 v[16:19], v[206:209], v[230:233], v[16:19]
	v_mfma_f32_16x16x32_bf16 v[8:11], v[194:197], v[238:241], v[8:11]
	v_mfma_f32_16x16x32_bf16 v[0:3], v[206:209], v[238:241], v[0:3]
	s_barrier
	s_add_i32 s72, s72, 2
	s_add_i32 s73, s73, 0x10000
	s_cmp_gt_u32 s72, 29
	s_mov_b64 s[36:37], s[38:39]
	s_cbranch_scc0 .LBB0_371
	s_and_b64 vcc, exec, s[20:21]
	s_cbranch_vccz .LBB0_374
	s_barrier

; #define PG8_STAGE(bufoff, gbase, voff) do { const unsigned long long gb_ = (unsigned long long)(gbase); _Pragma("unroll") for (int _i = 0; _i < 2; ++_i) { unsigned keep_; \
;         asm volatile("s_mov_b32 m0, %2\n\ts_nop 0\n\tglobal_load_lds_dwordx4 %0, %1" : : "v"((voff)[_i]), "s"(gb_), "s"((unsigned)(size_t)(lds + (bufoff) + ldsw + _i * 8192)) : "memory", "m0"); (void)keep_; } } while (0)
; #define PG8_LDA(dst, b, h) do { _Pragma("unroll") for (int m = 0; m < 4; ++m) _Pragma("unroll") for (int k = 0; k < 2; ++k) dst[m][k] = *(const PG8_LAS bf16x8*)(lds + PG8_SA(b, h) + aoff + m * 2048 + k * 1024); } while (0)
; #define PG8_LDB(dst, b, h) do { _Pragma("unroll") for (int n = 0; n < 2; ++n) _Pragma("unroll") for (int k = 0; k < 2; ++k) dst[n][k] = *(const PG8_LAS bf16x8*)(lds + PG8_SB(b, h) + boff + n * 2048 + k * 1024); } while (0)
; #define PG8_MMA(ai, bj, At, Bt) do { __builtin_amdgcn_s_setprio(1); _Pragma("unroll") for (int m = 0; m < 4; ++m) _Pragma("unroll") for (int n = 0; n < 2; ++n) _Pragma("unroll") for (int k = 0; k < 2; ++k) \
;         acc[ai][bj][m][n] = __builtin_amdgcn_mfma_f32_16x16x32_bf16(Bt[n][k], At[m][k], acc[ai][bj][m][n], 0, 0, 0); __builtin_amdgcn_s_setprio(0); } while (0)
; template <class Epi, class Sched, bool ALIGN_EPI = false, bool SP2 = false>
; __device__ __forceinline__ void gemm_phase(PG8_LAS unsigned char* lds, const Gemm g, const Sched& S, const Epi& E) {
;     ...
;         for (int t = 0; t < nt; t += 2) {
;             const bool last = (t == nt - 2);
;     ...
;             const char* a1 = cA + PG8_KOFFA(t + 1);
;             const char* a2 = last ? nA : cA + PG8_KOFFA(t + 2); const char* b2 = last ? nB : cB + (size_t)(t + 2) * kstep;
;             const char* a3 = last ? nA + kstep : cA + PG8_KOFFA(t + 3); const char* b3 = b2 + kstep;
;     ...
;             if (last && has_next) S.a_ready(nxt);
;             if constexpr (SP2) {
;             PG8_LDB(B0, 0, 0); PG8_LDB(B1, 0, 1); PG8_SCHED; PG8_LDA(At, 0, 0); PG8_STAGE(PG8_SA(1, 1), a1 + hstepA, voffA);
;             PG8_WAIT_V(8); PG8_WAIT_L(0); PG8_BAR; PG8_MMA(0, 0, At, B0); PG8_MMA(0, 1, At, B1); PG8_BAR; PG8_SCHED;
;             PG8_LDA(At, 0, 1); PG8_STAGE(PG8_SB(0, 0), b2, voffB); PG8_STAGE(PG8_SB(0, 1), b2 + hstepB, voffB); PG8_STAGE(PG8_SA(0, 0), a2, voffA);
;             PG8_WAIT_V(8); PG8_WAIT_L(0); PG8_BAR; PG8_MMA(1, 0, At, B0); PG8_MMA(1, 1, At, B1); PG8_BAR; PG8_SCHED;
.LBB0_511:
	ds_read_b128 v[128:131], v180
	ds_read_b128 v[132:135], v180 offset:1024
	ds_read_b128 v[136:139], v180 offset:2048
	ds_read_b128 v[140:143], v180 offset:3072
	ds_read_b128 v[168:171], v181
	ds_read_b128 v[172:175], v181 offset:1024
	ds_read_b128 v[186:189], v181 offset:2048
	ds_read_b128 v[190:193], v181 offset:3072
	s_add_u32 s28, s26, 0x10000
	s_addc_u32 s29, s27, 0
	s_cmpk_eq_i32 s64, 0x54
	s_cselect_b32 s36, s10, s28
	s_cselect_b32 s37, s11, s29
	s_cselect_b32 s34, s24, s0
	s_cselect_b32 s35, s25, s1
	s_add_u32 s30, s36, 0x80
	s_addc_u32 s31, s37, 0
	ds_read_b128 v[194:197], v182
	ds_read_b128 v[202:205], v182 offset:1024
	ds_read_b128 v[206:209], v182 offset:2048
	ds_read_b128 v[210:213], v182 offset:3072
	ds_read_b128 v[214:217], v182 offset:4096
	ds_read_b128 v[218:221], v182 offset:5120
	ds_read_b128 v[222:225], v182 offset:6144
	ds_read_b128 v[226:229], v182 offset:7168
	s_add_u32 s26, s26, 0x8080
	s_addc_u32 s27, s27, 0
	s_mov_b32 m0, s56
	s_nop 0
	global_load_lds_dwordx4 v176, s[26:27]
	s_nop 0
	s_mov_b32 m0, s57
	s_nop 0
	global_load_lds_dwordx4 v178, s[26:27]
	s_waitcnt vmcnt(8)
	s_waitcnt lgkmcnt(0)
	s_barrier
	v_mfma_f32_16x16x32_bf16 v[124:127], v[128:131], v[194:197], v[124:127]
	v_mfma_f32_16x16x32_bf16 v[120:123], v[136:139], v[194:197], v[120:123]
	v_mfma_f32_16x16x32_bf16 v[108:111], v[128:131], v[206:209], v[108:111]
	v_mfma_f32_16x16x32_bf16 v[104:107], v[136:139], v[206:209], v[104:107]
	v_mfma_f32_16x16x32_bf16 v[92:95], v[128:131], v[214:217], v[92:95]
	v_mfma_f32_16x16x32_bf16 v[88:91], v[136:139], v[214:217], v[88:91]
	v_mfma_f32_16x16x32_bf16 v[76:79], v[128:131], v[222:225], v[76:79]
	v_mfma_f32_16x16x32_bf16 v[72:75], v[136:139], v[222:225], v[72:75]
	v_mfma_f32_16x16x32_bf16 v[124:127], v[132:135], v[202:205], v[124:127]
	v_mfma_f32_16x16x32_bf16 v[120:123], v[140:143], v[202:205], v[120:123]
	v_mfma_f32_16x16x32_bf16 v[108:111], v[132:135], v[210:213], v[108:111]
	v_mfma_f32_16x16x32_bf16 v[104:107], v[140:143], v[210:213], v[104:107]
	v_mfma_f32_16x16x32_bf16 v[92:95], v[132:135], v[218:221], v[92:95]
	v_mfma_f32_16x16x32_bf16 v[88:91], v[140:143], v[218:221], v[88:91]
	v_mfma_f32_16x16x32_bf16 v[76:79], v[132:135], v[226:229], v[76:79]
	v_mfma_f32_16x16x32_bf16 v[72:75], v[140:143], v[226:229], v[72:75]
	v_mfma_f32_16x16x32_bf16 v[116:119], v[168:171], v[194:197], v[116:119]
	v_mfma_f32_16x16x32_bf16 v[112:115], v[186:189], v[194:197], v[112:115]
	v_mfma_f32_16x16x32_bf16 v[100:103], v[168:171], v[206:209], v[100:103]
	v_mfma_f32_16x16x32_bf16 v[96:99], v[186:189], v[206:209], v[96:99]
	v_mfma_f32_16x16x32_bf16 v[84:87], v[168:171], v[214:217], v[84:87]
	v_mfma_f32_16x16x32_bf16 v[80:83], v[186:189], v[214:217], v[80:83]
	v_mfma_f32_16x16x32_bf16 v[68:71], v[168:171], v[222:225], v[68:71]
	v_mfma_f32_16x16x32_bf16 v[64:67], v[186:189], v[222:225], v[64:67]
	v_mfma_f32_16x16x32_bf16 v[116:119], v[172:175], v[202:205], v[116:119]
	v_mfma_f32_16x16x32_bf16 v[112:115], v[190:193], v[202:205], v[112:115]
	v_mfma_f32_16x16x32_bf16 v[100:103], v[172:175], v[210:213], v[100:103]
	v_mfma_f32_16x16x32_bf16 v[96:99], v[190:193], v[210:213], v[96:99]
	v_mfma_f32_16x16x32_bf16 v[84:87], v[172:175], v[218:221], v[84:87]
	v_mfma_f32_16x16x32_bf16 v[80:83], v[190:193], v[218:221], v[80:83]
	v_mfma_f32_16x16x32_bf16 v[68:71], v[172:175], v[226:229], v[68:71]
	v_mfma_f32_16x16x32_bf16 v[64:67], v[190:193], v[226:229], v[64:67]
	s_barrier
	ds_read_b128 v[194:197], v182 offset:16384
	ds_read_b128 v[202:205], v182 offset:17408
	ds_read_b128 v[206:209], v182 offset:18432
	ds_read_b128 v[210:213], v182 offset:19456
	ds_read_b128 v[214:217], v182 offset:20480
	ds_read_b128 v[218:221], v182 offset:21504
	ds_read_b128 v[222:225], v182 offset:22528
	ds_read_b128 v[226:229], v182 offset:23552
	s_mov_b32 m0, s42
	s_nop 0
	global_load_lds_dwordx4 v177, s[34:35]
	s_add_u32 s26, s34, 0x160000
	s_mov_b32 m0, s43
	s_nop 0
	global_load_lds_dwordx4 v179, s[34:35]
	s_addc_u32 s27, s35, 0
	s_mov_b32 m0, s44
	s_nop 0
	global_load_lds_dwordx4 v177, s[26:27]
	s_nop 0
	s_mov_b32 m0, s45
	s_nop 0
	global_load_lds_dwordx4 v179, s[26:27]
	s_nop 0
	s_mov_b32 m0, s41
	s_nop 0
	global_load_lds_dwordx4 v176, s[36:37]
	s_nop 0
	s_mov_b32 m0, s46
	s_nop 0
	global_load_lds_dwordx4 v178, s[36:37]
	s_waitcnt vmcnt(8)
	s_waitcnt lgkmcnt(0)
	s_barrier
	v_mfma_f32_16x16x32_bf16 v[60:63], v[128:131], v[194:197], v[60:63]
	v_mfma_f32_16x16x32_bf16 v[56:59], v[136:139], v[194:197], v[56:59]
	v_mfma_f32_16x16x32_bf16 v[44:47], v[128:131], v[206:209], v[44:47]
	v_mfma_f32_16x16x32_bf16 v[40:43], v[136:139], v[206:209], v[40:43]
	v_mfma_f32_16x16x32_bf16 v[28:31], v[128:131], v[214:217], v[28:31]
	v_mfma_f32_16x16x32_bf16 v[24:27], v[136:139], v[214:217], v[24:27]
	v_mfma_f32_16x16x32_bf16 v[12:15], v[128:131], v[222:225], v[12:15]
	v_mfma_f32_16x16x32_bf16 v[8:11], v[136:139], v[222:225], v[8:11]
	v_mfma_f32_16x16x32_bf16 v[60:63], v[132:135], v[202:205], v[60:63]
	v_mfma_f32_16x16x32_bf16 v[56:59], v[140:143], v[202:205], v[56:59]
	v_mfma_f32_16x16x32_bf16 v[44:47], v[132:135], v[210:213], v[44:47]
	v_mfma_f32_16x16x32_bf16 v[40:43], v[140:143], v[210:213], v[40:43]
	v_mfma_f32_16x16x32_bf16 v[28:31], v[132:135], v[218:221], v[28:31]
	v_mfma_f32_16x16x32_bf16 v[24:27], v[140:143], v[218:221], v[24:27]
	v_mfma_f32_16x16x32_bf16 v[12:15], v[132:135], v[226:229], v[12:15]
	v_mfma_f32_16x16x32_bf16 v[8:11], v[140:143], v[226:229], v[8:11]
	v_mfma_f32_16x16x32_bf16 v[52:55], v[168:171], v[194:197], v[52:55]
	v_mfma_f32_16x16x32_bf16 v[48:51], v[186:189], v[194:197], v[48:51]
	v_mfma_f32_16x16x32_bf16 v[36:39], v[168:171], v[206:209], v[36:39]
	v_mfma_f32_16x16x32_bf16 v[32:35], v[186:189], v[206:209], v[32:35]
	v_mfma_f32_16x16x32_bf16 v[20:23], v[168:171], v[214:217], v[20:23]
	v_mfma_f32_16x16x32_bf16 v[16:19], v[186:189], v[214:217], v[16:19]
	v_mfma_f32_16x16x32_bf16 v[4:7], v[168:171], v[222:225], v[4:7]
	v_mfma_f32_16x16x32_bf16 v[0:3], v[186:189], v[222:225], v[0:3]
	v_mfma_f32_16x16x32_bf16 v[52:55], v[172:175], v[202:205], v[52:55]
	v_mfma_f32_16x16x32_bf16 v[48:51], v[190:193], v[202:205], v[48:51]
	v_mfma_f32_16x16x32_bf16 v[36:39], v[172:175], v[210:213], v[36:39]
	v_mfma_f32_16x16x32_bf16 v[32:35], v[190:193], v[210:213], v[32:35]
	v_mfma_f32_16x16x32_bf16 v[20:23], v[172:175], v[218:221], v[20:23]
	v_mfma_f32_16x16x32_bf16 v[16:19], v[190:193], v[218:221], v[16:19]
	v_mfma_f32_16x16x32_bf16 v[4:7], v[172:175], v[226:229], v[4:7]
	v_mfma_f32_16x16x32_bf16 v[0:3], v[190:193], v[226:229], v[0:3]
	s_barrier
; #define PG8_STAGE(bufoff, gbase, voff) do { const unsigned long long gb_ = (unsigned long long)(gbase); _Pragma("unroll") for (int _i = 0; _i < 2; ++_i) { unsigned keep_; \
;         asm volatile("s_mov_b32 m0, %2\n\ts_nop 0\n\tglobal_load_lds_dwordx4 %0, %1" : : "v"((voff)[_i]), "s"(gb_), "s"((unsigned)(size_t)(lds + (bufoff) + ldsw + _i * 8192)) : "memory", "m0"); (void)keep_; } } while (0)
; #define PG8_LDA(dst, b, h) do { _Pragma("unroll") for (int m = 0; m < 4; ++m) _Pragma("unroll") for (int k = 0; k < 2; ++k) dst[m][k] = *(const PG8_LAS bf16x8*)(lds + PG8_SA(b, h) + aoff + m * 2048 + k * 1024); } while (0)
; #define PG8_LDB(dst, b, h) do { _Pragma("unroll") for (int n = 0; n < 2; ++n) _Pragma("unroll") for (int k = 0; k < 2; ++k) dst[n][k] = *(const PG8_LAS bf16x8*)(lds + PG8_SB(b, h) + boff + n * 2048 + k * 1024); } while (0)
; #define PG8_MMA(ai, bj, At, Bt) do { __builtin_amdgcn_s_setprio(1); _Pragma("unroll") for (int m = 0; m < 4; ++m) _Pragma("unroll") for (int n = 0; n < 2; ++n) _Pragma("unroll") for (int k = 0; k < 2; ++k) \
;         acc[ai][bj][m][n] = __builtin_amdgcn_mfma_f32_16x16x32_bf16(Bt[n][k], At[m][k], acc[ai][bj][m][n], 0, 0, 0); __builtin_amdgcn_s_setprio(0); } while (0)
; #define PG8_WAIT_V(n) asm volatile("s_waitcnt vmcnt(" #n ")" ::: "memory")
; #define PG8_WAIT_L(n) asm volatile("s_waitcnt lgkmcnt(" #n ")" ::: "memory")
; #define PG8_BAR __builtin_amdgcn_s_barrier()
; #define PG8_SCHED __builtin_amdgcn_sched_barrier(0)
; template <class Epi, class Sched, bool ALIGN_EPI = false, bool SP2 = false>
; __device__ __forceinline__ void gemm_phase(PG8_LAS unsigned char* lds, const Gemm g, const Sched& S, const Epi& E) {
;     ...
;             PG8_LDB(B0, 1, 0); PG8_LDB(B1, 1, 1); PG8_SCHED; PG8_LDA(At, 1, 0); PG8_STAGE(PG8_SA(0, 1), a2 + hstepA, voffA);
;             PG8_WAIT_V(8); PG8_WAIT_L(0); PG8_BAR; PG8_MMA(0, 0, At, B0); PG8_MMA(0, 1, At, B1); PG8_BAR; PG8_SCHED;
;             PG8_LDA(At, 1, 1); PG8_STAGE(PG8_SB(1, 0), b3, voffB); PG8_STAGE(PG8_SB(1, 1), b3 + hstepB, voffB); PG8_STAGE(PG8_SA(1, 0), a3, voffA);
;             PG8_WAIT_V(8); PG8_WAIT_L(0); PG8_BAR; PG8_MMA(1, 0, At, B0); PG8_MMA(1, 1, At, B1); PG8_BAR; PG8_SCHED;
	ds_read_b128 v[128:131], v183
	ds_read_b128 v[132:135], v183 offset:1024
	ds_read_b128 v[136:139], v183 offset:2048
	ds_read_b128 v[140:143], v183 offset:3072
	ds_read_b128 v[168:171], v184
	ds_read_b128 v[172:175], v184 offset:1024
	ds_read_b128 v[186:189], v184 offset:2048
	ds_read_b128 v[190:193], v184 offset:3072
	ds_read_b128 v[194:197], v182 offset:32768
	ds_read_b128 v[202:205], v182 offset:33792
	ds_read_b128 v[206:209], v182 offset:34816
	ds_read_b128 v[210:213], v182 offset:35840
	ds_read_b128 v[214:217], v182 offset:36864
	ds_read_b128 v[218:221], v182 offset:37888
	ds_read_b128 v[222:225], v182 offset:38912
	ds_read_b128 v[226:229], v182 offset:39936
	s_add_u32 s26, s36, 0x8000
	s_addc_u32 s27, s37, 0
	s_mov_b32 m0, s47
	s_nop 0
	global_load_lds_dwordx4 v176, s[26:27]
	s_nop 0
	s_mov_b32 m0, s48
	s_nop 0
	global_load_lds_dwordx4 v178, s[26:27]
	s_waitcnt vmcnt(8)
	s_waitcnt lgkmcnt(0)
	s_barrier
	v_mfma_f32_16x16x32_bf16 v[124:127], v[128:131], v[194:197], v[124:127]
	v_mfma_f32_16x16x32_bf16 v[120:123], v[136:139], v[194:197], v[120:123]
	v_mfma_f32_16x16x32_bf16 v[108:111], v[128:131], v[206:209], v[108:111]
	v_mfma_f32_16x16x32_bf16 v[104:107], v[136:139], v[206:209], v[104:107]
	v_mfma_f32_16x16x32_bf16 v[92:95], v[128:131], v[214:217], v[92:95]
	v_mfma_f32_16x16x32_bf16 v[88:91], v[136:139], v[214:217], v[88:91]
	v_mfma_f32_16x16x32_bf16 v[76:79], v[128:131], v[222:225], v[76:79]
	v_mfma_f32_16x16x32_bf16 v[72:75], v[136:139], v[222:225], v[72:75]
	v_mfma_f32_16x16x32_bf16 v[124:127], v[132:135], v[202:205], v[124:127]
	v_mfma_f32_16x16x32_bf16 v[120:123], v[140:143], v[202:205], v[120:123]
	v_mfma_f32_16x16x32_bf16 v[108:111], v[132:135], v[210:213], v[108:111]
	v_mfma_f32_16x16x32_bf16 v[104:107], v[140:143], v[210:213], v[104:107]
	v_mfma_f32_16x16x32_bf16 v[92:95], v[132:135], v[218:221], v[92:95]
	v_mfma_f32_16x16x32_bf16 v[88:91], v[140:143], v[218:221], v[88:91]
	v_mfma_f32_16x16x32_bf16 v[76:79], v[132:135], v[226:229], v[76:79]
	v_mfma_f32_16x16x32_bf16 v[72:75], v[140:143], v[226:229], v[72:75]
	v_mfma_f32_16x16x32_bf16 v[116:119], v[168:171], v[194:197], v[116:119]
	v_mfma_f32_16x16x32_bf16 v[112:115], v[186:189], v[194:197], v[112:115]
	v_mfma_f32_16x16x32_bf16 v[100:103], v[168:171], v[206:209], v[100:103]
	v_mfma_f32_16x16x32_bf16 v[96:99], v[186:189], v[206:209], v[96:99]
	v_mfma_f32_16x16x32_bf16 v[84:87], v[168:171], v[214:217], v[84:87]
	v_mfma_f32_16x16x32_bf16 v[80:83], v[186:189], v[214:217], v[80:83]
	v_mfma_f32_16x16x32_bf16 v[68:71], v[168:171], v[222:225], v[68:71]
	v_mfma_f32_16x16x32_bf16 v[64:67], v[186:189], v[222:225], v[64:67]
	v_mfma_f32_16x16x32_bf16 v[116:119], v[172:175], v[202:205], v[116:119]
	v_mfma_f32_16x16x32_bf16 v[112:115], v[190:193], v[202:205], v[112:115]
	v_mfma_f32_16x16x32_bf16 v[100:103], v[172:175], v[210:213], v[100:103]
	v_mfma_f32_16x16x32_bf16 v[96:99], v[190:193], v[210:213], v[96:99]
	v_mfma_f32_16x16x32_bf16 v[84:87], v[172:175], v[218:221], v[84:87]
	v_mfma_f32_16x16x32_bf16 v[80:83], v[190:193], v[218:221], v[80:83]
	v_mfma_f32_16x16x32_bf16 v[68:71], v[172:175], v[226:229], v[68:71]
	v_mfma_f32_16x16x32_bf16 v[64:67], v[190:193], v[226:229], v[64:67]
	s_barrier
	ds_read_b128 v[194:197], v182 offset:49152
	ds_read_b128 v[202:205], v182 offset:50176
	ds_read_b128 v[206:209], v182 offset:51200
	ds_read_b128 v[210:213], v182 offset:52224
	ds_read_b128 v[214:217], v182 offset:53248
	ds_read_b128 v[218:221], v182 offset:54272
	ds_read_b128 v[222:225], v182 offset:55296
	ds_read_b128 v[226:229], v182 offset:56320
	s_add_u32 s26, s34, 0x80
	s_addc_u32 s27, s35, 0
	s_mov_b32 m0, s50
	s_nop 0
	global_load_lds_dwordx4 v177, s[26:27]
	s_nop 0
	s_mov_b32 m0, s51
	s_nop 0
	global_load_lds_dwordx4 v179, s[26:27]
	s_add_u32 s26, s34, 0x160080
	s_addc_u32 s27, s35, 0
	s_mov_b32 m0, s54
	s_nop 0
	global_load_lds_dwordx4 v177, s[26:27]
	s_nop 0
	s_mov_b32 m0, s55
	s_nop 0
	global_load_lds_dwordx4 v179, s[26:27]
	s_nop 0
	s_mov_b32 m0, s52
	s_nop 0
	global_load_lds_dwordx4 v176, s[30:31]
	s_nop 0
	s_mov_b32 m0, s53
	s_nop 0
	global_load_lds_dwordx4 v178, s[30:31]
	s_waitcnt vmcnt(8)
	s_waitcnt lgkmcnt(0)
	s_barrier
	v_mfma_f32_16x16x32_bf16 v[60:63], v[128:131], v[194:197], v[60:63]
	v_mfma_f32_16x16x32_bf16 v[56:59], v[136:139], v[194:197], v[56:59]
	v_mfma_f32_16x16x32_bf16 v[44:47], v[128:131], v[206:209], v[44:47]
	v_mfma_f32_16x16x32_bf16 v[40:43], v[136:139], v[206:209], v[40:43]
	v_mfma_f32_16x16x32_bf16 v[28:31], v[128:131], v[214:217], v[28:31]
	v_mfma_f32_16x16x32_bf16 v[24:27], v[136:139], v[214:217], v[24:27]
	v_mfma_f32_16x16x32_bf16 v[12:15], v[128:131], v[222:225], v[12:15]
	v_mfma_f32_16x16x32_bf16 v[8:11], v[136:139], v[222:225], v[8:11]
	v_mfma_f32_16x16x32_bf16 v[60:63], v[132:135], v[202:205], v[60:63]
	v_mfma_f32_16x16x32_bf16 v[56:59], v[140:143], v[202:205], v[56:59]
	v_mfma_f32_16x16x32_bf16 v[44:47], v[132:135], v[210:213], v[44:47]
	v_mfma_f32_16x16x32_bf16 v[40:43], v[140:143], v[210:213], v[40:43]
	v_mfma_f32_16x16x32_bf16 v[28:31], v[132:135], v[218:221], v[28:31]
	v_mfma_f32_16x16x32_bf16 v[24:27], v[140:143], v[218:221], v[24:27]
	v_mfma_f32_16x16x32_bf16 v[12:15], v[132:135], v[226:229], v[12:15]
	v_mfma_f32_16x16x32_bf16 v[8:11], v[140:143], v[226:229], v[8:11]
	v_mfma_f32_16x16x32_bf16 v[52:55], v[168:171], v[194:197], v[52:55]
	v_mfma_f32_16x16x32_bf16 v[48:51], v[186:189], v[194:197], v[48:51]
	v_mfma_f32_16x16x32_bf16 v[36:39], v[168:171], v[206:209], v[36:39]
	v_mfma_f32_16x16x32_bf16 v[32:35], v[186:189], v[206:209], v[32:35]
	v_mfma_f32_16x16x32_bf16 v[20:23], v[168:171], v[214:217], v[20:23]
	v_mfma_f32_16x16x32_bf16 v[16:19], v[186:189], v[214:217], v[16:19]
	v_mfma_f32_16x16x32_bf16 v[4:7], v[168:171], v[222:225], v[4:7]
	v_mfma_f32_16x16x32_bf16 v[0:3], v[186:189], v[222:225], v[0:3]
	v_mfma_f32_16x16x32_bf16 v[52:55], v[172:175], v[202:205], v[52:55]
	v_mfma_f32_16x16x32_bf16 v[48:51], v[190:193], v[202:205], v[48:51]
	v_mfma_f32_16x16x32_bf16 v[36:39], v[172:175], v[210:213], v[36:39]
	v_mfma_f32_16x16x32_bf16 v[32:35], v[190:193], v[210:213], v[32:35]
	v_mfma_f32_16x16x32_bf16 v[20:23], v[172:175], v[218:221], v[20:23]
	v_mfma_f32_16x16x32_bf16 v[16:19], v[190:193], v[218:221], v[16:19]
	v_mfma_f32_16x16x32_bf16 v[4:7], v[172:175], v[226:229], v[4:7]
	v_mfma_f32_16x16x32_bf16 v[0:3], v[190:193], v[226:229], v[0:3]
	s_barrier
	s_add_i32 s64, s64, 2
	s_add_u32 s0, s0, 0x100
	s_addc_u32 s1, s1, 0
	s_cmpk_gt_u32 s64, 0x55
	s_mov_b64 s[26:27], s[28:29]
	s_cbranch_scc0 .LBB0_511
	s_and_b64 vcc, exec, s[22:23]
	s_cbranch_vccz .LBB0_514
	s_barrier

; #define PG8_STAGE(bufoff, gbase, voff) do { const unsigned long long gb_ = (unsigned long long)(gbase); _Pragma("unroll") for (int _i = 0; _i < 2; ++_i) { unsigned keep_; \
;         asm volatile("s_mov_b32 m0, %2\n\ts_nop 0\n\tglobal_load_lds_dwordx4 %0, %1" : : "v"((voff)[_i]), "s"(gb_), "s"((unsigned)(size_t)(lds + (bufoff) + ldsw + _i * 8192)) : "memory", "m0"); (void)keep_; } } while (0)
; #define PG8_LDA(dst, b, h) do { _Pragma("unroll") for (int m = 0; m < 4; ++m) _Pragma("unroll") for (int k = 0; k < 2; ++k) dst[m][k] = *(const PG8_LAS bf16x8*)(lds + PG8_SA(b, h) + aoff + m * 2048 + k * 1024); } while (0)
; #define PG8_LDB(dst, b, h) do { _Pragma("unroll") for (int n = 0; n < 2; ++n) _Pragma("unroll") for (int k = 0; k < 2; ++k) dst[n][k] = *(const PG8_LAS bf16x8*)(lds + PG8_SB(b, h) + boff + n * 2048 + k * 1024); } while (0)
; #define PG8_MMA(ai, bj, At, Bt) do { __builtin_amdgcn_s_setprio(1); _Pragma("unroll") for (int m = 0; m < 4; ++m) _Pragma("unroll") for (int n = 0; n < 2; ++n) _Pragma("unroll") for (int k = 0; k < 2; ++k) \
;         acc[ai][bj][m][n] = __builtin_amdgcn_mfma_f32_16x16x32_bf16(Bt[n][k], At[m][k], acc[ai][bj][m][n], 0, 0, 0); __builtin_amdgcn_s_setprio(0); } while (0)
; #define PG8_WAIT_V(n) asm volatile("s_waitcnt vmcnt(" #n ")" ::: "memory")
; #define PG8_BAR __builtin_amdgcn_s_barrier()
; template <class Epi, class Sched, bool ALIGN_EPI = false, bool SP2 = false>
; __device__ __forceinline__ void gemm_phase(PG8_LAS unsigned char* lds, const Gemm g, const Sched& S, const Epi& E) {
;     ...
;         for (int t = 0; t < nt; t += 2) {
;             const bool last = (t == nt - 2);
;     ...
;             const char* a1 = cA + PG8_KOFFA(t + 1);
;             const char* a2 = last ? nA : cA + PG8_KOFFA(t + 2); const char* b2 = last ? nB : cB + (size_t)(t + 2) * kstep;
;             const char* a3 = last ? nA + kstep : cA + PG8_KOFFA(t + 3); const char* b3 = b2 + kstep;
;     ...
;             if (last && has_next) S.a_ready(nxt);
;             if constexpr (SP2) {
;             PG8_LDB(B0, 0, 0); PG8_LDB(B1, 0, 1); PG8_SCHED; PG8_LDA(At, 0, 0); PG8_STAGE(PG8_SA(1, 1), a1 + hstepA, voffA);
;             PG8_WAIT_V(8); PG8_WAIT_L(0); PG8_BAR; PG8_MMA(0, 0, At, B0); PG8_MMA(0, 1, At, B1); PG8_BAR; PG8_SCHED;
;             PG8_LDA(At, 0, 1); PG8_STAGE(PG8_SB(0, 0), b2, voffB); PG8_STAGE(PG8_SB(0, 1), b2 + hstepB, voffB); PG8_STAGE(PG8_SA(0, 0), a2, voffA);
.LBB0_632:
	s_add_i32 s57, s84, 0xfffe8000
	s_and_b32 s56, s52, 0x100
	s_and_b32 s57, s57, 0xe0000
	s_or_b32 s56, s56, s57
	s_add_u32 s85, s10, s56
	s_addc_u32 s87, s11, 0
	s_add_u32 s56, s52, 0x100
	s_addc_u32 s57, s53, 0
	s_add_i32 s59, s84, 0xffff8000
	s_and_b32 s58, s56, 0x100
	s_and_b32 s59, s59, 0x1e0000
	s_or_b32 s58, s59, s58
	ds_read_b128 v[182:185], v173
	ds_read_b128 v[186:189], v173 offset:1024
	ds_read_b128 v[194:197], v173 offset:2048
	ds_read_b128 v[202:205], v173 offset:3072
	ds_read_b128 v[206:209], v177
	ds_read_b128 v[210:213], v177 offset:1024
	ds_read_b128 v[214:217], v177 offset:2048
	ds_read_b128 v[218:221], v177 offset:3072
	s_add_u32 s58, s10, s58
	s_addc_u32 s59, s11, 0
	s_add_u32 s86, s45, s52
	s_addc_u32 s53, s51, s53
	s_add_i32 s60, s52, 0x180
	s_and_b32 s60, s60, 0x180
	s_and_b32 s61, s84, 0x1e0000
	s_or_b32 s60, s61, s60
	s_add_u32 s90, s10, s60
	s_addc_u32 s91, s11, 0
	s_cmpk_eq_i32 s52, 0xf00
	s_cselect_b32 s61, s0, s59
	s_cselect_b32 s59, s4, s53
	s_cselect_b32 s53, s43, s91
	s_cselect_b32 s52, s16, s90
	s_cselect_b32 s60, s1, s58
	s_cselect_b32 s58, s5, s86
	ds_read_b128 v[222:225], v181
	ds_read_b128 v[226:229], v181 offset:1024
	ds_read_b128 v[230:233], v181 offset:2048
	ds_read_b128 v[234:237], v181 offset:3072
	ds_read_b128 v[238:241], v181 offset:4096
	ds_read_b128 v[242:245], v181 offset:5120
	ds_read_b128 v[246:249], v181 offset:6144
	ds_read_b128 v[250:253], v181 offset:7168
	s_add_u32 s86, s85, 0x10080
	s_addc_u32 s87, s87, 0
	s_mov_b32 m0, s79
	s_nop 0
	global_load_lds_dwordx4 v157, s[86:87]
	s_nop 0
	s_mov_b32 m0, s80
	s_nop 0
	global_load_lds_dwordx4 v165, s[86:87]
	s_waitcnt vmcnt(8)
	s_waitcnt lgkmcnt(0)
	s_barrier
	v_mfma_f32_16x16x32_bf16 v[124:127], v[182:185], v[222:225], v[124:127]
	v_mfma_f32_16x16x32_bf16 v[120:123], v[194:197], v[222:225], v[120:123]
	v_mfma_f32_16x16x32_bf16 v[108:111], v[182:185], v[230:233], v[108:111]
	v_mfma_f32_16x16x32_bf16 v[104:107], v[194:197], v[230:233], v[104:107]
	v_mfma_f32_16x16x32_bf16 v[92:95], v[182:185], v[238:241], v[92:95]
	v_mfma_f32_16x16x32_bf16 v[88:91], v[194:197], v[238:241], v[88:91]
	v_mfma_f32_16x16x32_bf16 v[76:79], v[182:185], v[246:249], v[76:79]
	v_mfma_f32_16x16x32_bf16 v[72:75], v[194:197], v[246:249], v[72:75]
	v_mfma_f32_16x16x32_bf16 v[124:127], v[186:189], v[226:229], v[124:127]
	v_mfma_f32_16x16x32_bf16 v[120:123], v[202:205], v[226:229], v[120:123]
	v_mfma_f32_16x16x32_bf16 v[108:111], v[186:189], v[234:237], v[108:111]
	v_mfma_f32_16x16x32_bf16 v[104:107], v[202:205], v[234:237], v[104:107]
	v_mfma_f32_16x16x32_bf16 v[92:95], v[186:189], v[242:245], v[92:95]
	v_mfma_f32_16x16x32_bf16 v[88:91], v[202:205], v[242:245], v[88:91]
	v_mfma_f32_16x16x32_bf16 v[76:79], v[186:189], v[250:253], v[76:79]
	v_mfma_f32_16x16x32_bf16 v[72:75], v[202:205], v[250:253], v[72:75]
	v_mfma_f32_16x16x32_bf16 v[116:119], v[206:209], v[222:225], v[116:119]
	v_mfma_f32_16x16x32_bf16 v[112:115], v[214:217], v[222:225], v[112:115]
	v_mfma_f32_16x16x32_bf16 v[100:103], v[206:209], v[230:233], v[100:103]
	v_mfma_f32_16x16x32_bf16 v[96:99], v[214:217], v[230:233], v[96:99]
	v_mfma_f32_16x16x32_bf16 v[84:87], v[206:209], v[238:241], v[84:87]
	v_mfma_f32_16x16x32_bf16 v[80:83], v[214:217], v[238:241], v[80:83]
	v_mfma_f32_16x16x32_bf16 v[68:71], v[206:209], v[246:249], v[68:71]
	v_mfma_f32_16x16x32_bf16 v[64:67], v[214:217], v[246:249], v[64:67]
	v_mfma_f32_16x16x32_bf16 v[116:119], v[210:213], v[226:229], v[116:119]
	v_mfma_f32_16x16x32_bf16 v[112:115], v[218:221], v[226:229], v[112:115]
	v_mfma_f32_16x16x32_bf16 v[100:103], v[210:213], v[234:237], v[100:103]
	v_mfma_f32_16x16x32_bf16 v[96:99], v[218:221], v[234:237], v[96:99]
	v_mfma_f32_16x16x32_bf16 v[84:87], v[210:213], v[242:245], v[84:87]
	v_mfma_f32_16x16x32_bf16 v[80:83], v[218:221], v[242:245], v[80:83]
	v_mfma_f32_16x16x32_bf16 v[68:71], v[210:213], v[250:253], v[68:71]
	v_mfma_f32_16x16x32_bf16 v[64:67], v[218:221], v[250:253], v[64:67]
	s_barrier
	ds_read_b128 v[222:225], v181 offset:16384
	ds_read_b128 v[226:229], v181 offset:17408
	ds_read_b128 v[230:233], v181 offset:18432
	ds_read_b128 v[234:237], v181 offset:19456
	ds_read_b128 v[238:241], v181 offset:20480
	ds_read_b128 v[242:245], v181 offset:21504
	ds_read_b128 v[246:249], v181 offset:22528
	ds_read_b128 v[250:253], v181 offset:23552
	s_mov_b32 m0, s41
	s_nop 0
	global_load_lds_dwordx4 v161, s[58:59]
	s_add_u32 s86, s58, 0x80000
	s_mov_b32 m0, s62
	s_nop 0
	global_load_lds_dwordx4 v169, s[58:59]
	s_addc_u32 s87, s59, 0
	s_mov_b32 m0, s63
	s_nop 0
	global_load_lds_dwordx4 v161, s[86:87]
	s_nop 0
	s_mov_b32 m0, s64
	s_nop 0
	global_load_lds_dwordx4 v169, s[86:87]
	s_nop 0
	s_mov_b32 m0, s39
	s_nop 0
	global_load_lds_dwordx4 v157, s[60:61]
	s_nop 0
	s_mov_b32 m0, s65
	s_nop 0
	global_load_lds_dwordx4 v165, s[60:61]
	s_waitcnt vmcnt(8)
	s_waitcnt lgkmcnt(0)
	s_barrier
; #define PG8_STAGE(bufoff, gbase, voff) do { const unsigned long long gb_ = (unsigned long long)(gbase); _Pragma("unroll") for (int _i = 0; _i < 2; ++_i) { unsigned keep_; \
;         asm volatile("s_mov_b32 m0, %2\n\ts_nop 0\n\tglobal_load_lds_dwordx4 %0, %1" : : "v"((voff)[_i]), "s"(gb_), "s"((unsigned)(size_t)(lds + (bufoff) + ldsw + _i * 8192)) : "memory", "m0"); (void)keep_; } } while (0)
; #define PG8_LDA(dst, b, h) do { _Pragma("unroll") for (int m = 0; m < 4; ++m) _Pragma("unroll") for (int k = 0; k < 2; ++k) dst[m][k] = *(const PG8_LAS bf16x8*)(lds + PG8_SA(b, h) + aoff + m * 2048 + k * 1024); } while (0)
; #define PG8_LDB(dst, b, h) do { _Pragma("unroll") for (int n = 0; n < 2; ++n) _Pragma("unroll") for (int k = 0; k < 2; ++k) dst[n][k] = *(const PG8_LAS bf16x8*)(lds + PG8_SB(b, h) + boff + n * 2048 + k * 1024); } while (0)
; #define PG8_MMA(ai, bj, At, Bt) do { __builtin_amdgcn_s_setprio(1); _Pragma("unroll") for (int m = 0; m < 4; ++m) _Pragma("unroll") for (int n = 0; n < 2; ++n) _Pragma("unroll") for (int k = 0; k < 2; ++k) \
;         acc[ai][bj][m][n] = __builtin_amdgcn_mfma_f32_16x16x32_bf16(Bt[n][k], At[m][k], acc[ai][bj][m][n], 0, 0, 0); __builtin_amdgcn_s_setprio(0); } while (0)
; #define PG8_WAIT_V(n) asm volatile("s_waitcnt vmcnt(" #n ")" ::: "memory")
; #define PG8_WAIT_L(n) asm volatile("s_waitcnt lgkmcnt(" #n ")" ::: "memory")
; #define PG8_BAR __builtin_amdgcn_s_barrier()
; #define PG8_SCHED __builtin_amdgcn_sched_barrier(0)
; template <class Epi, class Sched, bool ALIGN_EPI = false, bool SP2 = false>
; __device__ __forceinline__ void gemm_phase(PG8_LAS unsigned char* lds, const Gemm g, const Sched& S, const Epi& E) {
;     ...
;             PG8_WAIT_V(8); PG8_WAIT_L(0); PG8_BAR; PG8_MMA(1, 0, At, B0); PG8_MMA(1, 1, At, B1); PG8_BAR; PG8_SCHED;
;             PG8_LDB(B0, 1, 0); PG8_LDB(B1, 1, 1); PG8_SCHED; PG8_LDA(At, 1, 0); PG8_STAGE(PG8_SA(0, 1), a2 + hstepA, voffA);
;             PG8_WAIT_V(8); PG8_WAIT_L(0); PG8_BAR; PG8_MMA(0, 0, At, B0); PG8_MMA(0, 1, At, B1); PG8_BAR; PG8_SCHED;
	v_mfma_f32_16x16x32_bf16 v[60:63], v[182:185], v[222:225], v[60:63]
	v_mfma_f32_16x16x32_bf16 v[56:59], v[194:197], v[222:225], v[56:59]
	v_mfma_f32_16x16x32_bf16 v[44:47], v[182:185], v[230:233], v[44:47]
	v_mfma_f32_16x16x32_bf16 v[40:43], v[194:197], v[230:233], v[40:43]
	v_mfma_f32_16x16x32_bf16 v[28:31], v[182:185], v[238:241], v[28:31]
	v_mfma_f32_16x16x32_bf16 v[24:27], v[194:197], v[238:241], v[24:27]
	v_mfma_f32_16x16x32_bf16 v[12:15], v[182:185], v[246:249], v[12:15]
	v_mfma_f32_16x16x32_bf16 v[8:11], v[194:197], v[246:249], v[8:11]
	v_mfma_f32_16x16x32_bf16 v[60:63], v[186:189], v[226:229], v[60:63]
	v_mfma_f32_16x16x32_bf16 v[56:59], v[202:205], v[226:229], v[56:59]
	v_mfma_f32_16x16x32_bf16 v[44:47], v[186:189], v[234:237], v[44:47]
	v_mfma_f32_16x16x32_bf16 v[40:43], v[202:205], v[234:237], v[40:43]
	v_mfma_f32_16x16x32_bf16 v[28:31], v[186:189], v[242:245], v[28:31]
	v_mfma_f32_16x16x32_bf16 v[24:27], v[202:205], v[242:245], v[24:27]
	v_mfma_f32_16x16x32_bf16 v[12:15], v[186:189], v[250:253], v[12:15]
	v_mfma_f32_16x16x32_bf16 v[8:11], v[202:205], v[250:253], v[8:11]
	v_mfma_f32_16x16x32_bf16 v[52:55], v[206:209], v[222:225], v[52:55]
	v_mfma_f32_16x16x32_bf16 v[48:51], v[214:217], v[222:225], v[48:51]
	v_mfma_f32_16x16x32_bf16 v[36:39], v[206:209], v[230:233], v[36:39]
	v_mfma_f32_16x16x32_bf16 v[32:35], v[214:217], v[230:233], v[32:35]
	v_mfma_f32_16x16x32_bf16 v[20:23], v[206:209], v[238:241], v[20:23]
	v_mfma_f32_16x16x32_bf16 v[16:19], v[214:217], v[238:241], v[16:19]
	v_mfma_f32_16x16x32_bf16 v[4:7], v[206:209], v[246:249], v[4:7]
	v_mfma_f32_16x16x32_bf16 v[0:3], v[214:217], v[246:249], v[0:3]
	v_mfma_f32_16x16x32_bf16 v[52:55], v[210:213], v[226:229], v[52:55]
	v_mfma_f32_16x16x32_bf16 v[48:51], v[218:221], v[226:229], v[48:51]
	v_mfma_f32_16x16x32_bf16 v[36:39], v[210:213], v[234:237], v[36:39]
	v_mfma_f32_16x16x32_bf16 v[32:35], v[218:221], v[234:237], v[32:35]
	v_mfma_f32_16x16x32_bf16 v[20:23], v[210:213], v[242:245], v[20:23]
	v_mfma_f32_16x16x32_bf16 v[16:19], v[218:221], v[242:245], v[16:19]
	v_mfma_f32_16x16x32_bf16 v[4:7], v[210:213], v[250:253], v[4:7]
	v_mfma_f32_16x16x32_bf16 v[0:3], v[218:221], v[250:253], v[0:3]
	s_barrier
	ds_read_b128 v[182:185], v190
	ds_read_b128 v[186:189], v190 offset:1024
	ds_read_b128 v[194:197], v190 offset:2048
	ds_read_b128 v[202:205], v190 offset:3072
	ds_read_b128 v[206:209], v191
	ds_read_b128 v[210:213], v191 offset:1024
	ds_read_b128 v[214:217], v191 offset:2048
	ds_read_b128 v[218:221], v191 offset:3072
	ds_read_b128 v[222:225], v181 offset:32768
	ds_read_b128 v[226:229], v181 offset:33792
	ds_read_b128 v[230:233], v181 offset:34816
	ds_read_b128 v[234:237], v181 offset:35840
	ds_read_b128 v[238:241], v181 offset:36864
	ds_read_b128 v[242:245], v181 offset:37888
	ds_read_b128 v[246:249], v181 offset:38912
	ds_read_b128 v[250:253], v181 offset:39936
	s_add_u32 s60, s60, 0x10000
	s_addc_u32 s61, s61, 0
	s_mov_b32 m0, s66
	s_nop 0
	global_load_lds_dwordx4 v157, s[60:61]
	s_nop 0
	s_mov_b32 m0, s67
	s_nop 0
	global_load_lds_dwordx4 v165, s[60:61]
	s_waitcnt vmcnt(8)
	s_waitcnt lgkmcnt(0)
	s_barrier
	v_mfma_f32_16x16x32_bf16 v[124:127], v[182:185], v[222:225], v[124:127]
	v_mfma_f32_16x16x32_bf16 v[120:123], v[194:197], v[222:225], v[120:123]
	v_mfma_f32_16x16x32_bf16 v[108:111], v[182:185], v[230:233], v[108:111]
	v_mfma_f32_16x16x32_bf16 v[104:107], v[194:197], v[230:233], v[104:107]
	v_mfma_f32_16x16x32_bf16 v[92:95], v[182:185], v[238:241], v[92:95]
	v_mfma_f32_16x16x32_bf16 v[88:91], v[194:197], v[238:241], v[88:91]
	v_mfma_f32_16x16x32_bf16 v[76:79], v[182:185], v[246:249], v[76:79]
	v_mfma_f32_16x16x32_bf16 v[72:75], v[194:197], v[246:249], v[72:75]
	v_mfma_f32_16x16x32_bf16 v[124:127], v[186:189], v[226:229], v[124:127]
	v_mfma_f32_16x16x32_bf16 v[120:123], v[202:205], v[226:229], v[120:123]
	v_mfma_f32_16x16x32_bf16 v[108:111], v[186:189], v[234:237], v[108:111]
	v_mfma_f32_16x16x32_bf16 v[104:107], v[202:205], v[234:237], v[104:107]
	v_mfma_f32_16x16x32_bf16 v[92:95], v[186:189], v[242:245], v[92:95]
	v_mfma_f32_16x16x32_bf16 v[88:91], v[202:205], v[242:245], v[88:91]
	v_mfma_f32_16x16x32_bf16 v[76:79], v[186:189], v[250:253], v[76:79]
	v_mfma_f32_16x16x32_bf16 v[72:75], v[202:205], v[250:253], v[72:75]
	v_mfma_f32_16x16x32_bf16 v[116:119], v[206:209], v[222:225], v[116:119]
	v_mfma_f32_16x16x32_bf16 v[112:115], v[214:217], v[222:225], v[112:115]
	v_mfma_f32_16x16x32_bf16 v[100:103], v[206:209], v[230:233], v[100:103]
	v_mfma_f32_16x16x32_bf16 v[96:99], v[214:217], v[230:233], v[96:99]
	v_mfma_f32_16x16x32_bf16 v[84:87], v[206:209], v[238:241], v[84:87]
	v_mfma_f32_16x16x32_bf16 v[80:83], v[214:217], v[238:241], v[80:83]
	v_mfma_f32_16x16x32_bf16 v[68:71], v[206:209], v[246:249], v[68:71]
	v_mfma_f32_16x16x32_bf16 v[64:67], v[214:217], v[246:249], v[64:67]
	v_mfma_f32_16x16x32_bf16 v[116:119], v[210:213], v[226:229], v[116:119]
	v_mfma_f32_16x16x32_bf16 v[112:115], v[218:221], v[226:229], v[112:115]
	v_mfma_f32_16x16x32_bf16 v[100:103], v[210:213], v[234:237], v[100:103]
	v_mfma_f32_16x16x32_bf16 v[96:99], v[218:221], v[234:237], v[96:99]
	v_mfma_f32_16x16x32_bf16 v[84:87], v[210:213], v[242:245], v[84:87]
	v_mfma_f32_16x16x32_bf16 v[80:83], v[218:221], v[242:245], v[80:83]
	v_mfma_f32_16x16x32_bf16 v[68:71], v[210:213], v[250:253], v[68:71]
	v_mfma_f32_16x16x32_bf16 v[64:67], v[218:221], v[250:253], v[64:67]
	s_barrier
; #define PG8_STAGE(bufoff, gbase, voff) do { const unsigned long long gb_ = (unsigned long long)(gbase); _Pragma("unroll") for (int _i = 0; _i < 2; ++_i) { unsigned keep_; \
;         asm volatile("s_mov_b32 m0, %2\n\ts_nop 0\n\tglobal_load_lds_dwordx4 %0, %1" : : "v"((voff)[_i]), "s"(gb_), "s"((unsigned)(size_t)(lds + (bufoff) + ldsw + _i * 8192)) : "memory", "m0"); (void)keep_; } } while (0)
; #define PG8_LDA(dst, b, h) do { _Pragma("unroll") for (int m = 0; m < 4; ++m) _Pragma("unroll") for (int k = 0; k < 2; ++k) dst[m][k] = *(const PG8_LAS bf16x8*)(lds + PG8_SA(b, h) + aoff + m * 2048 + k * 1024); } while (0)
; #define PG8_MMA(ai, bj, At, Bt) do { __builtin_amdgcn_s_setprio(1); _Pragma("unroll") for (int m = 0; m < 4; ++m) _Pragma("unroll") for (int n = 0; n < 2; ++n) _Pragma("unroll") for (int k = 0; k < 2; ++k) \
;         acc[ai][bj][m][n] = __builtin_amdgcn_mfma_f32_16x16x32_bf16(Bt[n][k], At[m][k], acc[ai][bj][m][n], 0, 0, 0); __builtin_amdgcn_s_setprio(0); } while (0)
; #define PG8_WAIT_V(n) asm volatile("s_waitcnt vmcnt(" #n ")" ::: "memory")
; #define PG8_WAIT_L(n) asm volatile("s_waitcnt lgkmcnt(" #n ")" ::: "memory")
; #define PG8_BAR __builtin_amdgcn_s_barrier()
; #define PG8_SCHED __builtin_amdgcn_sched_barrier(0)
; template <class Epi, class Sched, bool ALIGN_EPI = false, bool SP2 = false>
; __device__ __forceinline__ void gemm_phase(PG8_LAS unsigned char* lds, const Gemm g, const Sched& S, const Epi& E) {
;     ...
;         for (int t = 0; t < nt; t += 2) {
;     ...
;             PG8_LDA(At, 1, 1); PG8_STAGE(PG8_SB(1, 0), b3, voffB); PG8_STAGE(PG8_SB(1, 1), b3 + hstepB, voffB); PG8_STAGE(PG8_SA(1, 0), a3, voffA);
;             PG8_WAIT_V(8); PG8_WAIT_L(0); PG8_BAR; PG8_MMA(1, 0, At, B0); PG8_MMA(1, 1, At, B1); PG8_BAR; PG8_SCHED;
	ds_read_b128 v[222:225], v181 offset:49152
	ds_read_b128 v[226:229], v181 offset:50176
	ds_read_b128 v[230:233], v181 offset:51200
	ds_read_b128 v[234:237], v181 offset:52224
	ds_read_b128 v[238:241], v181 offset:53248
	ds_read_b128 v[242:245], v181 offset:54272
	ds_read_b128 v[246:249], v181 offset:55296
	ds_read_b128 v[250:253], v181 offset:56320
	s_add_u32 s60, s58, 0x80
	s_addc_u32 s61, s59, 0
	s_mov_b32 m0, s71
	s_nop 0
	global_load_lds_dwordx4 v161, s[60:61]
	s_add_u32 s58, s58, 0x80080
	s_mov_b32 m0, s72
	s_nop 0
	global_load_lds_dwordx4 v169, s[60:61]
	s_addc_u32 s59, s59, 0
	s_mov_b32 m0, s77
	s_nop 0
	global_load_lds_dwordx4 v161, s[58:59]
	s_nop 0
	s_mov_b32 m0, s78
	s_nop 0
	global_load_lds_dwordx4 v169, s[58:59]
	s_nop 0
	s_mov_b32 m0, s73
	s_nop 0
	global_load_lds_dwordx4 v157, s[52:53]
	s_nop 0
	s_mov_b32 m0, s76
	s_nop 0
	global_load_lds_dwordx4 v165, s[52:53]
	s_waitcnt vmcnt(8)
	s_waitcnt lgkmcnt(0)
	s_barrier
	v_mfma_f32_16x16x32_bf16 v[60:63], v[182:185], v[222:225], v[60:63]
	v_mfma_f32_16x16x32_bf16 v[56:59], v[194:197], v[222:225], v[56:59]
	v_mfma_f32_16x16x32_bf16 v[44:47], v[182:185], v[230:233], v[44:47]
	v_mfma_f32_16x16x32_bf16 v[40:43], v[194:197], v[230:233], v[40:43]
	v_mfma_f32_16x16x32_bf16 v[28:31], v[182:185], v[238:241], v[28:31]
	v_mfma_f32_16x16x32_bf16 v[24:27], v[194:197], v[238:241], v[24:27]
	v_mfma_f32_16x16x32_bf16 v[12:15], v[182:185], v[246:249], v[12:15]
	v_mfma_f32_16x16x32_bf16 v[8:11], v[194:197], v[246:249], v[8:11]
	v_mfma_f32_16x16x32_bf16 v[60:63], v[186:189], v[226:229], v[60:63]
	v_mfma_f32_16x16x32_bf16 v[56:59], v[202:205], v[226:229], v[56:59]
	v_mfma_f32_16x16x32_bf16 v[44:47], v[186:189], v[234:237], v[44:47]
	v_mfma_f32_16x16x32_bf16 v[40:43], v[202:205], v[234:237], v[40:43]
	v_mfma_f32_16x16x32_bf16 v[28:31], v[186:189], v[242:245], v[28:31]
	v_mfma_f32_16x16x32_bf16 v[24:27], v[202:205], v[242:245], v[24:27]
	v_mfma_f32_16x16x32_bf16 v[12:15], v[186:189], v[250:253], v[12:15]
	v_mfma_f32_16x16x32_bf16 v[8:11], v[202:205], v[250:253], v[8:11]
	v_mfma_f32_16x16x32_bf16 v[52:55], v[206:209], v[222:225], v[52:55]
	v_mfma_f32_16x16x32_bf16 v[48:51], v[214:217], v[222:225], v[48:51]
	v_mfma_f32_16x16x32_bf16 v[36:39], v[206:209], v[230:233], v[36:39]
	v_mfma_f32_16x16x32_bf16 v[32:35], v[214:217], v[230:233], v[32:35]
	v_mfma_f32_16x16x32_bf16 v[20:23], v[206:209], v[238:241], v[20:23]
	v_mfma_f32_16x16x32_bf16 v[16:19], v[214:217], v[238:241], v[16:19]
	v_mfma_f32_16x16x32_bf16 v[4:7], v[206:209], v[246:249], v[4:7]
	v_mfma_f32_16x16x32_bf16 v[0:3], v[214:217], v[246:249], v[0:3]
	v_mfma_f32_16x16x32_bf16 v[52:55], v[210:213], v[226:229], v[52:55]
	v_mfma_f32_16x16x32_bf16 v[48:51], v[218:221], v[226:229], v[48:51]
	v_mfma_f32_16x16x32_bf16 v[36:39], v[210:213], v[234:237], v[36:39]
	v_mfma_f32_16x16x32_bf16 v[32:35], v[218:221], v[234:237], v[32:35]
	v_mfma_f32_16x16x32_bf16 v[20:23], v[210:213], v[242:245], v[20:23]
	v_mfma_f32_16x16x32_bf16 v[16:19], v[218:221], v[242:245], v[16:19]
	v_mfma_f32_16x16x32_bf16 v[4:7], v[210:213], v[250:253], v[4:7]
	v_mfma_f32_16x16x32_bf16 v[0:3], v[218:221], v[250:253], v[0:3]
	s_barrier
	s_add_i32 s55, s55, 2
	s_add_i32 s84, s84, 0x10000
	s_cmp_gt_u32 s55, 29
	s_mov_b64 s[52:53], s[56:57]
	s_cbranch_scc0 .LBB0_632
	s_and_b64 vcc, exec, s[24:25]
	s_cbranch_vccz .LBB0_635
	s_barrier

; #define PG8_STAGE(bufoff, gbase, voff) do { const unsigned long long gb_ = (unsigned long long)(gbase); _Pragma("unroll") for (int _i = 0; _i < 2; ++_i) { unsigned keep_; \
;         asm volatile("s_mov_b32 m0, %2\n\ts_nop 0\n\tglobal_load_lds_dwordx4 %0, %1" : : "v"((voff)[_i]), "s"(gb_), "s"((unsigned)(size_t)(lds + (bufoff) + ldsw + _i * 8192)) : "memory", "m0"); (void)keep_; } } while (0)
; #define PG8_LDA(dst, b, h) do { _Pragma("unroll") for (int m = 0; m < 4; ++m) _Pragma("unroll") for (int k = 0; k < 2; ++k) dst[m][k] = *(const PG8_LAS bf16x8*)(lds + PG8_SA(b, h) + aoff + m * 2048 + k * 1024); } while (0)
; #define PG8_LDB(dst, b, h) do { _Pragma("unroll") for (int n = 0; n < 2; ++n) _Pragma("unroll") for (int k = 0; k < 2; ++k) dst[n][k] = *(const PG8_LAS bf16x8*)(lds + PG8_SB(b, h) + boff + n * 2048 + k * 1024); } while (0)
; #define PG8_MMA(ai, bj, At, Bt) do { __builtin_amdgcn_s_setprio(1); _Pragma("unroll") for (int m = 0; m < 4; ++m) _Pragma("unroll") for (int n = 0; n < 2; ++n) _Pragma("unroll") for (int k = 0; k < 2; ++k) \
;         acc[ai][bj][m][n] = __builtin_amdgcn_mfma_f32_16x16x32_bf16(Bt[n][k], At[m][k], acc[ai][bj][m][n], 0, 0, 0); __builtin_amdgcn_s_setprio(0); } while (0)
; #define PG8_WAIT_V(n) asm volatile("s_waitcnt vmcnt(" #n ")" ::: "memory")
; #define PG8_BAR __builtin_amdgcn_s_barrier()
; template <class Epi, class Sched, bool ALIGN_EPI = false, bool SP2 = false>
; __device__ __forceinline__ void gemm_phase(PG8_LAS unsigned char* lds, const Gemm g, const Sched& S, const Epi& E) {
;     ...
;         for (int t = 0; t < nt; t += 2) {
;             const bool last = (t == nt - 2);
;     ...
;             const char* a1 = cA + PG8_KOFFA(t + 1);
;             const char* a2 = last ? nA : cA + PG8_KOFFA(t + 2); const char* b2 = last ? nB : cB + (size_t)(t + 2) * kstep;
;             const char* a3 = last ? nA + kstep : cA + PG8_KOFFA(t + 3); const char* b3 = b2 + kstep;
;     ...
;             if (last && has_next) S.a_ready(nxt);
;             if constexpr (SP2) {
;             PG8_LDB(B0, 0, 0); PG8_LDB(B1, 0, 1); PG8_SCHED; PG8_LDA(At, 0, 0); PG8_STAGE(PG8_SA(1, 1), a1 + hstepA, voffA);
;             PG8_WAIT_V(8); PG8_WAIT_L(0); PG8_BAR; PG8_MMA(0, 0, At, B0); PG8_MMA(0, 1, At, B1); PG8_BAR; PG8_SCHED;
;             PG8_LDA(At, 0, 1); PG8_STAGE(PG8_SB(0, 0), b2, voffB); PG8_STAGE(PG8_SB(0, 1), b2 + hstepB, voffB); PG8_STAGE(PG8_SA(0, 0), a2, voffA);
.LBB0_840:
	s_add_i32 s72, s44, 2
	s_lshr_b32 s12, s72, 2
	s_lshl_b64 s[76:77], s[12:13], 17
	s_add_i32 s12, s42, 0xffffff00
	s_and_b32 s73, s12, 0x100
	s_add_i32 s12, s44, 4
	s_lshr_b32 s12, s12, 2
	s_lshl_b64 s[46:47], s[12:13], 17
	s_and_b32 s12, s42, 0x100
	s_add_u32 s45, s40, s46
	s_addc_u32 s46, s41, s47
	s_add_u32 s45, s45, s12
	s_addc_u32 s48, s46, 0
	s_add_u32 s78, s38, s42
	ds_read_b128 v[104:107], v185
	ds_read_b128 v[116:119], v185 offset:1024
	ds_read_b128 v[128:131], v185 offset:2048
	ds_read_b128 v[140:143], v185 offset:3072
	ds_read_b128 v[144:147], v214
	ds_read_b128 v[148:151], v214 offset:1024
	ds_read_b128 v[152:155], v214 offset:2048
	ds_read_b128 v[156:159], v214 offset:3072
	s_addc_u32 s79, s39, s43
	s_add_i32 s12, s44, 5
	s_lshr_b32 s12, s12, 2
	s_lshl_b64 s[46:47], s[12:13], 17
	s_add_i32 s12, s42, 0x80
	s_and_b32 s12, s12, 0x180
	s_add_u32 s46, s40, s46
	s_addc_u32 s47, s41, s47
	s_add_u32 s12, s46, s12
	s_addc_u32 s80, s47, 0
	s_cmp_eq_u32 s44, 60
	s_cselect_b32 s44, s37, s12
	s_cselect_b32 s49, s0, s48
	s_cselect_b32 s48, s1, s45
	s_cselect_b32 s47, s25, s79
	s_cselect_b32 s46, s27, s78
	s_cselect_b32 s45, s71, s80
	ds_read_b128 v[160:163], v215
	ds_read_b128 v[164:167], v215 offset:1024
	ds_read_b128 v[168:171], v215 offset:2048
	ds_read_b128 v[172:175], v215 offset:3072
	ds_read_b128 v[176:179], v215 offset:4096
	ds_read_b128 v[180:183], v215 offset:5120
	ds_read_b128 v[220:223], v215 offset:6144
	ds_read_b128 v[224:227], v215 offset:7168
	s_add_u32 s12, s40, s76
	s_addc_u32 s76, s41, s77
	s_add_u32 s12, s12, s73
	s_addc_u32 s73, s76, 0
	s_add_u32 s76, s12, 0x10080
	s_addc_u32 s77, s73, 0
	s_mov_b32 m0, s66
	s_nop 0
	global_load_lds_dwordx4 v187, s[76:77]
	s_nop 0
	s_mov_b32 m0, s67
	s_nop 0
	global_load_lds_dwordx4 v212, s[76:77]
	s_waitcnt vmcnt(8)
	s_waitcnt lgkmcnt(0)
	s_barrier
	v_mfma_f32_16x16x32_bf16 v[136:139], v[104:107], v[160:163], v[136:139]
	v_mfma_f32_16x16x32_bf16 v[132:135], v[128:131], v[160:163], v[132:135]
	v_mfma_f32_16x16x32_bf16 v[112:115], v[104:107], v[168:171], v[112:115]
	v_mfma_f32_16x16x32_bf16 v[108:111], v[128:131], v[168:171], v[108:111]
	v_mfma_f32_16x16x32_bf16 v[92:95], v[104:107], v[176:179], v[92:95]
	v_mfma_f32_16x16x32_bf16 v[88:91], v[128:131], v[176:179], v[88:91]
	v_mfma_f32_16x16x32_bf16 v[76:79], v[104:107], v[220:223], v[76:79]
	v_mfma_f32_16x16x32_bf16 v[72:75], v[128:131], v[220:223], v[72:75]
	v_mfma_f32_16x16x32_bf16 v[136:139], v[116:119], v[164:167], v[136:139]
	v_mfma_f32_16x16x32_bf16 v[132:135], v[140:143], v[164:167], v[132:135]
	v_mfma_f32_16x16x32_bf16 v[112:115], v[116:119], v[172:175], v[112:115]
	v_mfma_f32_16x16x32_bf16 v[108:111], v[140:143], v[172:175], v[108:111]
	v_mfma_f32_16x16x32_bf16 v[92:95], v[116:119], v[180:183], v[92:95]
	v_mfma_f32_16x16x32_bf16 v[88:91], v[140:143], v[180:183], v[88:91]
	v_mfma_f32_16x16x32_bf16 v[76:79], v[116:119], v[224:227], v[76:79]
	v_mfma_f32_16x16x32_bf16 v[72:75], v[140:143], v[224:227], v[72:75]
	v_mfma_f32_16x16x32_bf16 v[124:127], v[144:147], v[160:163], v[124:127]
	v_mfma_f32_16x16x32_bf16 v[120:123], v[152:155], v[160:163], v[120:123]
	v_mfma_f32_16x16x32_bf16 v[100:103], v[144:147], v[168:171], v[100:103]
	v_mfma_f32_16x16x32_bf16 v[96:99], v[152:155], v[168:171], v[96:99]
	v_mfma_f32_16x16x32_bf16 v[84:87], v[144:147], v[176:179], v[84:87]
	v_mfma_f32_16x16x32_bf16 v[80:83], v[152:155], v[176:179], v[80:83]
	v_mfma_f32_16x16x32_bf16 v[68:71], v[144:147], v[220:223], v[68:71]
	v_mfma_f32_16x16x32_bf16 v[64:67], v[152:155], v[220:223], v[64:67]
	v_mfma_f32_16x16x32_bf16 v[124:127], v[148:151], v[164:167], v[124:127]
	v_mfma_f32_16x16x32_bf16 v[120:123], v[156:159], v[164:167], v[120:123]
	v_mfma_f32_16x16x32_bf16 v[100:103], v[148:151], v[172:175], v[100:103]
	v_mfma_f32_16x16x32_bf16 v[96:99], v[156:159], v[172:175], v[96:99]
	v_mfma_f32_16x16x32_bf16 v[84:87], v[148:151], v[180:183], v[84:87]
	v_mfma_f32_16x16x32_bf16 v[80:83], v[156:159], v[180:183], v[80:83]
	v_mfma_f32_16x16x32_bf16 v[68:71], v[148:151], v[224:227], v[68:71]
	v_mfma_f32_16x16x32_bf16 v[64:67], v[156:159], v[224:227], v[64:67]
	s_barrier
	ds_read_b128 v[160:163], v215 offset:16384
	ds_read_b128 v[164:167], v215 offset:17408
	ds_read_b128 v[168:171], v215 offset:18432
	ds_read_b128 v[172:175], v215 offset:19456
	ds_read_b128 v[176:179], v215 offset:20480
	ds_read_b128 v[180:183], v215 offset:21504
	ds_read_b128 v[220:223], v215 offset:22528
	ds_read_b128 v[224:227], v215 offset:23552
	s_mov_b32 m0, s52
	s_nop 0
	global_load_lds_dwordx4 v201, s[46:47]
	s_add_u32 s76, s46, 0x100000
	s_mov_b32 m0, s53
	s_nop 0
	global_load_lds_dwordx4 v213, s[46:47]
	s_addc_u32 s77, s47, 0
	s_mov_b32 m0, s54
	s_nop 0
	global_load_lds_dwordx4 v201, s[76:77]
	s_nop 0
	s_mov_b32 m0, s55
	s_nop 0
	global_load_lds_dwordx4 v213, s[76:77]
	s_nop 0
	s_mov_b32 m0, s35
	s_nop 0
	global_load_lds_dwordx4 v187, s[48:49]
	s_nop 0
	s_mov_b32 m0, s56
	s_nop 0
	global_load_lds_dwordx4 v212, s[48:49]
	s_waitcnt vmcnt(8)
	s_waitcnt lgkmcnt(0)
	s_barrier
; #define PG8_STAGE(bufoff, gbase, voff) do { const unsigned long long gb_ = (unsigned long long)(gbase); _Pragma("unroll") for (int _i = 0; _i < 2; ++_i) { unsigned keep_; \
;         asm volatile("s_mov_b32 m0, %2\n\ts_nop 0\n\tglobal_load_lds_dwordx4 %0, %1" : : "v"((voff)[_i]), "s"(gb_), "s"((unsigned)(size_t)(lds + (bufoff) + ldsw + _i * 8192)) : "memory", "m0"); (void)keep_; } } while (0)
; #define PG8_LDA(dst, b, h) do { _Pragma("unroll") for (int m = 0; m < 4; ++m) _Pragma("unroll") for (int k = 0; k < 2; ++k) dst[m][k] = *(const PG8_LAS bf16x8*)(lds + PG8_SA(b, h) + aoff + m * 2048 + k * 1024); } while (0)
; #define PG8_LDB(dst, b, h) do { _Pragma("unroll") for (int n = 0; n < 2; ++n) _Pragma("unroll") for (int k = 0; k < 2; ++k) dst[n][k] = *(const PG8_LAS bf16x8*)(lds + PG8_SB(b, h) + boff + n * 2048 + k * 1024); } while (0)
; #define PG8_MMA(ai, bj, At, Bt) do { __builtin_amdgcn_s_setprio(1); _Pragma("unroll") for (int m = 0; m < 4; ++m) _Pragma("unroll") for (int n = 0; n < 2; ++n) _Pragma("unroll") for (int k = 0; k < 2; ++k) \
;         acc[ai][bj][m][n] = __builtin_amdgcn_mfma_f32_16x16x32_bf16(Bt[n][k], At[m][k], acc[ai][bj][m][n], 0, 0, 0); __builtin_amdgcn_s_setprio(0); } while (0)
; #define PG8_WAIT_V(n) asm volatile("s_waitcnt vmcnt(" #n ")" ::: "memory")
; #define PG8_WAIT_L(n) asm volatile("s_waitcnt lgkmcnt(" #n ")" ::: "memory")
; #define PG8_BAR __builtin_amdgcn_s_barrier()
; #define PG8_SCHED __builtin_amdgcn_sched_barrier(0)
; template <class Epi, class Sched, bool ALIGN_EPI = false, bool SP2 = false>
; __device__ __forceinline__ void gemm_phase(PG8_LAS unsigned char* lds, const Gemm g, const Sched& S, const Epi& E) {
;     ...
;             PG8_WAIT_V(8); PG8_WAIT_L(0); PG8_BAR; PG8_MMA(1, 0, At, B0); PG8_MMA(1, 1, At, B1); PG8_BAR; PG8_SCHED;
;             PG8_LDB(B0, 1, 0); PG8_LDB(B1, 1, 1); PG8_SCHED; PG8_LDA(At, 1, 0); PG8_STAGE(PG8_SA(0, 1), a2 + hstepA, voffA);
;             PG8_WAIT_V(8); PG8_WAIT_L(0); PG8_BAR; PG8_MMA(0, 0, At, B0); PG8_MMA(0, 1, At, B1); PG8_BAR; PG8_SCHED;
	v_mfma_f32_16x16x32_bf16 v[60:63], v[104:107], v[160:163], v[60:63]
	v_mfma_f32_16x16x32_bf16 v[56:59], v[128:131], v[160:163], v[56:59]
	v_mfma_f32_16x16x32_bf16 v[44:47], v[104:107], v[168:171], v[44:47]
	v_mfma_f32_16x16x32_bf16 v[40:43], v[128:131], v[168:171], v[40:43]
	v_mfma_f32_16x16x32_bf16 v[28:31], v[104:107], v[176:179], v[28:31]
	v_mfma_f32_16x16x32_bf16 v[24:27], v[128:131], v[176:179], v[24:27]
	v_mfma_f32_16x16x32_bf16 v[12:15], v[104:107], v[220:223], v[12:15]
	v_mfma_f32_16x16x32_bf16 v[8:11], v[128:131], v[220:223], v[8:11]
	v_mfma_f32_16x16x32_bf16 v[60:63], v[116:119], v[164:167], v[60:63]
	v_mfma_f32_16x16x32_bf16 v[56:59], v[140:143], v[164:167], v[56:59]
	v_mfma_f32_16x16x32_bf16 v[44:47], v[116:119], v[172:175], v[44:47]
	v_mfma_f32_16x16x32_bf16 v[40:43], v[140:143], v[172:175], v[40:43]
	v_mfma_f32_16x16x32_bf16 v[28:31], v[116:119], v[180:183], v[28:31]
	v_mfma_f32_16x16x32_bf16 v[24:27], v[140:143], v[180:183], v[24:27]
	v_mfma_f32_16x16x32_bf16 v[12:15], v[116:119], v[224:227], v[12:15]
	v_mfma_f32_16x16x32_bf16 v[8:11], v[140:143], v[224:227], v[8:11]
	v_mfma_f32_16x16x32_bf16 v[52:55], v[144:147], v[160:163], v[52:55]
	v_mfma_f32_16x16x32_bf16 v[48:51], v[152:155], v[160:163], v[48:51]
	v_mfma_f32_16x16x32_bf16 v[36:39], v[144:147], v[168:171], v[36:39]
	v_mfma_f32_16x16x32_bf16 v[32:35], v[152:155], v[168:171], v[32:35]
	v_mfma_f32_16x16x32_bf16 v[20:23], v[144:147], v[176:179], v[20:23]
	v_mfma_f32_16x16x32_bf16 v[16:19], v[152:155], v[176:179], v[16:19]
	v_mfma_f32_16x16x32_bf16 v[4:7], v[144:147], v[220:223], v[4:7]
	v_mfma_f32_16x16x32_bf16 v[0:3], v[152:155], v[220:223], v[0:3]
	v_mfma_f32_16x16x32_bf16 v[52:55], v[148:151], v[164:167], v[52:55]
	v_mfma_f32_16x16x32_bf16 v[48:51], v[156:159], v[164:167], v[48:51]
	v_mfma_f32_16x16x32_bf16 v[36:39], v[148:151], v[172:175], v[36:39]
	v_mfma_f32_16x16x32_bf16 v[32:35], v[156:159], v[172:175], v[32:35]
	v_mfma_f32_16x16x32_bf16 v[20:23], v[148:151], v[180:183], v[20:23]
	v_mfma_f32_16x16x32_bf16 v[16:19], v[156:159], v[180:183], v[16:19]
	v_mfma_f32_16x16x32_bf16 v[4:7], v[148:151], v[224:227], v[4:7]
	v_mfma_f32_16x16x32_bf16 v[0:3], v[156:159], v[224:227], v[0:3]
	s_barrier
	ds_read_b128 v[104:107], v216
	ds_read_b128 v[116:119], v216 offset:1024
	ds_read_b128 v[128:131], v216 offset:2048
	ds_read_b128 v[140:143], v216 offset:3072
	ds_read_b128 v[144:147], v217
	ds_read_b128 v[148:151], v217 offset:1024
	ds_read_b128 v[152:155], v217 offset:2048
	ds_read_b128 v[156:159], v217 offset:3072
	ds_read_b128 v[160:163], v215 offset:32768
	ds_read_b128 v[164:167], v215 offset:33792
	ds_read_b128 v[168:171], v215 offset:34816
	ds_read_b128 v[172:175], v215 offset:35840
	ds_read_b128 v[176:179], v215 offset:36864
	ds_read_b128 v[180:183], v215 offset:37888
	ds_read_b128 v[220:223], v215 offset:38912
	ds_read_b128 v[224:227], v215 offset:39936
	s_add_u32 s48, s48, 0x10000
	s_addc_u32 s49, s49, 0
	s_mov_b32 m0, s57
	s_nop 0
	global_load_lds_dwordx4 v187, s[48:49]
	s_nop 0
	s_mov_b32 m0, s58
	s_nop 0
	global_load_lds_dwordx4 v212, s[48:49]
	s_waitcnt vmcnt(8)
	s_waitcnt lgkmcnt(0)
	s_barrier
	v_mfma_f32_16x16x32_bf16 v[136:139], v[104:107], v[160:163], v[136:139]
	v_mfma_f32_16x16x32_bf16 v[132:135], v[128:131], v[160:163], v[132:135]
	v_mfma_f32_16x16x32_bf16 v[112:115], v[104:107], v[168:171], v[112:115]
	v_mfma_f32_16x16x32_bf16 v[108:111], v[128:131], v[168:171], v[108:111]
	v_mfma_f32_16x16x32_bf16 v[92:95], v[104:107], v[176:179], v[92:95]
	v_mfma_f32_16x16x32_bf16 v[88:91], v[128:131], v[176:179], v[88:91]
	v_mfma_f32_16x16x32_bf16 v[76:79], v[104:107], v[220:223], v[76:79]
	v_mfma_f32_16x16x32_bf16 v[72:75], v[128:131], v[220:223], v[72:75]
	v_mfma_f32_16x16x32_bf16 v[136:139], v[116:119], v[164:167], v[136:139]
	v_mfma_f32_16x16x32_bf16 v[132:135], v[140:143], v[164:167], v[132:135]
	v_mfma_f32_16x16x32_bf16 v[112:115], v[116:119], v[172:175], v[112:115]
	v_mfma_f32_16x16x32_bf16 v[108:111], v[140:143], v[172:175], v[108:111]
	v_mfma_f32_16x16x32_bf16 v[92:95], v[116:119], v[180:183], v[92:95]
	v_mfma_f32_16x16x32_bf16 v[88:91], v[140:143], v[180:183], v[88:91]
	v_mfma_f32_16x16x32_bf16 v[76:79], v[116:119], v[224:227], v[76:79]
	v_mfma_f32_16x16x32_bf16 v[72:75], v[140:143], v[224:227], v[72:75]
	v_mfma_f32_16x16x32_bf16 v[124:127], v[144:147], v[160:163], v[124:127]
	v_mfma_f32_16x16x32_bf16 v[120:123], v[152:155], v[160:163], v[120:123]
	v_mfma_f32_16x16x32_bf16 v[100:103], v[144:147], v[168:171], v[100:103]
	v_mfma_f32_16x16x32_bf16 v[96:99], v[152:155], v[168:171], v[96:99]
	v_mfma_f32_16x16x32_bf16 v[84:87], v[144:147], v[176:179], v[84:87]
	v_mfma_f32_16x16x32_bf16 v[80:83], v[152:155], v[176:179], v[80:83]
	v_mfma_f32_16x16x32_bf16 v[68:71], v[144:147], v[220:223], v[68:71]
	v_mfma_f32_16x16x32_bf16 v[64:67], v[152:155], v[220:223], v[64:67]
	v_mfma_f32_16x16x32_bf16 v[124:127], v[148:151], v[164:167], v[124:127]
	v_mfma_f32_16x16x32_bf16 v[120:123], v[156:159], v[164:167], v[120:123]
	v_mfma_f32_16x16x32_bf16 v[100:103], v[148:151], v[172:175], v[100:103]
	v_mfma_f32_16x16x32_bf16 v[96:99], v[156:159], v[172:175], v[96:99]
	v_mfma_f32_16x16x32_bf16 v[84:87], v[148:151], v[180:183], v[84:87]
	v_mfma_f32_16x16x32_bf16 v[80:83], v[156:159], v[180:183], v[80:83]
	v_mfma_f32_16x16x32_bf16 v[68:71], v[148:151], v[224:227], v[68:71]
	v_mfma_f32_16x16x32_bf16 v[64:67], v[156:159], v[224:227], v[64:67]
	s_barrier
; #define PG8_STAGE(bufoff, gbase, voff) do { const unsigned long long gb_ = (unsigned long long)(gbase); _Pragma("unroll") for (int _i = 0; _i < 2; ++_i) { unsigned keep_; \
;         asm volatile("s_mov_b32 m0, %2\n\ts_nop 0\n\tglobal_load_lds_dwordx4 %0, %1" : : "v"((voff)[_i]), "s"(gb_), "s"((unsigned)(size_t)(lds + (bufoff) + ldsw + _i * 8192)) : "memory", "m0"); (void)keep_; } } while (0)
; #define PG8_LDA(dst, b, h) do { _Pragma("unroll") for (int m = 0; m < 4; ++m) _Pragma("unroll") for (int k = 0; k < 2; ++k) dst[m][k] = *(const PG8_LAS bf16x8*)(lds + PG8_SA(b, h) + aoff + m * 2048 + k * 1024); } while (0)
; #define PG8_MMA(ai, bj, At, Bt) do { __builtin_amdgcn_s_setprio(1); _Pragma("unroll") for (int m = 0; m < 4; ++m) _Pragma("unroll") for (int n = 0; n < 2; ++n) _Pragma("unroll") for (int k = 0; k < 2; ++k) \
;         acc[ai][bj][m][n] = __builtin_amdgcn_mfma_f32_16x16x32_bf16(Bt[n][k], At[m][k], acc[ai][bj][m][n], 0, 0, 0); __builtin_amdgcn_s_setprio(0); } while (0)
; #define PG8_WAIT_V(n) asm volatile("s_waitcnt vmcnt(" #n ")" ::: "memory")
; #define PG8_WAIT_L(n) asm volatile("s_waitcnt lgkmcnt(" #n ")" ::: "memory")
; #define PG8_BAR __builtin_amdgcn_s_barrier()
; #define PG8_SCHED __builtin_amdgcn_sched_barrier(0)
; template <class Epi, class Sched, bool ALIGN_EPI = false, bool SP2 = false>
; __device__ __forceinline__ void gemm_phase(PG8_LAS unsigned char* lds, const Gemm g, const Sched& S, const Epi& E) {
;     ...
;         for (int t = 0; t < nt; t += 2) {
;     ...
;             PG8_LDA(At, 1, 1); PG8_STAGE(PG8_SB(1, 0), b3, voffB); PG8_STAGE(PG8_SB(1, 1), b3 + hstepB, voffB); PG8_STAGE(PG8_SA(1, 0), a3, voffA);
;             PG8_WAIT_V(8); PG8_WAIT_L(0); PG8_BAR; PG8_MMA(1, 0, At, B0); PG8_MMA(1, 1, At, B1); PG8_BAR; PG8_SCHED;
	ds_read_b128 v[160:163], v215 offset:49152
	ds_read_b128 v[164:167], v215 offset:50176
	ds_read_b128 v[168:171], v215 offset:51200
	ds_read_b128 v[172:175], v215 offset:52224
	ds_read_b128 v[176:179], v215 offset:53248
	ds_read_b128 v[180:183], v215 offset:54272
	ds_read_b128 v[220:223], v215 offset:55296
	ds_read_b128 v[224:227], v215 offset:56320
	s_add_u32 s48, s46, 0x80
	s_addc_u32 s49, s47, 0
	s_mov_b32 m0, s60
	s_nop 0
	global_load_lds_dwordx4 v201, s[48:49]
	s_add_u32 s46, s46, 0x100080
	s_mov_b32 m0, s61
	s_nop 0
	global_load_lds_dwordx4 v213, s[48:49]
	s_addc_u32 s47, s47, 0
	s_mov_b32 m0, s64
	s_nop 0
	global_load_lds_dwordx4 v201, s[46:47]
	s_nop 0
	s_mov_b32 m0, s65
	s_nop 0
	global_load_lds_dwordx4 v213, s[46:47]
	s_nop 0
	s_mov_b32 m0, s62
	s_nop 0
	global_load_lds_dwordx4 v187, s[44:45]
	s_nop 0
	s_mov_b32 m0, s63
	s_nop 0
	global_load_lds_dwordx4 v212, s[44:45]
	s_waitcnt vmcnt(8)
	s_waitcnt lgkmcnt(0)
	s_barrier
	v_mfma_f32_16x16x32_bf16 v[60:63], v[104:107], v[160:163], v[60:63]
	v_mfma_f32_16x16x32_bf16 v[56:59], v[128:131], v[160:163], v[56:59]
	v_mfma_f32_16x16x32_bf16 v[44:47], v[104:107], v[168:171], v[44:47]
	v_mfma_f32_16x16x32_bf16 v[40:43], v[128:131], v[168:171], v[40:43]
	v_mfma_f32_16x16x32_bf16 v[28:31], v[104:107], v[176:179], v[28:31]
	v_mfma_f32_16x16x32_bf16 v[24:27], v[128:131], v[176:179], v[24:27]
	v_mfma_f32_16x16x32_bf16 v[12:15], v[104:107], v[220:223], v[12:15]
	v_mfma_f32_16x16x32_bf16 v[8:11], v[128:131], v[220:223], v[8:11]
	v_mfma_f32_16x16x32_bf16 v[60:63], v[116:119], v[164:167], v[60:63]
	v_mfma_f32_16x16x32_bf16 v[56:59], v[140:143], v[164:167], v[56:59]
	v_mfma_f32_16x16x32_bf16 v[44:47], v[116:119], v[172:175], v[44:47]
	v_mfma_f32_16x16x32_bf16 v[40:43], v[140:143], v[172:175], v[40:43]
	v_mfma_f32_16x16x32_bf16 v[28:31], v[116:119], v[180:183], v[28:31]
	v_mfma_f32_16x16x32_bf16 v[24:27], v[140:143], v[180:183], v[24:27]
	v_mfma_f32_16x16x32_bf16 v[12:15], v[116:119], v[224:227], v[12:15]
	v_mfma_f32_16x16x32_bf16 v[8:11], v[140:143], v[224:227], v[8:11]
	v_mfma_f32_16x16x32_bf16 v[52:55], v[144:147], v[160:163], v[52:55]
	v_mfma_f32_16x16x32_bf16 v[48:51], v[152:155], v[160:163], v[48:51]
	v_mfma_f32_16x16x32_bf16 v[36:39], v[144:147], v[168:171], v[36:39]
	v_mfma_f32_16x16x32_bf16 v[32:35], v[152:155], v[168:171], v[32:35]
	v_mfma_f32_16x16x32_bf16 v[20:23], v[144:147], v[176:179], v[20:23]
	v_mfma_f32_16x16x32_bf16 v[16:19], v[152:155], v[176:179], v[16:19]
	v_mfma_f32_16x16x32_bf16 v[4:7], v[144:147], v[220:223], v[4:7]
	v_mfma_f32_16x16x32_bf16 v[0:3], v[152:155], v[220:223], v[0:3]
	v_mfma_f32_16x16x32_bf16 v[52:55], v[148:151], v[164:167], v[52:55]
	v_mfma_f32_16x16x32_bf16 v[48:51], v[156:159], v[164:167], v[48:51]
	v_mfma_f32_16x16x32_bf16 v[36:39], v[148:151], v[172:175], v[36:39]
	v_mfma_f32_16x16x32_bf16 v[32:35], v[156:159], v[172:175], v[32:35]
	v_mfma_f32_16x16x32_bf16 v[20:23], v[148:151], v[180:183], v[20:23]
	v_mfma_f32_16x16x32_bf16 v[16:19], v[156:159], v[180:183], v[16:19]
	v_mfma_f32_16x16x32_bf16 v[4:7], v[148:151], v[224:227], v[4:7]
	v_mfma_f32_16x16x32_bf16 v[0:3], v[156:159], v[224:227], v[0:3]
	s_barrier
	s_add_u32 s42, s42, 0x100
	s_addc_u32 s43, s43, 0
	s_cmp_gt_u32 s72, 61
	s_mov_b32 s44, s72
	s_cbranch_scc0 .LBB0_840
	s_and_b64 vcc, exec, s[22:23]
	s_cbranch_vccz .LBB0_843
	s_barrier

; #define PG8_STAGE(bufoff, gbase, voff) do { const unsigned long long gb_ = (unsigned long long)(gbase); _Pragma("unroll") for (int _i = 0; _i < 2; ++_i) { unsigned keep_; \
;         asm volatile("s_mov_b32 m0, %2\n\ts_nop 0\n\tglobal_load_lds_dwordx4 %0, %1" : : "v"((voff)[_i]), "s"(gb_), "s"((unsigned)(size_t)(lds + (bufoff) + ldsw + _i * 8192)) : "memory", "m0"); (void)keep_; } } while (0)
; #define PG8_LDA(dst, b, h) do { _Pragma("unroll") for (int m = 0; m < 4; ++m) _Pragma("unroll") for (int k = 0; k < 2; ++k) dst[m][k] = *(const PG8_LAS bf16x8*)(lds + PG8_SA(b, h) + aoff + m * 2048 + k * 1024); } while (0)
; #define PG8_LDB(dst, b, h) do { _Pragma("unroll") for (int n = 0; n < 2; ++n) _Pragma("unroll") for (int k = 0; k < 2; ++k) dst[n][k] = *(const PG8_LAS bf16x8*)(lds + PG8_SB(b, h) + boff + n * 2048 + k * 1024); } while (0)
; #define PG8_MMA(ai, bj, At, Bt) do { __builtin_amdgcn_s_setprio(1); _Pragma("unroll") for (int m = 0; m < 4; ++m) _Pragma("unroll") for (int n = 0; n < 2; ++n) _Pragma("unroll") for (int k = 0; k < 2; ++k) \
;         acc[ai][bj][m][n] = __builtin_amdgcn_mfma_f32_16x16x32_bf16(Bt[n][k], At[m][k], acc[ai][bj][m][n], 0, 0, 0); __builtin_amdgcn_s_setprio(0); } while (0)
; #define PG8_WAIT_V(n) asm volatile("s_waitcnt vmcnt(" #n ")" ::: "memory")
; #define PG8_BAR __builtin_amdgcn_s_barrier()
; template <class Epi, class Sched, bool ALIGN_EPI = false, bool SP2 = false>
; __device__ __forceinline__ void gemm_phase(PG8_LAS unsigned char* lds, const Gemm g, const Sched& S, const Epi& E) {
;     ...
;         for (int t = 0; t < nt; t += 2) {
;             const bool last = (t == nt - 2);
;     ...
;             const char* a1 = cA + PG8_KOFFA(t + 1);
;             const char* a2 = last ? nA : cA + PG8_KOFFA(t + 2); const char* b2 = last ? nB : cB + (size_t)(t + 2) * kstep;
;             const char* a3 = last ? nA + kstep : cA + PG8_KOFFA(t + 3); const char* b3 = b2 + kstep;
;     ...
;             if (last && has_next) S.a_ready(nxt);
;             if constexpr (SP2) {
;             PG8_LDB(B0, 0, 0); PG8_LDB(B1, 0, 1); PG8_SCHED; PG8_LDA(At, 0, 0); PG8_STAGE(PG8_SA(1, 1), a1 + hstepA, voffA);
;             PG8_WAIT_V(8); PG8_WAIT_L(0); PG8_BAR; PG8_MMA(0, 0, At, B0); PG8_MMA(0, 1, At, B1); PG8_BAR; PG8_SCHED;
;             PG8_LDA(At, 0, 1); PG8_STAGE(PG8_SB(0, 0), b2, voffB); PG8_STAGE(PG8_SB(0, 1), b2 + hstepB, voffB); PG8_STAGE(PG8_SA(0, 0), a2, voffA);
.LBB0_953:
	s_add_i32 s37, s71, 0xfffe8000
	s_and_b32 s36, s34, 0x100
	s_and_b32 s37, s37, 0xe0000
	s_or_b32 s36, s36, s37
	s_add_u32 s72, s8, s36
	s_addc_u32 s73, s9, 0
	s_add_u32 s36, s34, 0x100
	s_addc_u32 s37, s35, 0
	s_add_i32 s39, s71, 0xffff8000
	s_and_b32 s38, s36, 0x100
	s_and_b32 s39, s39, 0x1e0000
	s_or_b32 s38, s39, s38
	ds_read_b128 v[156:159], v177
	ds_read_b128 v[184:187], v177 offset:1024
	ds_read_b128 v[188:191], v177 offset:2048
	ds_read_b128 v[192:195], v177 offset:3072
	ds_read_b128 v[196:199], v178
	ds_read_b128 v[202:205], v178 offset:1024
	ds_read_b128 v[206:209], v178 offset:2048
	ds_read_b128 v[210:213], v178 offset:3072
	s_add_u32 s38, s8, s38
	s_addc_u32 s39, s9, 0
	s_add_u32 s76, s68, s34
	s_addc_u32 s35, s69, s35
	s_add_i32 s40, s34, 0x180
	s_and_b32 s40, s40, 0x180
	s_and_b32 s41, s71, 0x1e0000
	s_or_b32 s40, s41, s40
	s_add_u32 s77, s8, s40
	s_addc_u32 s78, s9, 0
	s_cmpk_eq_i32 s34, 0xf00
	s_cselect_b32 s41, s0, s39
	s_cselect_b32 s39, s21, s35
	s_cselect_b32 s35, s67, s78
	s_cselect_b32 s34, s29, s77
	s_cselect_b32 s40, s1, s38
	s_cselect_b32 s38, s23, s76
	ds_read_b128 v[214:217], v179
	ds_read_b128 v[218:221], v179 offset:1024
	ds_read_b128 v[222:225], v179 offset:2048
	ds_read_b128 v[226:229], v179 offset:3072
	ds_read_b128 v[230:233], v179 offset:4096
	ds_read_b128 v[234:237], v179 offset:5120
	ds_read_b128 v[238:241], v179 offset:6144
	ds_read_b128 v[242:245], v179 offset:7168
	s_add_u32 s72, s72, 0x10080
	s_addc_u32 s73, s73, 0
	s_mov_b32 m0, s61
	s_nop 0
	global_load_lds_dwordx4 v161, s[72:73]
	s_nop 0
	s_mov_b32 m0, s62
	s_nop 0
	global_load_lds_dwordx4 v163, s[72:73]
	s_waitcnt vmcnt(8)
	s_waitcnt lgkmcnt(0)
	s_barrier
	v_mfma_f32_16x16x32_bf16 v[124:127], v[156:159], v[214:217], v[124:127]
	v_mfma_f32_16x16x32_bf16 v[116:119], v[188:191], v[214:217], v[116:119]
	v_mfma_f32_16x16x32_bf16 v[108:111], v[156:159], v[222:225], v[108:111]
	v_mfma_f32_16x16x32_bf16 v[100:103], v[188:191], v[222:225], v[100:103]
	v_mfma_f32_16x16x32_bf16 v[92:95], v[156:159], v[230:233], v[92:95]
	v_mfma_f32_16x16x32_bf16 v[84:87], v[188:191], v[230:233], v[84:87]
	v_mfma_f32_16x16x32_bf16 v[76:79], v[156:159], v[238:241], v[76:79]
	v_mfma_f32_16x16x32_bf16 v[68:71], v[188:191], v[238:241], v[68:71]
	v_mfma_f32_16x16x32_bf16 v[124:127], v[184:187], v[218:221], v[124:127]
	v_mfma_f32_16x16x32_bf16 v[116:119], v[192:195], v[218:221], v[116:119]
	v_mfma_f32_16x16x32_bf16 v[108:111], v[184:187], v[226:229], v[108:111]
	v_mfma_f32_16x16x32_bf16 v[100:103], v[192:195], v[226:229], v[100:103]
	v_mfma_f32_16x16x32_bf16 v[92:95], v[184:187], v[234:237], v[92:95]
	v_mfma_f32_16x16x32_bf16 v[84:87], v[192:195], v[234:237], v[84:87]
	v_mfma_f32_16x16x32_bf16 v[76:79], v[184:187], v[242:245], v[76:79]
	v_mfma_f32_16x16x32_bf16 v[68:71], v[192:195], v[242:245], v[68:71]
	v_mfma_f32_16x16x32_bf16 v[120:123], v[196:199], v[214:217], v[120:123]
	v_mfma_f32_16x16x32_bf16 v[112:115], v[206:209], v[214:217], v[112:115]
	v_mfma_f32_16x16x32_bf16 v[104:107], v[196:199], v[222:225], v[104:107]
	v_mfma_f32_16x16x32_bf16 v[96:99], v[206:209], v[222:225], v[96:99]
	v_mfma_f32_16x16x32_bf16 v[88:91], v[196:199], v[230:233], v[88:91]
	v_mfma_f32_16x16x32_bf16 v[80:83], v[206:209], v[230:233], v[80:83]
	v_mfma_f32_16x16x32_bf16 v[72:75], v[196:199], v[238:241], v[72:75]
	v_mfma_f32_16x16x32_bf16 v[64:67], v[206:209], v[238:241], v[64:67]
	v_mfma_f32_16x16x32_bf16 v[120:123], v[202:205], v[218:221], v[120:123]
	v_mfma_f32_16x16x32_bf16 v[112:115], v[210:213], v[218:221], v[112:115]
	v_mfma_f32_16x16x32_bf16 v[104:107], v[202:205], v[226:229], v[104:107]
	v_mfma_f32_16x16x32_bf16 v[96:99], v[210:213], v[226:229], v[96:99]
	v_mfma_f32_16x16x32_bf16 v[88:91], v[202:205], v[234:237], v[88:91]
	v_mfma_f32_16x16x32_bf16 v[80:83], v[210:213], v[234:237], v[80:83]
	v_mfma_f32_16x16x32_bf16 v[72:75], v[202:205], v[242:245], v[72:75]
	v_mfma_f32_16x16x32_bf16 v[64:67], v[210:213], v[242:245], v[64:67]
	s_barrier
	ds_read_b128 v[214:217], v179 offset:16384
	ds_read_b128 v[218:221], v179 offset:17408
	ds_read_b128 v[222:225], v179 offset:18432
	ds_read_b128 v[226:229], v179 offset:19456
	ds_read_b128 v[230:233], v179 offset:20480
	ds_read_b128 v[234:237], v179 offset:21504
	ds_read_b128 v[238:241], v179 offset:22528
	ds_read_b128 v[242:245], v179 offset:23552
	s_mov_b32 m0, s45
	s_nop 0
	global_load_lds_dwordx4 v175, s[38:39]
	s_add_u32 s72, s38, 0x80000
	s_mov_b32 m0, s46
	s_nop 0
	global_load_lds_dwordx4 v176, s[38:39]
	s_addc_u32 s73, s39, 0
	s_mov_b32 m0, s47
	s_nop 0
	global_load_lds_dwordx4 v175, s[72:73]
	s_nop 0
	s_mov_b32 m0, s48
	s_nop 0
	global_load_lds_dwordx4 v176, s[72:73]
	s_nop 0
	s_mov_b32 m0, s31
	s_nop 0
	global_load_lds_dwordx4 v161, s[40:41]
	s_nop 0
	s_mov_b32 m0, s49
	s_nop 0
	global_load_lds_dwordx4 v163, s[40:41]
	s_waitcnt vmcnt(8)
	s_waitcnt lgkmcnt(0)
	s_barrier
; #define PG8_STAGE(bufoff, gbase, voff) do { const unsigned long long gb_ = (unsigned long long)(gbase); _Pragma("unroll") for (int _i = 0; _i < 2; ++_i) { unsigned keep_; \
;         asm volatile("s_mov_b32 m0, %2\n\ts_nop 0\n\tglobal_load_lds_dwordx4 %0, %1" : : "v"((voff)[_i]), "s"(gb_), "s"((unsigned)(size_t)(lds + (bufoff) + ldsw + _i * 8192)) : "memory", "m0"); (void)keep_; } } while (0)
; #define PG8_LDA(dst, b, h) do { _Pragma("unroll") for (int m = 0; m < 4; ++m) _Pragma("unroll") for (int k = 0; k < 2; ++k) dst[m][k] = *(const PG8_LAS bf16x8*)(lds + PG8_SA(b, h) + aoff + m * 2048 + k * 1024); } while (0)
; #define PG8_LDB(dst, b, h) do { _Pragma("unroll") for (int n = 0; n < 2; ++n) _Pragma("unroll") for (int k = 0; k < 2; ++k) dst[n][k] = *(const PG8_LAS bf16x8*)(lds + PG8_SB(b, h) + boff + n * 2048 + k * 1024); } while (0)
; #define PG8_MMA(ai, bj, At, Bt) do { __builtin_amdgcn_s_setprio(1); _Pragma("unroll") for (int m = 0; m < 4; ++m) _Pragma("unroll") for (int n = 0; n < 2; ++n) _Pragma("unroll") for (int k = 0; k < 2; ++k) \
;         acc[ai][bj][m][n] = __builtin_amdgcn_mfma_f32_16x16x32_bf16(Bt[n][k], At[m][k], acc[ai][bj][m][n], 0, 0, 0); __builtin_amdgcn_s_setprio(0); } while (0)
; #define PG8_WAIT_V(n) asm volatile("s_waitcnt vmcnt(" #n ")" ::: "memory")
; #define PG8_WAIT_L(n) asm volatile("s_waitcnt lgkmcnt(" #n ")" ::: "memory")
; #define PG8_BAR __builtin_amdgcn_s_barrier()
; #define PG8_SCHED __builtin_amdgcn_sched_barrier(0)
; template <class Epi, class Sched, bool ALIGN_EPI = false, bool SP2 = false>
; __device__ __forceinline__ void gemm_phase(PG8_LAS unsigned char* lds, const Gemm g, const Sched& S, const Epi& E) {
;     ...
;             PG8_WAIT_V(8); PG8_WAIT_L(0); PG8_BAR; PG8_MMA(1, 0, At, B0); PG8_MMA(1, 1, At, B1); PG8_BAR; PG8_SCHED;
;             PG8_LDB(B0, 1, 0); PG8_LDB(B1, 1, 1); PG8_SCHED; PG8_LDA(At, 1, 0); PG8_STAGE(PG8_SA(0, 1), a2 + hstepA, voffA);
;             PG8_WAIT_V(8); PG8_WAIT_L(0); PG8_BAR; PG8_MMA(0, 0, At, B0); PG8_MMA(0, 1, At, B1); PG8_BAR; PG8_SCHED;
	v_mfma_f32_16x16x32_bf16 v[60:63], v[156:159], v[214:217], v[60:63]
	v_mfma_f32_16x16x32_bf16 v[52:55], v[188:191], v[214:217], v[52:55]
	v_mfma_f32_16x16x32_bf16 v[44:47], v[156:159], v[222:225], v[44:47]
	v_mfma_f32_16x16x32_bf16 v[36:39], v[188:191], v[222:225], v[36:39]
	v_mfma_f32_16x16x32_bf16 v[28:31], v[156:159], v[230:233], v[28:31]
	v_mfma_f32_16x16x32_bf16 v[20:23], v[188:191], v[230:233], v[20:23]
	v_mfma_f32_16x16x32_bf16 v[12:15], v[156:159], v[238:241], v[12:15]
	v_mfma_f32_16x16x32_bf16 v[4:7], v[188:191], v[238:241], v[4:7]
	v_mfma_f32_16x16x32_bf16 v[60:63], v[184:187], v[218:221], v[60:63]
	v_mfma_f32_16x16x32_bf16 v[52:55], v[192:195], v[218:221], v[52:55]
	v_mfma_f32_16x16x32_bf16 v[44:47], v[184:187], v[226:229], v[44:47]
	v_mfma_f32_16x16x32_bf16 v[36:39], v[192:195], v[226:229], v[36:39]
	v_mfma_f32_16x16x32_bf16 v[28:31], v[184:187], v[234:237], v[28:31]
	v_mfma_f32_16x16x32_bf16 v[20:23], v[192:195], v[234:237], v[20:23]
	v_mfma_f32_16x16x32_bf16 v[12:15], v[184:187], v[242:245], v[12:15]
	v_mfma_f32_16x16x32_bf16 v[4:7], v[192:195], v[242:245], v[4:7]
	v_mfma_f32_16x16x32_bf16 v[56:59], v[196:199], v[214:217], v[56:59]
	v_mfma_f32_16x16x32_bf16 v[48:51], v[206:209], v[214:217], v[48:51]
	v_mfma_f32_16x16x32_bf16 v[40:43], v[196:199], v[222:225], v[40:43]
	v_mfma_f32_16x16x32_bf16 v[32:35], v[206:209], v[222:225], v[32:35]
	v_mfma_f32_16x16x32_bf16 v[24:27], v[196:199], v[230:233], v[24:27]
	v_mfma_f32_16x16x32_bf16 v[16:19], v[206:209], v[230:233], v[16:19]
	v_mfma_f32_16x16x32_bf16 v[8:11], v[196:199], v[238:241], v[8:11]
	v_mfma_f32_16x16x32_bf16 v[0:3], v[206:209], v[238:241], v[0:3]
	v_mfma_f32_16x16x32_bf16 v[56:59], v[202:205], v[218:221], v[56:59]
	v_mfma_f32_16x16x32_bf16 v[48:51], v[210:213], v[218:221], v[48:51]
	v_mfma_f32_16x16x32_bf16 v[40:43], v[202:205], v[226:229], v[40:43]
	v_mfma_f32_16x16x32_bf16 v[32:35], v[210:213], v[226:229], v[32:35]
	v_mfma_f32_16x16x32_bf16 v[24:27], v[202:205], v[234:237], v[24:27]
	v_mfma_f32_16x16x32_bf16 v[16:19], v[210:213], v[234:237], v[16:19]
	v_mfma_f32_16x16x32_bf16 v[8:11], v[202:205], v[242:245], v[8:11]
	v_mfma_f32_16x16x32_bf16 v[0:3], v[210:213], v[242:245], v[0:3]
	s_barrier
	ds_read_b128 v[156:159], v180
	ds_read_b128 v[184:187], v180 offset:1024
	ds_read_b128 v[188:191], v180 offset:2048
	ds_read_b128 v[192:195], v180 offset:3072
	ds_read_b128 v[196:199], v181
	ds_read_b128 v[202:205], v181 offset:1024
	ds_read_b128 v[206:209], v181 offset:2048
	ds_read_b128 v[210:213], v181 offset:3072
	ds_read_b128 v[214:217], v179 offset:32768
	ds_read_b128 v[218:221], v179 offset:33792
	ds_read_b128 v[222:225], v179 offset:34816
	ds_read_b128 v[226:229], v179 offset:35840
	ds_read_b128 v[230:233], v179 offset:36864
	ds_read_b128 v[234:237], v179 offset:37888
	ds_read_b128 v[238:241], v179 offset:38912
	ds_read_b128 v[242:245], v179 offset:39936
	s_add_u32 s40, s40, 0x10000
	s_addc_u32 s41, s41, 0
	s_mov_b32 m0, s50
	s_nop 0
	global_load_lds_dwordx4 v161, s[40:41]
	s_nop 0
	s_mov_b32 m0, s51
	s_nop 0
	global_load_lds_dwordx4 v163, s[40:41]
	s_waitcnt vmcnt(8)
	s_waitcnt lgkmcnt(0)
	s_barrier
	v_mfma_f32_16x16x32_bf16 v[124:127], v[156:159], v[214:217], v[124:127]
	v_mfma_f32_16x16x32_bf16 v[116:119], v[188:191], v[214:217], v[116:119]
	v_mfma_f32_16x16x32_bf16 v[108:111], v[156:159], v[222:225], v[108:111]
	v_mfma_f32_16x16x32_bf16 v[100:103], v[188:191], v[222:225], v[100:103]
	v_mfma_f32_16x16x32_bf16 v[92:95], v[156:159], v[230:233], v[92:95]
	v_mfma_f32_16x16x32_bf16 v[84:87], v[188:191], v[230:233], v[84:87]
	v_mfma_f32_16x16x32_bf16 v[76:79], v[156:159], v[238:241], v[76:79]
	v_mfma_f32_16x16x32_bf16 v[68:71], v[188:191], v[238:241], v[68:71]
	v_mfma_f32_16x16x32_bf16 v[124:127], v[184:187], v[218:221], v[124:127]
	v_mfma_f32_16x16x32_bf16 v[116:119], v[192:195], v[218:221], v[116:119]
	v_mfma_f32_16x16x32_bf16 v[108:111], v[184:187], v[226:229], v[108:111]
	v_mfma_f32_16x16x32_bf16 v[100:103], v[192:195], v[226:229], v[100:103]
	v_mfma_f32_16x16x32_bf16 v[92:95], v[184:187], v[234:237], v[92:95]
	v_mfma_f32_16x16x32_bf16 v[84:87], v[192:195], v[234:237], v[84:87]
	v_mfma_f32_16x16x32_bf16 v[76:79], v[184:187], v[242:245], v[76:79]
	v_mfma_f32_16x16x32_bf16 v[68:71], v[192:195], v[242:245], v[68:71]
	v_mfma_f32_16x16x32_bf16 v[120:123], v[196:199], v[214:217], v[120:123]
	v_mfma_f32_16x16x32_bf16 v[112:115], v[206:209], v[214:217], v[112:115]
	v_mfma_f32_16x16x32_bf16 v[104:107], v[196:199], v[222:225], v[104:107]
	v_mfma_f32_16x16x32_bf16 v[96:99], v[206:209], v[222:225], v[96:99]
	v_mfma_f32_16x16x32_bf16 v[88:91], v[196:199], v[230:233], v[88:91]
	v_mfma_f32_16x16x32_bf16 v[80:83], v[206:209], v[230:233], v[80:83]
	v_mfma_f32_16x16x32_bf16 v[72:75], v[196:199], v[238:241], v[72:75]
	v_mfma_f32_16x16x32_bf16 v[64:67], v[206:209], v[238:241], v[64:67]
	v_mfma_f32_16x16x32_bf16 v[120:123], v[202:205], v[218:221], v[120:123]
	v_mfma_f32_16x16x32_bf16 v[112:115], v[210:213], v[218:221], v[112:115]
	v_mfma_f32_16x16x32_bf16 v[104:107], v[202:205], v[226:229], v[104:107]
	v_mfma_f32_16x16x32_bf16 v[96:99], v[210:213], v[226:229], v[96:99]
	v_mfma_f32_16x16x32_bf16 v[88:91], v[202:205], v[234:237], v[88:91]
	v_mfma_f32_16x16x32_bf16 v[80:83], v[210:213], v[234:237], v[80:83]
	v_mfma_f32_16x16x32_bf16 v[72:75], v[202:205], v[242:245], v[72:75]
	v_mfma_f32_16x16x32_bf16 v[64:67], v[210:213], v[242:245], v[64:67]
	s_barrier
; #define PG8_STAGE(bufoff, gbase, voff) do { const unsigned long long gb_ = (unsigned long long)(gbase); _Pragma("unroll") for (int _i = 0; _i < 2; ++_i) { unsigned keep_; \
;         asm volatile("s_mov_b32 m0, %2\n\ts_nop 0\n\tglobal_load_lds_dwordx4 %0, %1" : : "v"((voff)[_i]), "s"(gb_), "s"((unsigned)(size_t)(lds + (bufoff) + ldsw + _i * 8192)) : "memory", "m0"); (void)keep_; } } while (0)
; #define PG8_LDA(dst, b, h) do { _Pragma("unroll") for (int m = 0; m < 4; ++m) _Pragma("unroll") for (int k = 0; k < 2; ++k) dst[m][k] = *(const PG8_LAS bf16x8*)(lds + PG8_SA(b, h) + aoff + m * 2048 + k * 1024); } while (0)
; #define PG8_MMA(ai, bj, At, Bt) do { __builtin_amdgcn_s_setprio(1); _Pragma("unroll") for (int m = 0; m < 4; ++m) _Pragma("unroll") for (int n = 0; n < 2; ++n) _Pragma("unroll") for (int k = 0; k < 2; ++k) \
;         acc[ai][bj][m][n] = __builtin_amdgcn_mfma_f32_16x16x32_bf16(Bt[n][k], At[m][k], acc[ai][bj][m][n], 0, 0, 0); __builtin_amdgcn_s_setprio(0); } while (0)
; #define PG8_WAIT_V(n) asm volatile("s_waitcnt vmcnt(" #n ")" ::: "memory")
; #define PG8_WAIT_L(n) asm volatile("s_waitcnt lgkmcnt(" #n ")" ::: "memory")
; #define PG8_BAR __builtin_amdgcn_s_barrier()
; #define PG8_SCHED __builtin_amdgcn_sched_barrier(0)
; template <class Epi, class Sched, bool ALIGN_EPI = false, bool SP2 = false>
; __device__ __forceinline__ void gemm_phase(PG8_LAS unsigned char* lds, const Gemm g, const Sched& S, const Epi& E) {
;     ...
;             PG8_LDA(At, 1, 1); PG8_STAGE(PG8_SB(1, 0), b3, voffB); PG8_STAGE(PG8_SB(1, 1), b3 + hstepB, voffB); PG8_STAGE(PG8_SA(1, 0), a3, voffA);
;             PG8_WAIT_V(8); PG8_WAIT_L(0); PG8_BAR; PG8_MMA(1, 0, At, B0); PG8_MMA(1, 1, At, B1); PG8_BAR; PG8_SCHED;
	ds_read_b128 v[214:217], v179 offset:49152
	ds_read_b128 v[218:221], v179 offset:50176
	ds_read_b128 v[222:225], v179 offset:51200
	ds_read_b128 v[226:229], v179 offset:52224
	ds_read_b128 v[230:233], v179 offset:53248
	ds_read_b128 v[234:237], v179 offset:54272
	ds_read_b128 v[238:241], v179 offset:55296
	ds_read_b128 v[242:245], v179 offset:56320
	s_add_u32 s40, s38, 0x80
	s_addc_u32 s41, s39, 0
	s_mov_b32 m0, s55
	s_nop 0
	global_load_lds_dwordx4 v175, s[40:41]
	s_add_u32 s38, s38, 0x80080
	s_mov_b32 m0, s56
	s_nop 0
	global_load_lds_dwordx4 v176, s[40:41]
	s_addc_u32 s39, s39, 0
	s_mov_b32 m0, s59
	s_nop 0
	global_load_lds_dwordx4 v175, s[38:39]
	s_nop 0
	s_mov_b32 m0, s60
	s_nop 0
	global_load_lds_dwordx4 v176, s[38:39]
	s_nop 0
	s_mov_b32 m0, s57
	s_nop 0
	global_load_lds_dwordx4 v161, s[34:35]
	s_nop 0
	s_mov_b32 m0, s58
	s_nop 0
	global_load_lds_dwordx4 v163, s[34:35]
	s_waitcnt vmcnt(8)
	s_waitcnt lgkmcnt(0)
	s_barrier
	v_mfma_f32_16x16x32_bf16 v[60:63], v[156:159], v[214:217], v[60:63]
	v_mfma_f32_16x16x32_bf16 v[52:55], v[188:191], v[214:217], v[52:55]
	v_mfma_f32_16x16x32_bf16 v[44:47], v[156:159], v[222:225], v[44:47]
	v_mfma_f32_16x16x32_bf16 v[36:39], v[188:191], v[222:225], v[36:39]
	v_mfma_f32_16x16x32_bf16 v[28:31], v[156:159], v[230:233], v[28:31]
	v_mfma_f32_16x16x32_bf16 v[20:23], v[188:191], v[230:233], v[20:23]
	v_mfma_f32_16x16x32_bf16 v[12:15], v[156:159], v[238:241], v[12:15]
	v_mfma_f32_16x16x32_bf16 v[4:7], v[188:191], v[238:241], v[4:7]
	v_mfma_f32_16x16x32_bf16 v[60:63], v[184:187], v[218:221], v[60:63]
	v_mfma_f32_16x16x32_bf16 v[52:55], v[192:195], v[218:221], v[52:55]
	v_mfma_f32_16x16x32_bf16 v[44:47], v[184:187], v[226:229], v[44:47]
	v_mfma_f32_16x16x32_bf16 v[36:39], v[192:195], v[226:229], v[36:39]
	v_mfma_f32_16x16x32_bf16 v[28:31], v[184:187], v[234:237], v[28:31]
	v_mfma_f32_16x16x32_bf16 v[20:23], v[192:195], v[234:237], v[20:23]
	v_mfma_f32_16x16x32_bf16 v[12:15], v[184:187], v[242:245], v[12:15]
	v_mfma_f32_16x16x32_bf16 v[4:7], v[192:195], v[242:245], v[4:7]
	v_mfma_f32_16x16x32_bf16 v[56:59], v[196:199], v[214:217], v[56:59]
	v_mfma_f32_16x16x32_bf16 v[48:51], v[206:209], v[214:217], v[48:51]
	v_mfma_f32_16x16x32_bf16 v[40:43], v[196:199], v[222:225], v[40:43]
	v_mfma_f32_16x16x32_bf16 v[32:35], v[206:209], v[222:225], v[32:35]
	v_mfma_f32_16x16x32_bf16 v[24:27], v[196:199], v[230:233], v[24:27]
	v_mfma_f32_16x16x32_bf16 v[16:19], v[206:209], v[230:233], v[16:19]
	v_mfma_f32_16x16x32_bf16 v[8:11], v[196:199], v[238:241], v[8:11]
	v_mfma_f32_16x16x32_bf16 v[0:3], v[206:209], v[238:241], v[0:3]
	v_mfma_f32_16x16x32_bf16 v[56:59], v[202:205], v[218:221], v[56:59]
	v_mfma_f32_16x16x32_bf16 v[48:51], v[210:213], v[218:221], v[48:51]
	v_mfma_f32_16x16x32_bf16 v[40:43], v[202:205], v[226:229], v[40:43]
	v_mfma_f32_16x16x32_bf16 v[32:35], v[210:213], v[226:229], v[32:35]
	v_mfma_f32_16x16x32_bf16 v[24:27], v[202:205], v[234:237], v[24:27]
	v_mfma_f32_16x16x32_bf16 v[16:19], v[210:213], v[234:237], v[16:19]
	v_mfma_f32_16x16x32_bf16 v[8:11], v[202:205], v[242:245], v[8:11]
	v_mfma_f32_16x16x32_bf16 v[0:3], v[210:213], v[242:245], v[0:3]
	s_barrier
	s_add_i32 s70, s70, 2
	s_add_i32 s71, s71, 0x10000
	s_cmp_gt_u32 s70, 29
	s_mov_b64 s[34:35], s[36:37]
	s_cbranch_scc0 .LBB0_953
	s_and_b64 vcc, exec, s[18:19]
	s_cbranch_vccz .LBB0_956
	s_barrier

; #define PG8_STAGE(bufoff, gbase, voff) do { const unsigned long long gb_ = (unsigned long long)(gbase); _Pragma("unroll") for (int _i = 0; _i < 2; ++_i) { unsigned keep_; \
;         asm volatile("s_mov_b32 m0, %2\n\ts_nop 0\n\tglobal_load_lds_dwordx4 %0, %1" : : "v"((voff)[_i]), "s"(gb_), "s"((unsigned)(size_t)(lds + (bufoff) + ldsw + _i * 8192)) : "memory", "m0"); (void)keep_; } } while (0)
; #define PG8_LDA(dst, b, h) do { _Pragma("unroll") for (int m = 0; m < 4; ++m) _Pragma("unroll") for (int k = 0; k < 2; ++k) dst[m][k] = *(const PG8_LAS bf16x8*)(lds + PG8_SA(b, h) + aoff + m * 2048 + k * 1024); } while (0)
; #define PG8_WAIT_V(n) asm volatile("s_waitcnt vmcnt(" #n ")" ::: "memory")
; template <class Epi, class Sched, bool ALIGN_EPI = false, bool SP2 = false>
; __device__ __forceinline__ void gemm_phase(PG8_LAS unsigned char* lds, const Gemm g, const Sched& S, const Epi& E) {
;     ...
;         for (int t = 0; t < nt; t += 2) {
;             const bool last = (t == nt - 2);
;     ...
;             const char* a1 = cA + PG8_KOFFA(t + 1);
;             const char* a2 = last ? nA : cA + PG8_KOFFA(t + 2); const char* b2 = last ? nB : cB + (size_t)(t + 2) * kstep;
;             const char* a3 = last ? nA + kstep : cA + PG8_KOFFA(t + 3); const char* b3 = b2 + kstep;
;     ...
;             if (last && has_next) S.a_ready(nxt);
;             if constexpr (SP2) {
;             PG8_LDB(B0, 0, 0); PG8_LDB(B1, 0, 1); PG8_SCHED; PG8_LDA(At, 0, 0); PG8_STAGE(PG8_SA(1, 1), a1 + hstepA, voffA);
;             PG8_WAIT_V(8); PG8_WAIT_L(0); PG8_BAR; PG8_MMA(0, 0, At, B0); PG8_MMA(0, 1, At, B1); PG8_BAR; PG8_SCHED;
;             PG8_LDA(At, 0, 1); PG8_STAGE(PG8_SB(0, 0), b2, voffB); PG8_STAGE(PG8_SB(0, 1), b2 + hstepB, voffB); PG8_STAGE(PG8_SA(0, 0), a2, voffA);
;             PG8_WAIT_V(8); PG8_WAIT_L(0); PG8_BAR; PG8_MMA(1, 0, At, B0); PG8_MMA(1, 1, At, B1); PG8_BAR; PG8_SCHED;
;             PG8_LDB(B0, 1, 0); PG8_LDB(B1, 1, 1); PG8_SCHED; PG8_LDA(At, 1, 0); PG8_STAGE(PG8_SA(0, 1), a2 + hstepA, voffA);
;             PG8_WAIT_V(8); PG8_WAIT_L(0); PG8_BAR; PG8_MMA(0, 0, At, B0); PG8_MMA(0, 1, At, B1); PG8_BAR; PG8_SCHED;
;             PG8_LDA(At, 1, 1); PG8_STAGE(PG8_SB(1, 0), b3, voffB); PG8_STAGE(PG8_SB(1, 1), b3 + hstepB, voffB); PG8_STAGE(PG8_SA(1, 0), a3, voffA);
;             PG8_WAIT_V(8); PG8_WAIT_L(0); PG8_BAR; PG8_MMA(1, 0, At, B0); PG8_MMA(1, 1, At, B1); PG8_BAR; PG8_SCHED;
.LBB0_1009:
	s_add_u32 s52, s38, s44
	s_addc_u32 s53, s39, 0
	s_add_u32 s45, s52, 0x100
	s_addc_u32 s48, s53, 0
	s_and_b64 s[46:47], s[42:43], exec
	s_cselect_b32 s49, s0, s48
	s_cselect_b32 s48, s1, s45
	s_add_u32 s44, s36, s44
	s_addc_u32 s45, s37, 0
	s_add_u32 s46, s44, 0x100
	s_addc_u32 s47, s45, 0
	s_and_b64 s[44:45], s[42:43], exec
	s_cselect_b32 s51, s25, s47
	s_cselect_b32 s50, s27, s46
	s_add_u32 s44, s52, 0x180
	s_addc_u32 s45, s53, 0
	ds_read_b128 v[142:145], v136
	ds_read_b128 v[146:149], v136 offset:1024
	ds_read_b128 v[150:153], v136 offset:2048
	ds_read_b128 v[154:157], v136 offset:3072
	ds_read_b128 v[164:167], v137
	ds_read_b128 v[168:171], v137 offset:1024
	ds_read_b128 v[172:175], v137 offset:2048
	ds_read_b128 v[176:179], v137 offset:3072
	s_and_b64 s[42:43], s[42:43], exec
	s_cselect_b32 s42, s85, s44
	s_cselect_b32 s43, s90, s45
	s_add_u32 s56, s52, 0x10080
	s_addc_u32 s57, s53, 0
	s_add_u32 s52, s50, 0x10000
	s_addc_u32 s53, s51, 0
	s_add_u32 s46, s48, 0x10000
	s_addc_u32 s47, s49, 0
	s_add_u32 s44, s50, 0x80
	s_addc_u32 s45, s51, 0
	s_add_u32 s54, s50, 0x10080
	s_addc_u32 s55, s51, 0
	ds_read_b128 v[180:183], v138
	ds_read_b128 v[184:187], v138 offset:1024
	ds_read_b128 v[188:191], v138 offset:2048
	ds_read_b128 v[192:195], v138 offset:3072
	ds_read_b128 v[196:199], v138 offset:4096
	ds_read_b128 v[202:205], v138 offset:5120
	ds_read_b128 v[206:209], v138 offset:6144
	ds_read_b128 v[210:213], v138 offset:7168
	s_mov_b32 m0, s77
	s_nop 0
	global_load_lds_dwordx4 v161, s[56:57]
	s_nop 0
	s_mov_b32 m0, s78
	s_nop 0
	global_load_lds_dwordx4 v163, s[56:57]
	s_waitcnt vmcnt(8)
	s_waitcnt lgkmcnt(0)
	s_barrier
	v_mfma_f32_16x16x32_bf16 v[124:127], v[142:145], v[180:183], v[124:127]
	v_mfma_f32_16x16x32_bf16 v[120:123], v[150:153], v[180:183], v[120:123]
	v_mfma_f32_16x16x32_bf16 v[112:115], v[142:145], v[188:191], v[112:115]
	v_mfma_f32_16x16x32_bf16 v[104:107], v[150:153], v[188:191], v[104:107]
	v_mfma_f32_16x16x32_bf16 v[96:99], v[142:145], v[196:199], v[96:99]
	v_mfma_f32_16x16x32_bf16 v[88:91], v[150:153], v[196:199], v[88:91]
	v_mfma_f32_16x16x32_bf16 v[80:83], v[142:145], v[206:209], v[80:83]
	v_mfma_f32_16x16x32_bf16 v[72:75], v[150:153], v[206:209], v[72:75]
	v_mfma_f32_16x16x32_bf16 v[124:127], v[146:149], v[184:187], v[124:127]
	v_mfma_f32_16x16x32_bf16 v[120:123], v[154:157], v[184:187], v[120:123]
	v_mfma_f32_16x16x32_bf16 v[112:115], v[146:149], v[192:195], v[112:115]
	v_mfma_f32_16x16x32_bf16 v[104:107], v[154:157], v[192:195], v[104:107]
	v_mfma_f32_16x16x32_bf16 v[96:99], v[146:149], v[202:205], v[96:99]
	v_mfma_f32_16x16x32_bf16 v[88:91], v[154:157], v[202:205], v[88:91]
	v_mfma_f32_16x16x32_bf16 v[80:83], v[146:149], v[210:213], v[80:83]
	v_mfma_f32_16x16x32_bf16 v[72:75], v[154:157], v[210:213], v[72:75]
	v_mfma_f32_16x16x32_bf16 v[116:119], v[164:167], v[180:183], v[116:119]
	v_mfma_f32_16x16x32_bf16 v[108:111], v[172:175], v[180:183], v[108:111]
	v_mfma_f32_16x16x32_bf16 v[100:103], v[164:167], v[188:191], v[100:103]
	v_mfma_f32_16x16x32_bf16 v[92:95], v[172:175], v[188:191], v[92:95]
	v_mfma_f32_16x16x32_bf16 v[84:87], v[164:167], v[196:199], v[84:87]
	v_mfma_f32_16x16x32_bf16 v[76:79], v[172:175], v[196:199], v[76:79]
	v_mfma_f32_16x16x32_bf16 v[68:71], v[164:167], v[206:209], v[68:71]
	v_mfma_f32_16x16x32_bf16 v[64:67], v[172:175], v[206:209], v[64:67]
	v_mfma_f32_16x16x32_bf16 v[116:119], v[168:171], v[184:187], v[116:119]
	v_mfma_f32_16x16x32_bf16 v[108:111], v[176:179], v[184:187], v[108:111]
	v_mfma_f32_16x16x32_bf16 v[100:103], v[168:171], v[192:195], v[100:103]
	v_mfma_f32_16x16x32_bf16 v[92:95], v[176:179], v[192:195], v[92:95]
	v_mfma_f32_16x16x32_bf16 v[84:87], v[168:171], v[202:205], v[84:87]
	v_mfma_f32_16x16x32_bf16 v[76:79], v[176:179], v[202:205], v[76:79]
	v_mfma_f32_16x16x32_bf16 v[68:71], v[168:171], v[210:213], v[68:71]
	v_mfma_f32_16x16x32_bf16 v[64:67], v[176:179], v[210:213], v[64:67]
	s_barrier
	ds_read_b128 v[180:183], v138 offset:16384
	ds_read_b128 v[184:187], v138 offset:17408
	ds_read_b128 v[188:191], v138 offset:18432
	ds_read_b128 v[192:195], v138 offset:19456
	ds_read_b128 v[196:199], v138 offset:20480
	ds_read_b128 v[202:205], v138 offset:21504
	ds_read_b128 v[206:209], v138 offset:22528
	ds_read_b128 v[210:213], v138 offset:23552
	s_mov_b32 m0, s62
	s_nop 0
	global_load_lds_dwordx4 v132, s[50:51]
	s_nop 0
	s_mov_b32 m0, s63
	s_nop 0
	global_load_lds_dwordx4 v133, s[50:51]
	s_nop 0
	s_mov_b32 m0, s64
	s_nop 0
	global_load_lds_dwordx4 v132, s[52:53]
	s_nop 0
	s_mov_b32 m0, s65
	s_nop 0
	global_load_lds_dwordx4 v133, s[52:53]
	s_nop 0
	s_mov_b32 m0, s61
	s_nop 0
	global_load_lds_dwordx4 v161, s[48:49]
	s_nop 0
	s_mov_b32 m0, s66
	s_nop 0
	global_load_lds_dwordx4 v163, s[48:49]
	s_waitcnt vmcnt(8)
	s_waitcnt lgkmcnt(0)
	s_barrier
; #define PG8_STAGE(bufoff, gbase, voff) do { const unsigned long long gb_ = (unsigned long long)(gbase); _Pragma("unroll") for (int _i = 0; _i < 2; ++_i) { unsigned keep_; \
;         asm volatile("s_mov_b32 m0, %2\n\ts_nop 0\n\tglobal_load_lds_dwordx4 %0, %1" : : "v"((voff)[_i]), "s"(gb_), "s"((unsigned)(size_t)(lds + (bufoff) + ldsw + _i * 8192)) : "memory", "m0"); (void)keep_; } } while (0)
; #define PG8_LDA(dst, b, h) do { _Pragma("unroll") for (int m = 0; m < 4; ++m) _Pragma("unroll") for (int k = 0; k < 2; ++k) dst[m][k] = *(const PG8_LAS bf16x8*)(lds + PG8_SA(b, h) + aoff + m * 2048 + k * 1024); } while (0)
; #define PG8_LDB(dst, b, h) do { _Pragma("unroll") for (int n = 0; n < 2; ++n) _Pragma("unroll") for (int k = 0; k < 2; ++k) dst[n][k] = *(const PG8_LAS bf16x8*)(lds + PG8_SB(b, h) + boff + n * 2048 + k * 1024); } while (0)
; #define PG8_MMA(ai, bj, At, Bt) do { __builtin_amdgcn_s_setprio(1); _Pragma("unroll") for (int m = 0; m < 4; ++m) _Pragma("unroll") for (int n = 0; n < 2; ++n) _Pragma("unroll") for (int k = 0; k < 2; ++k) \
;         acc[ai][bj][m][n] = __builtin_amdgcn_mfma_f32_16x16x32_bf16(Bt[n][k], At[m][k], acc[ai][bj][m][n], 0, 0, 0); __builtin_amdgcn_s_setprio(0); } while (0)
; #define PG8_WAIT_V(n) asm volatile("s_waitcnt vmcnt(" #n ")" ::: "memory")
; #define PG8_WAIT_L(n) asm volatile("s_waitcnt lgkmcnt(" #n ")" ::: "memory")
; #define PG8_BAR __builtin_amdgcn_s_barrier()
; #define PG8_SCHED __builtin_amdgcn_sched_barrier(0)
; template <class Epi, class Sched, bool ALIGN_EPI = false, bool SP2 = false>
; __device__ __forceinline__ void gemm_phase(PG8_LAS unsigned char* lds, const Gemm g, const Sched& S, const Epi& E) {
;     ...
;             PG8_WAIT_V(8); PG8_WAIT_L(0); PG8_BAR; PG8_MMA(1, 0, At, B0); PG8_MMA(1, 1, At, B1); PG8_BAR; PG8_SCHED;
;             PG8_LDB(B0, 1, 0); PG8_LDB(B1, 1, 1); PG8_SCHED; PG8_LDA(At, 1, 0); PG8_STAGE(PG8_SA(0, 1), a2 + hstepA, voffA);
;             PG8_WAIT_V(8); PG8_WAIT_L(0); PG8_BAR; PG8_MMA(0, 0, At, B0); PG8_MMA(0, 1, At, B1); PG8_BAR; PG8_SCHED;
;             PG8_LDA(At, 1, 1); PG8_STAGE(PG8_SB(1, 0), b3, voffB); PG8_STAGE(PG8_SB(1, 1), b3 + hstepB, voffB); PG8_STAGE(PG8_SA(1, 0), a3, voffA);
;             PG8_WAIT_V(8); PG8_WAIT_L(0); PG8_BAR; PG8_MMA(1, 0, At, B0); PG8_MMA(1, 1, At, B1); PG8_BAR; PG8_SCHED;
	v_mfma_f32_16x16x32_bf16 v[60:63], v[142:145], v[180:183], v[60:63]
	v_mfma_f32_16x16x32_bf16 v[56:59], v[150:153], v[180:183], v[56:59]
	v_mfma_f32_16x16x32_bf16 v[48:51], v[142:145], v[188:191], v[48:51]
	v_mfma_f32_16x16x32_bf16 v[40:43], v[150:153], v[188:191], v[40:43]
	v_mfma_f32_16x16x32_bf16 v[32:35], v[142:145], v[196:199], v[32:35]
	v_mfma_f32_16x16x32_bf16 v[24:27], v[150:153], v[196:199], v[24:27]
	v_mfma_f32_16x16x32_bf16 v[16:19], v[142:145], v[206:209], v[16:19]
	v_mfma_f32_16x16x32_bf16 v[8:11], v[150:153], v[206:209], v[8:11]
	v_mfma_f32_16x16x32_bf16 v[60:63], v[146:149], v[184:187], v[60:63]
	v_mfma_f32_16x16x32_bf16 v[56:59], v[154:157], v[184:187], v[56:59]
	v_mfma_f32_16x16x32_bf16 v[48:51], v[146:149], v[192:195], v[48:51]
	v_mfma_f32_16x16x32_bf16 v[40:43], v[154:157], v[192:195], v[40:43]
	v_mfma_f32_16x16x32_bf16 v[32:35], v[146:149], v[202:205], v[32:35]
	v_mfma_f32_16x16x32_bf16 v[24:27], v[154:157], v[202:205], v[24:27]
	v_mfma_f32_16x16x32_bf16 v[16:19], v[146:149], v[210:213], v[16:19]
	v_mfma_f32_16x16x32_bf16 v[8:11], v[154:157], v[210:213], v[8:11]
	v_mfma_f32_16x16x32_bf16 v[52:55], v[164:167], v[180:183], v[52:55]
	v_mfma_f32_16x16x32_bf16 v[44:47], v[172:175], v[180:183], v[44:47]
	v_mfma_f32_16x16x32_bf16 v[36:39], v[164:167], v[188:191], v[36:39]
	v_mfma_f32_16x16x32_bf16 v[28:31], v[172:175], v[188:191], v[28:31]
	v_mfma_f32_16x16x32_bf16 v[20:23], v[164:167], v[196:199], v[20:23]
	v_mfma_f32_16x16x32_bf16 v[12:15], v[172:175], v[196:199], v[12:15]
	v_mfma_f32_16x16x32_bf16 v[4:7], v[164:167], v[206:209], v[4:7]
	v_mfma_f32_16x16x32_bf16 v[0:3], v[172:175], v[206:209], v[0:3]
	v_mfma_f32_16x16x32_bf16 v[52:55], v[168:171], v[184:187], v[52:55]
	v_mfma_f32_16x16x32_bf16 v[44:47], v[176:179], v[184:187], v[44:47]
	v_mfma_f32_16x16x32_bf16 v[36:39], v[168:171], v[192:195], v[36:39]
	v_mfma_f32_16x16x32_bf16 v[28:31], v[176:179], v[192:195], v[28:31]
	v_mfma_f32_16x16x32_bf16 v[20:23], v[168:171], v[202:205], v[20:23]
	v_mfma_f32_16x16x32_bf16 v[12:15], v[176:179], v[202:205], v[12:15]
	v_mfma_f32_16x16x32_bf16 v[4:7], v[168:171], v[210:213], v[4:7]
	v_mfma_f32_16x16x32_bf16 v[0:3], v[176:179], v[210:213], v[0:3]
	s_barrier
	ds_read_b128 v[142:145], v139
	ds_read_b128 v[146:149], v139 offset:1024
	ds_read_b128 v[150:153], v139 offset:2048
	ds_read_b128 v[154:157], v139 offset:3072
	ds_read_b128 v[164:167], v140
	ds_read_b128 v[168:171], v140 offset:1024
	ds_read_b128 v[172:175], v140 offset:2048
	ds_read_b128 v[176:179], v140 offset:3072
	ds_read_b128 v[180:183], v138 offset:32768
	ds_read_b128 v[184:187], v138 offset:33792
	ds_read_b128 v[188:191], v138 offset:34816
	ds_read_b128 v[192:195], v138 offset:35840
	ds_read_b128 v[196:199], v138 offset:36864
	ds_read_b128 v[202:205], v138 offset:37888
	ds_read_b128 v[206:209], v138 offset:38912
	ds_read_b128 v[210:213], v138 offset:39936
	s_mov_b32 m0, s67
	s_nop 0
	global_load_lds_dwordx4 v161, s[46:47]
	s_nop 0
	s_mov_b32 m0, s68
	s_nop 0
	global_load_lds_dwordx4 v163, s[46:47]
	s_waitcnt vmcnt(8)
	s_waitcnt lgkmcnt(0)
	s_barrier
	v_mfma_f32_16x16x32_bf16 v[124:127], v[142:145], v[180:183], v[124:127]
	v_mfma_f32_16x16x32_bf16 v[120:123], v[150:153], v[180:183], v[120:123]
	v_mfma_f32_16x16x32_bf16 v[112:115], v[142:145], v[188:191], v[112:115]
	v_mfma_f32_16x16x32_bf16 v[104:107], v[150:153], v[188:191], v[104:107]
	v_mfma_f32_16x16x32_bf16 v[96:99], v[142:145], v[196:199], v[96:99]
	v_mfma_f32_16x16x32_bf16 v[88:91], v[150:153], v[196:199], v[88:91]
	v_mfma_f32_16x16x32_bf16 v[80:83], v[142:145], v[206:209], v[80:83]
	v_mfma_f32_16x16x32_bf16 v[72:75], v[150:153], v[206:209], v[72:75]
	v_mfma_f32_16x16x32_bf16 v[124:127], v[146:149], v[184:187], v[124:127]
	v_mfma_f32_16x16x32_bf16 v[120:123], v[154:157], v[184:187], v[120:123]
	v_mfma_f32_16x16x32_bf16 v[112:115], v[146:149], v[192:195], v[112:115]
	v_mfma_f32_16x16x32_bf16 v[104:107], v[154:157], v[192:195], v[104:107]
	v_mfma_f32_16x16x32_bf16 v[96:99], v[146:149], v[202:205], v[96:99]
	v_mfma_f32_16x16x32_bf16 v[88:91], v[154:157], v[202:205], v[88:91]
	v_mfma_f32_16x16x32_bf16 v[80:83], v[146:149], v[210:213], v[80:83]
	v_mfma_f32_16x16x32_bf16 v[72:75], v[154:157], v[210:213], v[72:75]
	v_mfma_f32_16x16x32_bf16 v[116:119], v[164:167], v[180:183], v[116:119]
	v_mfma_f32_16x16x32_bf16 v[108:111], v[172:175], v[180:183], v[108:111]
	v_mfma_f32_16x16x32_bf16 v[100:103], v[164:167], v[188:191], v[100:103]
	v_mfma_f32_16x16x32_bf16 v[92:95], v[172:175], v[188:191], v[92:95]
	v_mfma_f32_16x16x32_bf16 v[84:87], v[164:167], v[196:199], v[84:87]
	v_mfma_f32_16x16x32_bf16 v[76:79], v[172:175], v[196:199], v[76:79]
	v_mfma_f32_16x16x32_bf16 v[68:71], v[164:167], v[206:209], v[68:71]
	v_mfma_f32_16x16x32_bf16 v[64:67], v[172:175], v[206:209], v[64:67]
	v_mfma_f32_16x16x32_bf16 v[116:119], v[168:171], v[184:187], v[116:119]
	v_mfma_f32_16x16x32_bf16 v[108:111], v[176:179], v[184:187], v[108:111]
	v_mfma_f32_16x16x32_bf16 v[100:103], v[168:171], v[192:195], v[100:103]
	v_mfma_f32_16x16x32_bf16 v[92:95], v[176:179], v[192:195], v[92:95]
	v_mfma_f32_16x16x32_bf16 v[84:87], v[168:171], v[202:205], v[84:87]
	v_mfma_f32_16x16x32_bf16 v[76:79], v[176:179], v[202:205], v[76:79]
	v_mfma_f32_16x16x32_bf16 v[68:71], v[168:171], v[210:213], v[68:71]
	v_mfma_f32_16x16x32_bf16 v[64:67], v[176:179], v[210:213], v[64:67]
	s_barrier
; #define PG8_STAGE(bufoff, gbase, voff) do { const unsigned long long gb_ = (unsigned long long)(gbase); _Pragma("unroll") for (int _i = 0; _i < 2; ++_i) { unsigned keep_; \
;         asm volatile("s_mov_b32 m0, %2\n\ts_nop 0\n\tglobal_load_lds_dwordx4 %0, %1" : : "v"((voff)[_i]), "s"(gb_), "s"((unsigned)(size_t)(lds + (bufoff) + ldsw + _i * 8192)) : "memory", "m0"); (void)keep_; } } while (0)
; #define PG8_LDA(dst, b, h) do { _Pragma("unroll") for (int m = 0; m < 4; ++m) _Pragma("unroll") for (int k = 0; k < 2; ++k) dst[m][k] = *(const PG8_LAS bf16x8*)(lds + PG8_SA(b, h) + aoff + m * 2048 + k * 1024); } while (0)
; #define PG8_MMA(ai, bj, At, Bt) do { __builtin_amdgcn_s_setprio(1); _Pragma("unroll") for (int m = 0; m < 4; ++m) _Pragma("unroll") for (int n = 0; n < 2; ++n) _Pragma("unroll") for (int k = 0; k < 2; ++k) \
;         acc[ai][bj][m][n] = __builtin_amdgcn_mfma_f32_16x16x32_bf16(Bt[n][k], At[m][k], acc[ai][bj][m][n], 0, 0, 0); __builtin_amdgcn_s_setprio(0); } while (0)
; #define PG8_WAIT_V(n) asm volatile("s_waitcnt vmcnt(" #n ")" ::: "memory")
; #define PG8_WAIT_L(n) asm volatile("s_waitcnt lgkmcnt(" #n ")" ::: "memory")
; #define PG8_BAR __builtin_amdgcn_s_barrier()
; #define PG8_SCHED __builtin_amdgcn_sched_barrier(0)
; template <class Epi, class Sched, bool ALIGN_EPI = false, bool SP2 = false>
; __device__ __forceinline__ void gemm_phase(PG8_LAS unsigned char* lds, const Gemm g, const Sched& S, const Epi& E) {
;     ...
;         for (int t = 0; t < nt; t += 2) {
;     ...
;             PG8_LDA(At, 1, 1); PG8_STAGE(PG8_SB(1, 0), b3, voffB); PG8_STAGE(PG8_SB(1, 1), b3 + hstepB, voffB); PG8_STAGE(PG8_SA(1, 0), a3, voffA);
;             PG8_WAIT_V(8); PG8_WAIT_L(0); PG8_BAR; PG8_MMA(1, 0, At, B0); PG8_MMA(1, 1, At, B1); PG8_BAR; PG8_SCHED;
	ds_read_b128 v[180:183], v138 offset:49152
	ds_read_b128 v[184:187], v138 offset:50176
	ds_read_b128 v[188:191], v138 offset:51200
	ds_read_b128 v[192:195], v138 offset:52224
	ds_read_b128 v[196:199], v138 offset:53248
	ds_read_b128 v[202:205], v138 offset:54272
	ds_read_b128 v[206:209], v138 offset:55296
	ds_read_b128 v[210:213], v138 offset:56320
	s_mov_b32 m0, s69
	s_nop 0
	global_load_lds_dwordx4 v132, s[44:45]
	s_nop 0
	s_mov_b32 m0, s70
	s_nop 0
	global_load_lds_dwordx4 v133, s[44:45]
	s_nop 0
	s_mov_b32 m0, s73
	s_nop 0
	global_load_lds_dwordx4 v132, s[54:55]
	s_nop 0
	s_mov_b32 m0, s76
	s_nop 0
	global_load_lds_dwordx4 v133, s[54:55]
	s_nop 0
	s_mov_b32 m0, s71
	s_nop 0
	global_load_lds_dwordx4 v161, s[42:43]
	s_nop 0
	s_mov_b32 m0, s72
	s_nop 0
	global_load_lds_dwordx4 v163, s[42:43]
	s_waitcnt vmcnt(8)
	s_waitcnt lgkmcnt(0)
	s_barrier
	v_mfma_f32_16x16x32_bf16 v[60:63], v[142:145], v[180:183], v[60:63]
	v_mfma_f32_16x16x32_bf16 v[56:59], v[150:153], v[180:183], v[56:59]
	v_mfma_f32_16x16x32_bf16 v[48:51], v[142:145], v[188:191], v[48:51]
	v_mfma_f32_16x16x32_bf16 v[40:43], v[150:153], v[188:191], v[40:43]
	v_mfma_f32_16x16x32_bf16 v[32:35], v[142:145], v[196:199], v[32:35]
	v_mfma_f32_16x16x32_bf16 v[24:27], v[150:153], v[196:199], v[24:27]
	v_mfma_f32_16x16x32_bf16 v[16:19], v[142:145], v[206:209], v[16:19]
	v_mfma_f32_16x16x32_bf16 v[8:11], v[150:153], v[206:209], v[8:11]
	v_mfma_f32_16x16x32_bf16 v[60:63], v[146:149], v[184:187], v[60:63]
	v_mfma_f32_16x16x32_bf16 v[56:59], v[154:157], v[184:187], v[56:59]
	v_mfma_f32_16x16x32_bf16 v[48:51], v[146:149], v[192:195], v[48:51]
	v_mfma_f32_16x16x32_bf16 v[40:43], v[154:157], v[192:195], v[40:43]
	v_mfma_f32_16x16x32_bf16 v[32:35], v[146:149], v[202:205], v[32:35]
	v_mfma_f32_16x16x32_bf16 v[24:27], v[154:157], v[202:205], v[24:27]
	v_mfma_f32_16x16x32_bf16 v[16:19], v[146:149], v[210:213], v[16:19]
	v_mfma_f32_16x16x32_bf16 v[8:11], v[154:157], v[210:213], v[8:11]
	v_mfma_f32_16x16x32_bf16 v[52:55], v[164:167], v[180:183], v[52:55]
	v_mfma_f32_16x16x32_bf16 v[44:47], v[172:175], v[180:183], v[44:47]
	v_mfma_f32_16x16x32_bf16 v[36:39], v[164:167], v[188:191], v[36:39]
	v_mfma_f32_16x16x32_bf16 v[28:31], v[172:175], v[188:191], v[28:31]
	v_mfma_f32_16x16x32_bf16 v[20:23], v[164:167], v[196:199], v[20:23]
	v_mfma_f32_16x16x32_bf16 v[12:15], v[172:175], v[196:199], v[12:15]
	v_mfma_f32_16x16x32_bf16 v[4:7], v[164:167], v[206:209], v[4:7]
	v_mfma_f32_16x16x32_bf16 v[0:3], v[172:175], v[206:209], v[0:3]
	v_mfma_f32_16x16x32_bf16 v[52:55], v[168:171], v[184:187], v[52:55]
	v_mfma_f32_16x16x32_bf16 v[44:47], v[176:179], v[184:187], v[44:47]
	v_mfma_f32_16x16x32_bf16 v[36:39], v[168:171], v[192:195], v[36:39]
	v_mfma_f32_16x16x32_bf16 v[28:31], v[176:179], v[192:195], v[28:31]
	v_mfma_f32_16x16x32_bf16 v[20:23], v[168:171], v[202:205], v[20:23]
	v_mfma_f32_16x16x32_bf16 v[12:15], v[176:179], v[202:205], v[12:15]
	v_mfma_f32_16x16x32_bf16 v[4:7], v[168:171], v[210:213], v[4:7]
	v_mfma_f32_16x16x32_bf16 v[0:3], v[176:179], v[210:213], v[0:3]
	s_barrier
	s_movk_i32 s44, 0x100
	s_andn2_b64 vcc, exec, s[40:41]
	s_mov_b64 s[42:43], -1
	s_mov_b64 s[40:41], 0
	s_cbranch_vccz .LBB0_1009
	s_and_b64 vcc, exec, s[14:15]
	s_cbranch_vccz .LBB0_1012
	s_barrier

; #define PG8_STAGE(bufoff, gbase, voff) do { const unsigned long long gb_ = (unsigned long long)(gbase); _Pragma("unroll") for (int _i = 0; _i < 2; ++_i) { unsigned keep_; \
;         asm volatile("s_mov_b32 m0, %2\n\ts_nop 0\n\tglobal_load_lds_dwordx4 %0, %1" : : "v"((voff)[_i]), "s"(gb_), "s"((unsigned)(size_t)(lds + (bufoff) + ldsw + _i * 8192)) : "memory", "m0"); (void)keep_; } } while (0)
; #define PG8_LDA(dst, b, h) do { _Pragma("unroll") for (int m = 0; m < 4; ++m) _Pragma("unroll") for (int k = 0; k < 2; ++k) dst[m][k] = *(const PG8_LAS bf16x8*)(lds + PG8_SA(b, h) + aoff + m * 2048 + k * 1024); } while (0)
; #define PG8_WAIT_V(n) asm volatile("s_waitcnt vmcnt(" #n ")" ::: "memory")
; template <class Epi, class Sched, bool ALIGN_EPI = false, bool SP2 = false>
; __device__ __forceinline__ void gemm_phase(PG8_LAS unsigned char* lds, const Gemm g, const Sched& S, const Epi& E) {
;     ...
;         for (int t = 0; t < nt; t += 2) {
;             const bool last = (t == nt - 2);
;     ...
;             const char* a1 = cA + PG8_KOFFA(t + 1);
;             const char* a2 = last ? nA : cA + PG8_KOFFA(t + 2); const char* b2 = last ? nB : cB + (size_t)(t + 2) * kstep;
;             const char* a3 = last ? nA + kstep : cA + PG8_KOFFA(t + 3); const char* b3 = b2 + kstep;
;     ...
;             if (last && has_next) S.a_ready(nxt);
;             if constexpr (SP2) {
;             PG8_LDB(B0, 0, 0); PG8_LDB(B1, 0, 1); PG8_SCHED; PG8_LDA(At, 0, 0); PG8_STAGE(PG8_SA(1, 1), a1 + hstepA, voffA);
;             PG8_WAIT_V(8); PG8_WAIT_L(0); PG8_BAR; PG8_MMA(0, 0, At, B0); PG8_MMA(0, 1, At, B1); PG8_BAR; PG8_SCHED;
;             PG8_LDA(At, 0, 1); PG8_STAGE(PG8_SB(0, 0), b2, voffB); PG8_STAGE(PG8_SB(0, 1), b2 + hstepB, voffB); PG8_STAGE(PG8_SA(0, 0), a2, voffA);
;             PG8_WAIT_V(8); PG8_WAIT_L(0); PG8_BAR; PG8_MMA(1, 0, At, B0); PG8_MMA(1, 1, At, B1); PG8_BAR; PG8_SCHED;
;             PG8_LDB(B0, 1, 0); PG8_LDB(B1, 1, 1); PG8_SCHED; PG8_LDA(At, 1, 0); PG8_STAGE(PG8_SA(0, 1), a2 + hstepA, voffA);
;             PG8_WAIT_V(8); PG8_WAIT_L(0); PG8_BAR; PG8_MMA(0, 0, At, B0); PG8_MMA(0, 1, At, B1); PG8_BAR; PG8_SCHED;
;             PG8_LDA(At, 1, 1); PG8_STAGE(PG8_SB(1, 0), b3, voffB); PG8_STAGE(PG8_SB(1, 1), b3 + hstepB, voffB); PG8_STAGE(PG8_SA(1, 0), a3, voffA);
;             PG8_WAIT_V(8); PG8_WAIT_L(0); PG8_BAR; PG8_MMA(1, 0, At, B0); PG8_MMA(1, 1, At, B1); PG8_BAR; PG8_SCHED;
.LBB0_1114:
	ds_read_b128 v[104:107], v185
	ds_read_b128 v[108:111], v185 offset:1024
	ds_read_b128 v[124:127], v185 offset:2048
	ds_read_b128 v[140:143], v185 offset:3072
	ds_read_b128 v[144:147], v214
	ds_read_b128 v[148:151], v214 offset:1024
	ds_read_b128 v[152:155], v214 offset:2048
	ds_read_b128 v[156:159], v214 offset:3072
	s_cmpk_eq_i32 s66, 0x54
	s_cselect_b32 s36, s10, s0
	s_cselect_b32 s37, s11, s1
	s_cselect_b32 s35, s27, s65
	s_cselect_b32 s34, s26, s64
	s_add_u32 s30, s36, 0x80
	s_addc_u32 s31, s37, 0
	ds_read_b128 v[160:163], v215
	ds_read_b128 v[164:167], v215 offset:1024
	ds_read_b128 v[168:171], v215 offset:2048
	ds_read_b128 v[172:175], v215 offset:3072
	ds_read_b128 v[176:179], v215 offset:4096
	ds_read_b128 v[180:183], v215 offset:5120
	ds_read_b128 v[220:223], v215 offset:6144
	ds_read_b128 v[224:227], v215 offset:7168
	s_mov_b32 m0, s56
	s_nop 0
	global_load_lds_dwordx4 v187, s[28:29]
	s_nop 0
	s_mov_b32 m0, s57
	s_nop 0
	global_load_lds_dwordx4 v212, s[28:29]
	s_waitcnt vmcnt(8)
	s_waitcnt lgkmcnt(0)
	s_barrier
	v_mfma_f32_16x16x32_bf16 v[136:139], v[104:107], v[160:163], v[136:139]
	v_mfma_f32_16x16x32_bf16 v[132:135], v[124:127], v[160:163], v[132:135]
	v_mfma_f32_16x16x32_bf16 v[116:119], v[104:107], v[168:171], v[116:119]
	v_mfma_f32_16x16x32_bf16 v[112:115], v[124:127], v[168:171], v[112:115]
	v_mfma_f32_16x16x32_bf16 v[92:95], v[104:107], v[176:179], v[92:95]
	v_mfma_f32_16x16x32_bf16 v[88:91], v[124:127], v[176:179], v[88:91]
	v_mfma_f32_16x16x32_bf16 v[76:79], v[104:107], v[220:223], v[76:79]
	v_mfma_f32_16x16x32_bf16 v[72:75], v[124:127], v[220:223], v[72:75]
	v_mfma_f32_16x16x32_bf16 v[136:139], v[108:111], v[164:167], v[136:139]
	v_mfma_f32_16x16x32_bf16 v[132:135], v[140:143], v[164:167], v[132:135]
	v_mfma_f32_16x16x32_bf16 v[116:119], v[108:111], v[172:175], v[116:119]
	v_mfma_f32_16x16x32_bf16 v[112:115], v[140:143], v[172:175], v[112:115]
	v_mfma_f32_16x16x32_bf16 v[92:95], v[108:111], v[180:183], v[92:95]
	v_mfma_f32_16x16x32_bf16 v[88:91], v[140:143], v[180:183], v[88:91]
	v_mfma_f32_16x16x32_bf16 v[76:79], v[108:111], v[224:227], v[76:79]
	v_mfma_f32_16x16x32_bf16 v[72:75], v[140:143], v[224:227], v[72:75]
	v_mfma_f32_16x16x32_bf16 v[128:131], v[144:147], v[160:163], v[128:131]
	v_mfma_f32_16x16x32_bf16 v[120:123], v[152:155], v[160:163], v[120:123]
	v_mfma_f32_16x16x32_bf16 v[100:103], v[144:147], v[168:171], v[100:103]
	v_mfma_f32_16x16x32_bf16 v[96:99], v[152:155], v[168:171], v[96:99]
	v_mfma_f32_16x16x32_bf16 v[84:87], v[144:147], v[176:179], v[84:87]
	v_mfma_f32_16x16x32_bf16 v[80:83], v[152:155], v[176:179], v[80:83]
	v_mfma_f32_16x16x32_bf16 v[68:71], v[144:147], v[220:223], v[68:71]
	v_mfma_f32_16x16x32_bf16 v[64:67], v[152:155], v[220:223], v[64:67]
	v_mfma_f32_16x16x32_bf16 v[128:131], v[148:151], v[164:167], v[128:131]
	v_mfma_f32_16x16x32_bf16 v[120:123], v[156:159], v[164:167], v[120:123]
	v_mfma_f32_16x16x32_bf16 v[100:103], v[148:151], v[172:175], v[100:103]
	v_mfma_f32_16x16x32_bf16 v[96:99], v[156:159], v[172:175], v[96:99]
	v_mfma_f32_16x16x32_bf16 v[84:87], v[148:151], v[180:183], v[84:87]
	v_mfma_f32_16x16x32_bf16 v[80:83], v[156:159], v[180:183], v[80:83]
	v_mfma_f32_16x16x32_bf16 v[68:71], v[148:151], v[224:227], v[68:71]
	v_mfma_f32_16x16x32_bf16 v[64:67], v[156:159], v[224:227], v[64:67]
	s_barrier
	ds_read_b128 v[160:163], v215 offset:16384
	ds_read_b128 v[164:167], v215 offset:17408
	ds_read_b128 v[168:171], v215 offset:18432
	ds_read_b128 v[172:175], v215 offset:19456
	ds_read_b128 v[176:179], v215 offset:20480
	ds_read_b128 v[180:183], v215 offset:21504
	ds_read_b128 v[220:223], v215 offset:22528
	ds_read_b128 v[224:227], v215 offset:23552
	s_mov_b32 m0, s42
	s_nop 0
	global_load_lds_dwordx4 v201, s[34:35]
	s_add_u32 s68, s34, 0x160000
	s_mov_b32 m0, s43
	s_nop 0
	global_load_lds_dwordx4 v213, s[34:35]
	s_addc_u32 s69, s35, 0
	s_mov_b32 m0, s44
	s_nop 0
	global_load_lds_dwordx4 v201, s[68:69]
	s_nop 0
	s_mov_b32 m0, s45
	s_nop 0
	global_load_lds_dwordx4 v213, s[68:69]
	s_nop 0
	s_mov_b32 m0, s41
	s_nop 0
	global_load_lds_dwordx4 v187, s[36:37]
	s_nop 0
	s_mov_b32 m0, s46
	s_nop 0
	global_load_lds_dwordx4 v212, s[36:37]
	s_waitcnt vmcnt(8)
	s_waitcnt lgkmcnt(0)
	s_barrier
	v_mfma_f32_16x16x32_bf16 v[60:63], v[104:107], v[160:163], v[60:63]
	v_mfma_f32_16x16x32_bf16 v[56:59], v[124:127], v[160:163], v[56:59]
	v_mfma_f32_16x16x32_bf16 v[44:47], v[104:107], v[168:171], v[44:47]
	v_mfma_f32_16x16x32_bf16 v[40:43], v[124:127], v[168:171], v[40:43]
	v_mfma_f32_16x16x32_bf16 v[28:31], v[104:107], v[176:179], v[28:31]
	v_mfma_f32_16x16x32_bf16 v[24:27], v[124:127], v[176:179], v[24:27]
	v_mfma_f32_16x16x32_bf16 v[12:15], v[104:107], v[220:223], v[12:15]
	v_mfma_f32_16x16x32_bf16 v[8:11], v[124:127], v[220:223], v[8:11]
	v_mfma_f32_16x16x32_bf16 v[60:63], v[108:111], v[164:167], v[60:63]
	v_mfma_f32_16x16x32_bf16 v[56:59], v[140:143], v[164:167], v[56:59]
	v_mfma_f32_16x16x32_bf16 v[44:47], v[108:111], v[172:175], v[44:47]
	v_mfma_f32_16x16x32_bf16 v[40:43], v[140:143], v[172:175], v[40:43]
	v_mfma_f32_16x16x32_bf16 v[28:31], v[108:111], v[180:183], v[28:31]
	v_mfma_f32_16x16x32_bf16 v[24:27], v[140:143], v[180:183], v[24:27]
	v_mfma_f32_16x16x32_bf16 v[12:15], v[108:111], v[224:227], v[12:15]
	v_mfma_f32_16x16x32_bf16 v[8:11], v[140:143], v[224:227], v[8:11]
	v_mfma_f32_16x16x32_bf16 v[52:55], v[144:147], v[160:163], v[52:55]
	v_mfma_f32_16x16x32_bf16 v[48:51], v[152:155], v[160:163], v[48:51]
	v_mfma_f32_16x16x32_bf16 v[36:39], v[144:147], v[168:171], v[36:39]
	v_mfma_f32_16x16x32_bf16 v[32:35], v[152:155], v[168:171], v[32:35]
	v_mfma_f32_16x16x32_bf16 v[20:23], v[144:147], v[176:179], v[20:23]
	v_mfma_f32_16x16x32_bf16 v[16:19], v[152:155], v[176:179], v[16:19]
	v_mfma_f32_16x16x32_bf16 v[4:7], v[144:147], v[220:223], v[4:7]
	v_mfma_f32_16x16x32_bf16 v[0:3], v[152:155], v[220:223], v[0:3]
	v_mfma_f32_16x16x32_bf16 v[52:55], v[148:151], v[164:167], v[52:55]
	v_mfma_f32_16x16x32_bf16 v[48:51], v[156:159], v[164:167], v[48:51]
	v_mfma_f32_16x16x32_bf16 v[36:39], v[148:151], v[172:175], v[36:39]
	v_mfma_f32_16x16x32_bf16 v[32:35], v[156:159], v[172:175], v[32:35]
	v_mfma_f32_16x16x32_bf16 v[20:23], v[148:151], v[180:183], v[20:23]
	v_mfma_f32_16x16x32_bf16 v[16:19], v[156:159], v[180:183], v[16:19]
	v_mfma_f32_16x16x32_bf16 v[4:7], v[148:151], v[224:227], v[4:7]
	v_mfma_f32_16x16x32_bf16 v[0:3], v[156:159], v[224:227], v[0:3]
	s_barrier
; #define PG8_STAGE(bufoff, gbase, voff) do { const unsigned long long gb_ = (unsigned long long)(gbase); _Pragma("unroll") for (int _i = 0; _i < 2; ++_i) { unsigned keep_; \
;         asm volatile("s_mov_b32 m0, %2\n\ts_nop 0\n\tglobal_load_lds_dwordx4 %0, %1" : : "v"((voff)[_i]), "s"(gb_), "s"((unsigned)(size_t)(lds + (bufoff) + ldsw + _i * 8192)) : "memory", "m0"); (void)keep_; } } while (0)
; #define PG8_LDA(dst, b, h) do { _Pragma("unroll") for (int m = 0; m < 4; ++m) _Pragma("unroll") for (int k = 0; k < 2; ++k) dst[m][k] = *(const PG8_LAS bf16x8*)(lds + PG8_SA(b, h) + aoff + m * 2048 + k * 1024); } while (0)
; #define PG8_LDB(dst, b, h) do { _Pragma("unroll") for (int n = 0; n < 2; ++n) _Pragma("unroll") for (int k = 0; k < 2; ++k) dst[n][k] = *(const PG8_LAS bf16x8*)(lds + PG8_SB(b, h) + boff + n * 2048 + k * 1024); } while (0)
; #define PG8_MMA(ai, bj, At, Bt) do { __builtin_amdgcn_s_setprio(1); _Pragma("unroll") for (int m = 0; m < 4; ++m) _Pragma("unroll") for (int n = 0; n < 2; ++n) _Pragma("unroll") for (int k = 0; k < 2; ++k) \
;         acc[ai][bj][m][n] = __builtin_amdgcn_mfma_f32_16x16x32_bf16(Bt[n][k], At[m][k], acc[ai][bj][m][n], 0, 0, 0); __builtin_amdgcn_s_setprio(0); } while (0)
; #define PG8_WAIT_V(n) asm volatile("s_waitcnt vmcnt(" #n ")" ::: "memory")
; #define PG8_WAIT_L(n) asm volatile("s_waitcnt lgkmcnt(" #n ")" ::: "memory")
; #define PG8_BAR __builtin_amdgcn_s_barrier()
; #define PG8_SCHED __builtin_amdgcn_sched_barrier(0)
; template <class Epi, class Sched, bool ALIGN_EPI = false, bool SP2 = false>
; __device__ __forceinline__ void gemm_phase(PG8_LAS unsigned char* lds, const Gemm g, const Sched& S, const Epi& E) {
;     ...
;         for (int t = 0; t < nt; t += 2) {
;     ...
;             PG8_LDB(B0, 1, 0); PG8_LDB(B1, 1, 1); PG8_SCHED; PG8_LDA(At, 1, 0); PG8_STAGE(PG8_SA(0, 1), a2 + hstepA, voffA);
;             PG8_WAIT_V(8); PG8_WAIT_L(0); PG8_BAR; PG8_MMA(0, 0, At, B0); PG8_MMA(0, 1, At, B1); PG8_BAR; PG8_SCHED;
;             PG8_LDA(At, 1, 1); PG8_STAGE(PG8_SB(1, 0), b3, voffB); PG8_STAGE(PG8_SB(1, 1), b3 + hstepB, voffB); PG8_STAGE(PG8_SA(1, 0), a3, voffA);
;             PG8_WAIT_V(8); PG8_WAIT_L(0); PG8_BAR; PG8_MMA(1, 0, At, B0); PG8_MMA(1, 1, At, B1); PG8_BAR; PG8_SCHED;
	ds_read_b128 v[104:107], v216
	ds_read_b128 v[108:111], v216 offset:1024
	ds_read_b128 v[124:127], v216 offset:2048
	ds_read_b128 v[140:143], v216 offset:3072
	ds_read_b128 v[144:147], v217
	ds_read_b128 v[148:151], v217 offset:1024
	ds_read_b128 v[152:155], v217 offset:2048
	ds_read_b128 v[156:159], v217 offset:3072
	ds_read_b128 v[160:163], v215 offset:32768
	ds_read_b128 v[164:167], v215 offset:33792
	ds_read_b128 v[168:171], v215 offset:34816
	ds_read_b128 v[172:175], v215 offset:35840
	ds_read_b128 v[176:179], v215 offset:36864
	ds_read_b128 v[180:183], v215 offset:37888
	ds_read_b128 v[220:223], v215 offset:38912
	ds_read_b128 v[224:227], v215 offset:39936
	s_add_u32 s36, s36, 0x8000
	s_addc_u32 s37, s37, 0
	s_mov_b32 m0, s47
	s_nop 0
	global_load_lds_dwordx4 v187, s[36:37]
	s_nop 0
	s_mov_b32 m0, s48
	s_nop 0
	global_load_lds_dwordx4 v212, s[36:37]
	s_waitcnt vmcnt(8)
	s_waitcnt lgkmcnt(0)
	s_barrier
	v_mfma_f32_16x16x32_bf16 v[136:139], v[104:107], v[160:163], v[136:139]
	v_mfma_f32_16x16x32_bf16 v[132:135], v[124:127], v[160:163], v[132:135]
	v_mfma_f32_16x16x32_bf16 v[116:119], v[104:107], v[168:171], v[116:119]
	v_mfma_f32_16x16x32_bf16 v[112:115], v[124:127], v[168:171], v[112:115]
	v_mfma_f32_16x16x32_bf16 v[92:95], v[104:107], v[176:179], v[92:95]
	v_mfma_f32_16x16x32_bf16 v[88:91], v[124:127], v[176:179], v[88:91]
	v_mfma_f32_16x16x32_bf16 v[76:79], v[104:107], v[220:223], v[76:79]
	v_mfma_f32_16x16x32_bf16 v[72:75], v[124:127], v[220:223], v[72:75]
	v_mfma_f32_16x16x32_bf16 v[136:139], v[108:111], v[164:167], v[136:139]
	v_mfma_f32_16x16x32_bf16 v[132:135], v[140:143], v[164:167], v[132:135]
	v_mfma_f32_16x16x32_bf16 v[116:119], v[108:111], v[172:175], v[116:119]
	v_mfma_f32_16x16x32_bf16 v[112:115], v[140:143], v[172:175], v[112:115]
	v_mfma_f32_16x16x32_bf16 v[92:95], v[108:111], v[180:183], v[92:95]
	v_mfma_f32_16x16x32_bf16 v[88:91], v[140:143], v[180:183], v[88:91]
	v_mfma_f32_16x16x32_bf16 v[76:79], v[108:111], v[224:227], v[76:79]
	v_mfma_f32_16x16x32_bf16 v[72:75], v[140:143], v[224:227], v[72:75]
	v_mfma_f32_16x16x32_bf16 v[128:131], v[144:147], v[160:163], v[128:131]
	v_mfma_f32_16x16x32_bf16 v[120:123], v[152:155], v[160:163], v[120:123]
	v_mfma_f32_16x16x32_bf16 v[100:103], v[144:147], v[168:171], v[100:103]
	v_mfma_f32_16x16x32_bf16 v[96:99], v[152:155], v[168:171], v[96:99]
	v_mfma_f32_16x16x32_bf16 v[84:87], v[144:147], v[176:179], v[84:87]
	v_mfma_f32_16x16x32_bf16 v[80:83], v[152:155], v[176:179], v[80:83]
	v_mfma_f32_16x16x32_bf16 v[68:71], v[144:147], v[220:223], v[68:71]
	v_mfma_f32_16x16x32_bf16 v[64:67], v[152:155], v[220:223], v[64:67]
	v_mfma_f32_16x16x32_bf16 v[128:131], v[148:151], v[164:167], v[128:131]
	v_mfma_f32_16x16x32_bf16 v[120:123], v[156:159], v[164:167], v[120:123]
	v_mfma_f32_16x16x32_bf16 v[100:103], v[148:151], v[172:175], v[100:103]
	v_mfma_f32_16x16x32_bf16 v[96:99], v[156:159], v[172:175], v[96:99]
	v_mfma_f32_16x16x32_bf16 v[84:87], v[148:151], v[180:183], v[84:87]
	v_mfma_f32_16x16x32_bf16 v[80:83], v[156:159], v[180:183], v[80:83]
	v_mfma_f32_16x16x32_bf16 v[68:71], v[148:151], v[224:227], v[68:71]
	v_mfma_f32_16x16x32_bf16 v[64:67], v[156:159], v[224:227], v[64:67]
	s_barrier
	ds_read_b128 v[160:163], v215 offset:49152
	ds_read_b128 v[164:167], v215 offset:50176
	ds_read_b128 v[168:171], v215 offset:51200
	ds_read_b128 v[172:175], v215 offset:52224
	ds_read_b128 v[176:179], v215 offset:53248
	ds_read_b128 v[180:183], v215 offset:54272
	ds_read_b128 v[220:223], v215 offset:55296
	ds_read_b128 v[224:227], v215 offset:56320
	s_add_u32 s36, s34, 0x80
	s_addc_u32 s37, s35, 0
	s_mov_b32 m0, s50
	s_nop 0
	global_load_lds_dwordx4 v201, s[36:37]
	s_add_u32 s34, s34, 0x160080
	s_mov_b32 m0, s51
	s_nop 0
	global_load_lds_dwordx4 v213, s[36:37]
	s_addc_u32 s35, s35, 0
	s_mov_b32 m0, s54
	s_nop 0
	global_load_lds_dwordx4 v201, s[34:35]
	s_nop 0
	s_mov_b32 m0, s55
	s_nop 0
	global_load_lds_dwordx4 v213, s[34:35]
	s_nop 0
	s_mov_b32 m0, s52
	s_nop 0
	global_load_lds_dwordx4 v187, s[30:31]
	s_nop 0
	s_mov_b32 m0, s53
	s_nop 0
	global_load_lds_dwordx4 v212, s[30:31]
	s_waitcnt vmcnt(8)
	s_waitcnt lgkmcnt(0)
	s_barrier
	v_mfma_f32_16x16x32_bf16 v[60:63], v[104:107], v[160:163], v[60:63]
	v_mfma_f32_16x16x32_bf16 v[56:59], v[124:127], v[160:163], v[56:59]
	v_mfma_f32_16x16x32_bf16 v[44:47], v[104:107], v[168:171], v[44:47]
	v_mfma_f32_16x16x32_bf16 v[40:43], v[124:127], v[168:171], v[40:43]
	v_mfma_f32_16x16x32_bf16 v[28:31], v[104:107], v[176:179], v[28:31]
	v_mfma_f32_16x16x32_bf16 v[24:27], v[124:127], v[176:179], v[24:27]
	v_mfma_f32_16x16x32_bf16 v[12:15], v[104:107], v[220:223], v[12:15]
	v_mfma_f32_16x16x32_bf16 v[8:11], v[124:127], v[220:223], v[8:11]
	v_mfma_f32_16x16x32_bf16 v[60:63], v[108:111], v[164:167], v[60:63]
	v_mfma_f32_16x16x32_bf16 v[56:59], v[140:143], v[164:167], v[56:59]
	v_mfma_f32_16x16x32_bf16 v[44:47], v[108:111], v[172:175], v[44:47]
	v_mfma_f32_16x16x32_bf16 v[40:43], v[140:143], v[172:175], v[40:43]
	v_mfma_f32_16x16x32_bf16 v[28:31], v[108:111], v[180:183], v[28:31]
	v_mfma_f32_16x16x32_bf16 v[24:27], v[140:143], v[180:183], v[24:27]
	v_mfma_f32_16x16x32_bf16 v[12:15], v[108:111], v[224:227], v[12:15]
	v_mfma_f32_16x16x32_bf16 v[8:11], v[140:143], v[224:227], v[8:11]
	v_mfma_f32_16x16x32_bf16 v[52:55], v[144:147], v[160:163], v[52:55]
	v_mfma_f32_16x16x32_bf16 v[48:51], v[152:155], v[160:163], v[48:51]
	v_mfma_f32_16x16x32_bf16 v[36:39], v[144:147], v[168:171], v[36:39]
	v_mfma_f32_16x16x32_bf16 v[32:35], v[152:155], v[168:171], v[32:35]
	v_mfma_f32_16x16x32_bf16 v[20:23], v[144:147], v[176:179], v[20:23]
	v_mfma_f32_16x16x32_bf16 v[16:19], v[152:155], v[176:179], v[16:19]
	v_mfma_f32_16x16x32_bf16 v[4:7], v[144:147], v[220:223], v[4:7]
	v_mfma_f32_16x16x32_bf16 v[0:3], v[152:155], v[220:223], v[0:3]
	v_mfma_f32_16x16x32_bf16 v[52:55], v[148:151], v[164:167], v[52:55]
	v_mfma_f32_16x16x32_bf16 v[48:51], v[156:159], v[164:167], v[48:51]
	v_mfma_f32_16x16x32_bf16 v[36:39], v[148:151], v[172:175], v[36:39]
	v_mfma_f32_16x16x32_bf16 v[32:35], v[156:159], v[172:175], v[32:35]
	v_mfma_f32_16x16x32_bf16 v[20:23], v[148:151], v[180:183], v[20:23]
	v_mfma_f32_16x16x32_bf16 v[16:19], v[156:159], v[180:183], v[16:19]
	v_mfma_f32_16x16x32_bf16 v[4:7], v[148:151], v[224:227], v[4:7]
	v_mfma_f32_16x16x32_bf16 v[0:3], v[156:159], v[224:227], v[0:3]
	s_barrier
	s_add_i32 s66, s66, 2
	s_add_u32 s0, s0, 0x10000
	s_addc_u32 s1, s1, 0
	s_add_u32 s64, s64, 0x100
	s_addc_u32 s65, s65, 0
	s_add_u32 s28, s28, 0x10000
	s_addc_u32 s29, s29, 0
	s_cmpk_gt_u32 s66, 0x55
	s_cbranch_scc0 .LBB0_1114
	s_and_b64 vcc, exec, s[24:25]
	s_cbranch_vccz .LBB0_1117
	s_barrier

; #define PG8_STAGE(bufoff, gbase, voff) do { const unsigned long long gb_ = (unsigned long long)(gbase); _Pragma("unroll") for (int _i = 0; _i < 2; ++_i) { unsigned keep_; \
;         asm volatile("s_mov_b32 m0, %2\n\ts_nop 0\n\tglobal_load_lds_dwordx4 %0, %1" : : "v"((voff)[_i]), "s"(gb_), "s"((unsigned)(size_t)(lds + (bufoff) + ldsw + _i * 8192)) : "memory", "m0"); (void)keep_; } } while (0)
; #define PG8_LDA(dst, b, h) do { _Pragma("unroll") for (int m = 0; m < 4; ++m) _Pragma("unroll") for (int k = 0; k < 2; ++k) dst[m][k] = *(const PG8_LAS bf16x8*)(lds + PG8_SA(b, h) + aoff + m * 2048 + k * 1024); } while (0)
; #define PG8_WAIT_V(n) asm volatile("s_waitcnt vmcnt(" #n ")" ::: "memory")
; template <class Epi, class Sched, bool ALIGN_EPI = false, bool SP2 = false>
; __device__ __forceinline__ void gemm_phase(PG8_LAS unsigned char* lds, const Gemm g, const Sched& S, const Epi& E) {
;     ...
;         for (int t = 0; t < nt; t += 2) {
;             const bool last = (t == nt - 2);
;     ...
;             const char* a1 = cA + PG8_KOFFA(t + 1);
;             const char* a2 = last ? nA : cA + PG8_KOFFA(t + 2); const char* b2 = last ? nB : cB + (size_t)(t + 2) * kstep;
;             const char* a3 = last ? nA + kstep : cA + PG8_KOFFA(t + 3); const char* b3 = b2 + kstep;
;     ...
;             if (last && has_next) S.a_ready(nxt);
;             if constexpr (SP2) {
;             PG8_LDB(B0, 0, 0); PG8_LDB(B1, 0, 1); PG8_SCHED; PG8_LDA(At, 0, 0); PG8_STAGE(PG8_SA(1, 1), a1 + hstepA, voffA);
;             PG8_WAIT_V(8); PG8_WAIT_L(0); PG8_BAR; PG8_MMA(0, 0, At, B0); PG8_MMA(0, 1, At, B1); PG8_BAR; PG8_SCHED;
;             PG8_LDA(At, 0, 1); PG8_STAGE(PG8_SB(0, 0), b2, voffB); PG8_STAGE(PG8_SB(0, 1), b2 + hstepB, voffB); PG8_STAGE(PG8_SA(0, 0), a2, voffA);
;             PG8_WAIT_V(8); PG8_WAIT_L(0); PG8_BAR; PG8_MMA(1, 0, At, B0); PG8_MMA(1, 1, At, B1); PG8_BAR; PG8_SCHED;
;             PG8_LDB(B0, 1, 0); PG8_LDB(B1, 1, 1); PG8_SCHED; PG8_LDA(At, 1, 0); PG8_STAGE(PG8_SA(0, 1), a2 + hstepA, voffA);
;             PG8_WAIT_V(8); PG8_WAIT_L(0); PG8_BAR; PG8_MMA(0, 0, At, B0); PG8_MMA(0, 1, At, B1); PG8_BAR; PG8_SCHED;
;             PG8_LDA(At, 1, 1); PG8_STAGE(PG8_SB(1, 0), b3, voffB); PG8_STAGE(PG8_SB(1, 1), b3 + hstepB, voffB); PG8_STAGE(PG8_SA(1, 0), a3, voffA);
;             PG8_WAIT_V(8); PG8_WAIT_L(0); PG8_BAR; PG8_MMA(1, 0, At, B0); PG8_MMA(1, 1, At, B1); PG8_BAR; PG8_SCHED;
.LBB0_1235:
	s_add_i32 s45, s77, 0xfffe8000
	s_and_b32 s44, s42, 0x100
	s_and_b32 s45, s45, 0xe0000
	s_or_b32 s44, s44, s45
	s_add_u32 s78, s10, s44
	s_addc_u32 s79, s11, 0
	s_add_u32 s44, s42, 0x100
	s_addc_u32 s45, s43, 0
	s_add_i32 s47, s77, 0xffff8000
	s_and_b32 s46, s44, 0x100
	s_and_b32 s47, s47, 0x1e0000
	s_or_b32 s46, s47, s46
	ds_read_b128 v[128:131], v175
	ds_read_b128 v[132:135], v175 offset:1024
	ds_read_b128 v[162:165], v175 offset:2048
	ds_read_b128 v[166:169], v175 offset:3072
	ds_read_b128 v[182:185], v176
	ds_read_b128 v[186:189], v176 offset:1024
	ds_read_b128 v[190:193], v176 offset:2048
	ds_read_b128 v[194:197], v176 offset:3072
	s_add_u32 s46, s10, s46
	s_addc_u32 s47, s11, 0
	s_add_u32 s80, s41, s42
	s_addc_u32 s43, s73, s43
	s_add_i32 s48, s42, 0x180
	s_and_b32 s48, s48, 0x180
	s_and_b32 s49, s77, 0x1e0000
	s_or_b32 s48, s49, s48
	s_add_u32 s81, s10, s48
	s_addc_u32 s82, s11, 0
	s_cmpk_eq_i32 s42, 0xf00
	s_cselect_b32 s49, s0, s47
	s_cselect_b32 s47, s4, s43
	s_cselect_b32 s43, s35, s82
	s_cselect_b32 s42, s31, s81
	s_cselect_b32 s48, s1, s46
	s_cselect_b32 s46, s5, s80
	ds_read_b128 v[202:205], v177
	ds_read_b128 v[206:209], v177 offset:1024
	ds_read_b128 v[210:213], v177 offset:2048
	ds_read_b128 v[214:217], v177 offset:3072
	ds_read_b128 v[218:221], v177 offset:4096
	ds_read_b128 v[222:225], v177 offset:5120
	ds_read_b128 v[226:229], v177 offset:6144
	ds_read_b128 v[230:233], v177 offset:7168
	s_add_u32 s78, s78, 0x10080
	s_addc_u32 s79, s79, 0
	s_mov_b32 m0, s68
	s_nop 0
	global_load_lds_dwordx4 v139, s[78:79]
	s_nop 0
	s_mov_b32 m0, s69
	s_nop 0
	global_load_lds_dwordx4 v173, s[78:79]
	s_waitcnt vmcnt(8)
	s_waitcnt lgkmcnt(0)
	s_barrier
	v_mfma_f32_16x16x32_bf16 v[124:127], v[128:131], v[202:205], v[124:127]
	v_mfma_f32_16x16x32_bf16 v[120:123], v[162:165], v[202:205], v[120:123]
	v_mfma_f32_16x16x32_bf16 v[108:111], v[128:131], v[210:213], v[108:111]
	v_mfma_f32_16x16x32_bf16 v[104:107], v[162:165], v[210:213], v[104:107]
	v_mfma_f32_16x16x32_bf16 v[92:95], v[128:131], v[218:221], v[92:95]
	v_mfma_f32_16x16x32_bf16 v[88:91], v[162:165], v[218:221], v[88:91]
	v_mfma_f32_16x16x32_bf16 v[76:79], v[128:131], v[226:229], v[76:79]
	v_mfma_f32_16x16x32_bf16 v[72:75], v[162:165], v[226:229], v[72:75]
	v_mfma_f32_16x16x32_bf16 v[124:127], v[132:135], v[206:209], v[124:127]
	v_mfma_f32_16x16x32_bf16 v[120:123], v[166:169], v[206:209], v[120:123]
	v_mfma_f32_16x16x32_bf16 v[108:111], v[132:135], v[214:217], v[108:111]
	v_mfma_f32_16x16x32_bf16 v[104:107], v[166:169], v[214:217], v[104:107]
	v_mfma_f32_16x16x32_bf16 v[92:95], v[132:135], v[222:225], v[92:95]
	v_mfma_f32_16x16x32_bf16 v[88:91], v[166:169], v[222:225], v[88:91]
	v_mfma_f32_16x16x32_bf16 v[76:79], v[132:135], v[230:233], v[76:79]
	v_mfma_f32_16x16x32_bf16 v[72:75], v[166:169], v[230:233], v[72:75]
	v_mfma_f32_16x16x32_bf16 v[116:119], v[182:185], v[202:205], v[116:119]
	v_mfma_f32_16x16x32_bf16 v[112:115], v[190:193], v[202:205], v[112:115]
	v_mfma_f32_16x16x32_bf16 v[100:103], v[182:185], v[210:213], v[100:103]
	v_mfma_f32_16x16x32_bf16 v[96:99], v[190:193], v[210:213], v[96:99]
	v_mfma_f32_16x16x32_bf16 v[84:87], v[182:185], v[218:221], v[84:87]
	v_mfma_f32_16x16x32_bf16 v[80:83], v[190:193], v[218:221], v[80:83]
	v_mfma_f32_16x16x32_bf16 v[68:71], v[182:185], v[226:229], v[68:71]
	v_mfma_f32_16x16x32_bf16 v[64:67], v[190:193], v[226:229], v[64:67]
	v_mfma_f32_16x16x32_bf16 v[116:119], v[186:189], v[206:209], v[116:119]
	v_mfma_f32_16x16x32_bf16 v[112:115], v[194:197], v[206:209], v[112:115]
	v_mfma_f32_16x16x32_bf16 v[100:103], v[186:189], v[214:217], v[100:103]
	v_mfma_f32_16x16x32_bf16 v[96:99], v[194:197], v[214:217], v[96:99]
	v_mfma_f32_16x16x32_bf16 v[84:87], v[186:189], v[222:225], v[84:87]
	v_mfma_f32_16x16x32_bf16 v[80:83], v[194:197], v[222:225], v[80:83]
	v_mfma_f32_16x16x32_bf16 v[68:71], v[186:189], v[230:233], v[68:71]
	v_mfma_f32_16x16x32_bf16 v[64:67], v[194:197], v[230:233], v[64:67]
	s_barrier
	ds_read_b128 v[202:205], v177 offset:16384
	ds_read_b128 v[206:209], v177 offset:17408
	ds_read_b128 v[210:213], v177 offset:18432
	ds_read_b128 v[214:217], v177 offset:19456
	ds_read_b128 v[218:221], v177 offset:20480
	ds_read_b128 v[222:225], v177 offset:21504
	ds_read_b128 v[226:229], v177 offset:22528
	ds_read_b128 v[230:233], v177 offset:23552
	s_mov_b32 m0, s54
	s_nop 0
	global_load_lds_dwordx4 v172, s[46:47]
	s_add_u32 s78, s46, 0x80000
	s_mov_b32 m0, s55
	s_nop 0
	global_load_lds_dwordx4 v174, s[46:47]
	s_addc_u32 s79, s47, 0
	s_mov_b32 m0, s56
	s_nop 0
	global_load_lds_dwordx4 v172, s[78:79]
	s_nop 0
	s_mov_b32 m0, s57
	s_nop 0
	global_load_lds_dwordx4 v174, s[78:79]
	s_nop 0
	s_mov_b32 m0, s53
	s_nop 0
	global_load_lds_dwordx4 v139, s[48:49]
	s_nop 0
	s_mov_b32 m0, s58
	s_nop 0
	global_load_lds_dwordx4 v173, s[48:49]
	s_waitcnt vmcnt(8)
	s_waitcnt lgkmcnt(0)
	s_barrier
; #define PG8_STAGE(bufoff, gbase, voff) do { const unsigned long long gb_ = (unsigned long long)(gbase); _Pragma("unroll") for (int _i = 0; _i < 2; ++_i) { unsigned keep_; \
;         asm volatile("s_mov_b32 m0, %2\n\ts_nop 0\n\tglobal_load_lds_dwordx4 %0, %1" : : "v"((voff)[_i]), "s"(gb_), "s"((unsigned)(size_t)(lds + (bufoff) + ldsw + _i * 8192)) : "memory", "m0"); (void)keep_; } } while (0)
; #define PG8_LDA(dst, b, h) do { _Pragma("unroll") for (int m = 0; m < 4; ++m) _Pragma("unroll") for (int k = 0; k < 2; ++k) dst[m][k] = *(const PG8_LAS bf16x8*)(lds + PG8_SA(b, h) + aoff + m * 2048 + k * 1024); } while (0)
; #define PG8_LDB(dst, b, h) do { _Pragma("unroll") for (int n = 0; n < 2; ++n) _Pragma("unroll") for (int k = 0; k < 2; ++k) dst[n][k] = *(const PG8_LAS bf16x8*)(lds + PG8_SB(b, h) + boff + n * 2048 + k * 1024); } while (0)
; #define PG8_MMA(ai, bj, At, Bt) do { __builtin_amdgcn_s_setprio(1); _Pragma("unroll") for (int m = 0; m < 4; ++m) _Pragma("unroll") for (int n = 0; n < 2; ++n) _Pragma("unroll") for (int k = 0; k < 2; ++k) \
;         acc[ai][bj][m][n] = __builtin_amdgcn_mfma_f32_16x16x32_bf16(Bt[n][k], At[m][k], acc[ai][bj][m][n], 0, 0, 0); __builtin_amdgcn_s_setprio(0); } while (0)
; #define PG8_WAIT_V(n) asm volatile("s_waitcnt vmcnt(" #n ")" ::: "memory")
; #define PG8_WAIT_L(n) asm volatile("s_waitcnt lgkmcnt(" #n ")" ::: "memory")
; #define PG8_BAR __builtin_amdgcn_s_barrier()
; #define PG8_SCHED __builtin_amdgcn_sched_barrier(0)
; template <class Epi, class Sched, bool ALIGN_EPI = false, bool SP2 = false>
; __device__ __forceinline__ void gemm_phase(PG8_LAS unsigned char* lds, const Gemm g, const Sched& S, const Epi& E) {
;     ...
;             PG8_WAIT_V(8); PG8_WAIT_L(0); PG8_BAR; PG8_MMA(1, 0, At, B0); PG8_MMA(1, 1, At, B1); PG8_BAR; PG8_SCHED;
;             PG8_LDB(B0, 1, 0); PG8_LDB(B1, 1, 1); PG8_SCHED; PG8_LDA(At, 1, 0); PG8_STAGE(PG8_SA(0, 1), a2 + hstepA, voffA);
;             PG8_WAIT_V(8); PG8_WAIT_L(0); PG8_BAR; PG8_MMA(0, 0, At, B0); PG8_MMA(0, 1, At, B1); PG8_BAR; PG8_SCHED;
;             PG8_LDA(At, 1, 1); PG8_STAGE(PG8_SB(1, 0), b3, voffB); PG8_STAGE(PG8_SB(1, 1), b3 + hstepB, voffB); PG8_STAGE(PG8_SA(1, 0), a3, voffA);
;             PG8_WAIT_V(8); PG8_WAIT_L(0); PG8_BAR; PG8_MMA(1, 0, At, B0); PG8_MMA(1, 1, At, B1); PG8_BAR; PG8_SCHED;
	v_mfma_f32_16x16x32_bf16 v[60:63], v[128:131], v[202:205], v[60:63]
	v_mfma_f32_16x16x32_bf16 v[56:59], v[162:165], v[202:205], v[56:59]
	v_mfma_f32_16x16x32_bf16 v[44:47], v[128:131], v[210:213], v[44:47]
	v_mfma_f32_16x16x32_bf16 v[40:43], v[162:165], v[210:213], v[40:43]
	v_mfma_f32_16x16x32_bf16 v[28:31], v[128:131], v[218:221], v[28:31]
	v_mfma_f32_16x16x32_bf16 v[24:27], v[162:165], v[218:221], v[24:27]
	v_mfma_f32_16x16x32_bf16 v[12:15], v[128:131], v[226:229], v[12:15]
	v_mfma_f32_16x16x32_bf16 v[8:11], v[162:165], v[226:229], v[8:11]
	v_mfma_f32_16x16x32_bf16 v[60:63], v[132:135], v[206:209], v[60:63]
	v_mfma_f32_16x16x32_bf16 v[56:59], v[166:169], v[206:209], v[56:59]
	v_mfma_f32_16x16x32_bf16 v[44:47], v[132:135], v[214:217], v[44:47]
	v_mfma_f32_16x16x32_bf16 v[40:43], v[166:169], v[214:217], v[40:43]
	v_mfma_f32_16x16x32_bf16 v[28:31], v[132:135], v[222:225], v[28:31]
	v_mfma_f32_16x16x32_bf16 v[24:27], v[166:169], v[222:225], v[24:27]
	v_mfma_f32_16x16x32_bf16 v[12:15], v[132:135], v[230:233], v[12:15]
	v_mfma_f32_16x16x32_bf16 v[8:11], v[166:169], v[230:233], v[8:11]
	v_mfma_f32_16x16x32_bf16 v[52:55], v[182:185], v[202:205], v[52:55]
	v_mfma_f32_16x16x32_bf16 v[48:51], v[190:193], v[202:205], v[48:51]
	v_mfma_f32_16x16x32_bf16 v[36:39], v[182:185], v[210:213], v[36:39]
	v_mfma_f32_16x16x32_bf16 v[32:35], v[190:193], v[210:213], v[32:35]
	v_mfma_f32_16x16x32_bf16 v[20:23], v[182:185], v[218:221], v[20:23]
	v_mfma_f32_16x16x32_bf16 v[16:19], v[190:193], v[218:221], v[16:19]
	v_mfma_f32_16x16x32_bf16 v[4:7], v[182:185], v[226:229], v[4:7]
	v_mfma_f32_16x16x32_bf16 v[0:3], v[190:193], v[226:229], v[0:3]
	v_mfma_f32_16x16x32_bf16 v[52:55], v[186:189], v[206:209], v[52:55]
	v_mfma_f32_16x16x32_bf16 v[48:51], v[194:197], v[206:209], v[48:51]
	v_mfma_f32_16x16x32_bf16 v[36:39], v[186:189], v[214:217], v[36:39]
	v_mfma_f32_16x16x32_bf16 v[32:35], v[194:197], v[214:217], v[32:35]
	v_mfma_f32_16x16x32_bf16 v[20:23], v[186:189], v[222:225], v[20:23]
	v_mfma_f32_16x16x32_bf16 v[16:19], v[194:197], v[222:225], v[16:19]
	v_mfma_f32_16x16x32_bf16 v[4:7], v[186:189], v[230:233], v[4:7]
	v_mfma_f32_16x16x32_bf16 v[0:3], v[194:197], v[230:233], v[0:3]
	s_barrier
	ds_read_b128 v[128:131], v178
	ds_read_b128 v[132:135], v178 offset:1024
	ds_read_b128 v[162:165], v178 offset:2048
	ds_read_b128 v[166:169], v178 offset:3072
	ds_read_b128 v[182:185], v179
	ds_read_b128 v[186:189], v179 offset:1024
	ds_read_b128 v[190:193], v179 offset:2048
	ds_read_b128 v[194:197], v179 offset:3072
	ds_read_b128 v[202:205], v177 offset:32768
	ds_read_b128 v[206:209], v177 offset:33792
	ds_read_b128 v[210:213], v177 offset:34816
	ds_read_b128 v[214:217], v177 offset:35840
	ds_read_b128 v[218:221], v177 offset:36864
	ds_read_b128 v[222:225], v177 offset:37888
	ds_read_b128 v[226:229], v177 offset:38912
	ds_read_b128 v[230:233], v177 offset:39936
	s_add_u32 s48, s48, 0x10000
	s_addc_u32 s49, s49, 0
	s_mov_b32 m0, s59
	s_nop 0
	global_load_lds_dwordx4 v139, s[48:49]
	s_nop 0
	s_mov_b32 m0, s60
	s_nop 0
	global_load_lds_dwordx4 v173, s[48:49]
	s_waitcnt vmcnt(8)
	s_waitcnt lgkmcnt(0)
	s_barrier
	v_mfma_f32_16x16x32_bf16 v[124:127], v[128:131], v[202:205], v[124:127]
	v_mfma_f32_16x16x32_bf16 v[120:123], v[162:165], v[202:205], v[120:123]
	v_mfma_f32_16x16x32_bf16 v[108:111], v[128:131], v[210:213], v[108:111]
	v_mfma_f32_16x16x32_bf16 v[104:107], v[162:165], v[210:213], v[104:107]
	v_mfma_f32_16x16x32_bf16 v[92:95], v[128:131], v[218:221], v[92:95]
	v_mfma_f32_16x16x32_bf16 v[88:91], v[162:165], v[218:221], v[88:91]
	v_mfma_f32_16x16x32_bf16 v[76:79], v[128:131], v[226:229], v[76:79]
	v_mfma_f32_16x16x32_bf16 v[72:75], v[162:165], v[226:229], v[72:75]
	v_mfma_f32_16x16x32_bf16 v[124:127], v[132:135], v[206:209], v[124:127]
	v_mfma_f32_16x16x32_bf16 v[120:123], v[166:169], v[206:209], v[120:123]
	v_mfma_f32_16x16x32_bf16 v[108:111], v[132:135], v[214:217], v[108:111]
	v_mfma_f32_16x16x32_bf16 v[104:107], v[166:169], v[214:217], v[104:107]
	v_mfma_f32_16x16x32_bf16 v[92:95], v[132:135], v[222:225], v[92:95]
	v_mfma_f32_16x16x32_bf16 v[88:91], v[166:169], v[222:225], v[88:91]
	v_mfma_f32_16x16x32_bf16 v[76:79], v[132:135], v[230:233], v[76:79]
	v_mfma_f32_16x16x32_bf16 v[72:75], v[166:169], v[230:233], v[72:75]
	v_mfma_f32_16x16x32_bf16 v[116:119], v[182:185], v[202:205], v[116:119]
	v_mfma_f32_16x16x32_bf16 v[112:115], v[190:193], v[202:205], v[112:115]
	v_mfma_f32_16x16x32_bf16 v[100:103], v[182:185], v[210:213], v[100:103]
	v_mfma_f32_16x16x32_bf16 v[96:99], v[190:193], v[210:213], v[96:99]
	v_mfma_f32_16x16x32_bf16 v[84:87], v[182:185], v[218:221], v[84:87]
	v_mfma_f32_16x16x32_bf16 v[80:83], v[190:193], v[218:221], v[80:83]
	v_mfma_f32_16x16x32_bf16 v[68:71], v[182:185], v[226:229], v[68:71]
	v_mfma_f32_16x16x32_bf16 v[64:67], v[190:193], v[226:229], v[64:67]
	v_mfma_f32_16x16x32_bf16 v[116:119], v[186:189], v[206:209], v[116:119]
	v_mfma_f32_16x16x32_bf16 v[112:115], v[194:197], v[206:209], v[112:115]
	v_mfma_f32_16x16x32_bf16 v[100:103], v[186:189], v[214:217], v[100:103]
	v_mfma_f32_16x16x32_bf16 v[96:99], v[194:197], v[214:217], v[96:99]
	v_mfma_f32_16x16x32_bf16 v[84:87], v[186:189], v[222:225], v[84:87]
	v_mfma_f32_16x16x32_bf16 v[80:83], v[194:197], v[222:225], v[80:83]
	v_mfma_f32_16x16x32_bf16 v[68:71], v[186:189], v[230:233], v[68:71]
	v_mfma_f32_16x16x32_bf16 v[64:67], v[194:197], v[230:233], v[64:67]
	s_barrier
; #define PG8_STAGE(bufoff, gbase, voff) do { const unsigned long long gb_ = (unsigned long long)(gbase); _Pragma("unroll") for (int _i = 0; _i < 2; ++_i) { unsigned keep_; \
;         asm volatile("s_mov_b32 m0, %2\n\ts_nop 0\n\tglobal_load_lds_dwordx4 %0, %1" : : "v"((voff)[_i]), "s"(gb_), "s"((unsigned)(size_t)(lds + (bufoff) + ldsw + _i * 8192)) : "memory", "m0"); (void)keep_; } } while (0)
; #define PG8_LDA(dst, b, h) do { _Pragma("unroll") for (int m = 0; m < 4; ++m) _Pragma("unroll") for (int k = 0; k < 2; ++k) dst[m][k] = *(const PG8_LAS bf16x8*)(lds + PG8_SA(b, h) + aoff + m * 2048 + k * 1024); } while (0)
; #define PG8_MMA(ai, bj, At, Bt) do { __builtin_amdgcn_s_setprio(1); _Pragma("unroll") for (int m = 0; m < 4; ++m) _Pragma("unroll") for (int n = 0; n < 2; ++n) _Pragma("unroll") for (int k = 0; k < 2; ++k) \
;         acc[ai][bj][m][n] = __builtin_amdgcn_mfma_f32_16x16x32_bf16(Bt[n][k], At[m][k], acc[ai][bj][m][n], 0, 0, 0); __builtin_amdgcn_s_setprio(0); } while (0)
; #define PG8_WAIT_V(n) asm volatile("s_waitcnt vmcnt(" #n ")" ::: "memory")
; #define PG8_WAIT_L(n) asm volatile("s_waitcnt lgkmcnt(" #n ")" ::: "memory")
; #define PG8_BAR __builtin_amdgcn_s_barrier()
; #define PG8_SCHED __builtin_amdgcn_sched_barrier(0)
; template <class Epi, class Sched, bool ALIGN_EPI = false, bool SP2 = false>
; __device__ __forceinline__ void gemm_phase(PG8_LAS unsigned char* lds, const Gemm g, const Sched& S, const Epi& E) {
;     ...
;         for (int t = 0; t < nt; t += 2) {
;     ...
;             PG8_LDA(At, 1, 1); PG8_STAGE(PG8_SB(1, 0), b3, voffB); PG8_STAGE(PG8_SB(1, 1), b3 + hstepB, voffB); PG8_STAGE(PG8_SA(1, 0), a3, voffA);
;             PG8_WAIT_V(8); PG8_WAIT_L(0); PG8_BAR; PG8_MMA(1, 0, At, B0); PG8_MMA(1, 1, At, B1); PG8_BAR; PG8_SCHED;
	ds_read_b128 v[202:205], v177 offset:49152
	ds_read_b128 v[206:209], v177 offset:50176
	ds_read_b128 v[210:213], v177 offset:51200
	ds_read_b128 v[214:217], v177 offset:52224
	ds_read_b128 v[218:221], v177 offset:53248
	ds_read_b128 v[222:225], v177 offset:54272
	ds_read_b128 v[226:229], v177 offset:55296
	ds_read_b128 v[230:233], v177 offset:56320
	s_add_u32 s48, s46, 0x80
	s_addc_u32 s49, s47, 0
	s_mov_b32 m0, s62
	s_nop 0
	global_load_lds_dwordx4 v172, s[48:49]
	s_add_u32 s46, s46, 0x80080
	s_mov_b32 m0, s63
	s_nop 0
	global_load_lds_dwordx4 v174, s[48:49]
	s_addc_u32 s47, s47, 0
	s_mov_b32 m0, s66
	s_nop 0
	global_load_lds_dwordx4 v172, s[46:47]
	s_nop 0
	s_mov_b32 m0, s67
	s_nop 0
	global_load_lds_dwordx4 v174, s[46:47]
	s_nop 0
	s_mov_b32 m0, s64
	s_nop 0
	global_load_lds_dwordx4 v139, s[42:43]
	s_nop 0
	s_mov_b32 m0, s65
	s_nop 0
	global_load_lds_dwordx4 v173, s[42:43]
	s_waitcnt vmcnt(8)
	s_waitcnt lgkmcnt(0)
	s_barrier
	v_mfma_f32_16x16x32_bf16 v[60:63], v[128:131], v[202:205], v[60:63]
	v_mfma_f32_16x16x32_bf16 v[56:59], v[162:165], v[202:205], v[56:59]
	v_mfma_f32_16x16x32_bf16 v[44:47], v[128:131], v[210:213], v[44:47]
	v_mfma_f32_16x16x32_bf16 v[40:43], v[162:165], v[210:213], v[40:43]
	v_mfma_f32_16x16x32_bf16 v[28:31], v[128:131], v[218:221], v[28:31]
	v_mfma_f32_16x16x32_bf16 v[24:27], v[162:165], v[218:221], v[24:27]
	v_mfma_f32_16x16x32_bf16 v[12:15], v[128:131], v[226:229], v[12:15]
	v_mfma_f32_16x16x32_bf16 v[8:11], v[162:165], v[226:229], v[8:11]
	v_mfma_f32_16x16x32_bf16 v[60:63], v[132:135], v[206:209], v[60:63]
	v_mfma_f32_16x16x32_bf16 v[56:59], v[166:169], v[206:209], v[56:59]
	v_mfma_f32_16x16x32_bf16 v[44:47], v[132:135], v[214:217], v[44:47]
	v_mfma_f32_16x16x32_bf16 v[40:43], v[166:169], v[214:217], v[40:43]
	v_mfma_f32_16x16x32_bf16 v[28:31], v[132:135], v[222:225], v[28:31]
	v_mfma_f32_16x16x32_bf16 v[24:27], v[166:169], v[222:225], v[24:27]
	v_mfma_f32_16x16x32_bf16 v[12:15], v[132:135], v[230:233], v[12:15]
	v_mfma_f32_16x16x32_bf16 v[8:11], v[166:169], v[230:233], v[8:11]
	v_mfma_f32_16x16x32_bf16 v[52:55], v[182:185], v[202:205], v[52:55]
	v_mfma_f32_16x16x32_bf16 v[48:51], v[190:193], v[202:205], v[48:51]
	v_mfma_f32_16x16x32_bf16 v[36:39], v[182:185], v[210:213], v[36:39]
	v_mfma_f32_16x16x32_bf16 v[32:35], v[190:193], v[210:213], v[32:35]
	v_mfma_f32_16x16x32_bf16 v[20:23], v[182:185], v[218:221], v[20:23]
	v_mfma_f32_16x16x32_bf16 v[16:19], v[190:193], v[218:221], v[16:19]
	v_mfma_f32_16x16x32_bf16 v[4:7], v[182:185], v[226:229], v[4:7]
	v_mfma_f32_16x16x32_bf16 v[0:3], v[190:193], v[226:229], v[0:3]
	v_mfma_f32_16x16x32_bf16 v[52:55], v[186:189], v[206:209], v[52:55]
	v_mfma_f32_16x16x32_bf16 v[48:51], v[194:197], v[206:209], v[48:51]
	v_mfma_f32_16x16x32_bf16 v[36:39], v[186:189], v[214:217], v[36:39]
	v_mfma_f32_16x16x32_bf16 v[32:35], v[194:197], v[214:217], v[32:35]
	v_mfma_f32_16x16x32_bf16 v[20:23], v[186:189], v[222:225], v[20:23]
	v_mfma_f32_16x16x32_bf16 v[16:19], v[194:197], v[222:225], v[16:19]
	v_mfma_f32_16x16x32_bf16 v[4:7], v[186:189], v[230:233], v[4:7]
	v_mfma_f32_16x16x32_bf16 v[0:3], v[194:197], v[230:233], v[0:3]
	s_barrier
	s_add_i32 s76, s76, 2
	s_add_i32 s77, s77, 0x10000
	s_cmp_gt_u32 s76, 29
	s_mov_b64 s[42:43], s[44:45]
	s_cbranch_scc0 .LBB0_1235
	s_and_b64 vcc, exec, s[28:29]
	s_cbranch_vccz .LBB0_1238
	s_barrier

; #define PG8_STAGE(bufoff, gbase, voff) do { const unsigned long long gb_ = (unsigned long long)(gbase); _Pragma("unroll") for (int _i = 0; _i < 2; ++_i) { unsigned keep_; \
;         asm volatile("s_mov_b32 m0, %2\n\ts_nop 0\n\tglobal_load_lds_dwordx4 %0, %1" : : "v"((voff)[_i]), "s"(gb_), "s"((unsigned)(size_t)(lds + (bufoff) + ldsw + _i * 8192)) : "memory", "m0"); (void)keep_; } } while (0)
; #define PG8_LDA(dst, b, h) do { _Pragma("unroll") for (int m = 0; m < 4; ++m) _Pragma("unroll") for (int k = 0; k < 2; ++k) dst[m][k] = *(const PG8_LAS bf16x8*)(lds + PG8_SA(b, h) + aoff + m * 2048 + k * 1024); } while (0)
; #define PG8_WAIT_V(n) asm volatile("s_waitcnt vmcnt(" #n ")" ::: "memory")
; template <class Epi, class Sched, bool ALIGN_EPI = false, bool SP2 = false>
; __device__ __forceinline__ void gemm_phase(PG8_LAS unsigned char* lds, const Gemm g, const Sched& S, const Epi& E) {
;     ...
;         for (int t = 0; t < nt; t += 2) {
;             const bool last = (t == nt - 2);
;     ...
;             const char* a1 = cA + PG8_KOFFA(t + 1);
;             const char* a2 = last ? nA : cA + PG8_KOFFA(t + 2); const char* b2 = last ? nB : cB + (size_t)(t + 2) * kstep;
;             const char* a3 = last ? nA + kstep : cA + PG8_KOFFA(t + 3); const char* b3 = b2 + kstep;
;     ...
;             if (last && has_next) S.a_ready(nxt);
;             if constexpr (SP2) {
;             PG8_LDB(B0, 0, 0); PG8_LDB(B1, 0, 1); PG8_SCHED; PG8_LDA(At, 0, 0); PG8_STAGE(PG8_SA(1, 1), a1 + hstepA, voffA);
;             PG8_WAIT_V(8); PG8_WAIT_L(0); PG8_BAR; PG8_MMA(0, 0, At, B0); PG8_MMA(0, 1, At, B1); PG8_BAR; PG8_SCHED;
;             PG8_LDA(At, 0, 1); PG8_STAGE(PG8_SB(0, 0), b2, voffB); PG8_STAGE(PG8_SB(0, 1), b2 + hstepB, voffB); PG8_STAGE(PG8_SA(0, 0), a2, voffA);
;             PG8_WAIT_V(8); PG8_WAIT_L(0); PG8_BAR; PG8_MMA(1, 0, At, B0); PG8_MMA(1, 1, At, B1); PG8_BAR; PG8_SCHED;
;             PG8_LDB(B0, 1, 0); PG8_LDB(B1, 1, 1); PG8_SCHED; PG8_LDA(At, 1, 0); PG8_STAGE(PG8_SA(0, 1), a2 + hstepA, voffA);
;             PG8_WAIT_V(8); PG8_WAIT_L(0); PG8_BAR; PG8_MMA(0, 0, At, B0); PG8_MMA(0, 1, At, B1); PG8_BAR; PG8_SCHED;
;             PG8_LDA(At, 1, 1); PG8_STAGE(PG8_SB(1, 0), b3, voffB); PG8_STAGE(PG8_SB(1, 1), b3 + hstepB, voffB); PG8_STAGE(PG8_SA(1, 0), a3, voffA);
;             PG8_WAIT_V(8); PG8_WAIT_L(0); PG8_BAR; PG8_MMA(1, 0, At, B0); PG8_MMA(1, 1, At, B1); PG8_BAR; PG8_SCHED;
.LBB0_1380:
	s_add_i32 s37, s71, 0xfffe8000
	s_and_b32 s36, s34, 0x100
	s_and_b32 s37, s37, 0xe0000
	s_or_b32 s36, s36, s37
	s_add_u32 s72, s8, s36
	s_addc_u32 s73, s9, 0
	s_add_u32 s36, s34, 0x100
	s_addc_u32 s37, s35, 0
	s_add_i32 s39, s71, 0xffff8000
	s_and_b32 s38, s36, 0x100
	s_and_b32 s39, s39, 0x1e0000
	s_or_b32 s38, s39, s38
	ds_read_b128 v[154:157], v167
	ds_read_b128 v[178:181], v167 offset:1024
	ds_read_b128 v[182:185], v167 offset:2048
	ds_read_b128 v[186:189], v167 offset:3072
	ds_read_b128 v[190:193], v169
	ds_read_b128 v[194:197], v169 offset:1024
	ds_read_b128 v[202:205], v169 offset:2048
	ds_read_b128 v[206:209], v169 offset:3072
	s_add_u32 s38, s8, s38
	s_addc_u32 s39, s9, 0
	s_add_u32 s76, s68, s34
	s_addc_u32 s35, s69, s35
	s_add_i32 s40, s34, 0x180
	s_and_b32 s40, s40, 0x180
	s_and_b32 s41, s71, 0x1e0000
	s_or_b32 s40, s41, s40
	s_add_u32 s77, s8, s40
	s_addc_u32 s78, s9, 0
	s_cmpk_eq_i32 s34, 0xf00
	s_cselect_b32 s41, s0, s39
	s_cselect_b32 s39, s21, s35
	s_cselect_b32 s35, s67, s78
	s_cselect_b32 s34, s29, s77
	s_cselect_b32 s40, s1, s38
	s_cselect_b32 s38, s23, s76
	ds_read_b128 v[210:213], v172
	ds_read_b128 v[214:217], v172 offset:1024
	ds_read_b128 v[218:221], v172 offset:2048
	ds_read_b128 v[222:225], v172 offset:3072
	ds_read_b128 v[226:229], v172 offset:4096
	ds_read_b128 v[230:233], v172 offset:5120
	ds_read_b128 v[234:237], v172 offset:6144
	ds_read_b128 v[238:241], v172 offset:7168
	s_add_u32 s72, s72, 0x10080
	s_addc_u32 s73, s73, 0
	s_mov_b32 m0, s61
	s_nop 0
	global_load_lds_dwordx4 v159, s[72:73]
	s_nop 0
	s_mov_b32 m0, s62
	s_nop 0
	global_load_lds_dwordx4 v163, s[72:73]
	s_waitcnt vmcnt(8)
	s_waitcnt lgkmcnt(0)
	s_barrier
	v_mfma_f32_16x16x32_bf16 v[124:127], v[154:157], v[210:213], v[124:127]
	v_mfma_f32_16x16x32_bf16 v[116:119], v[182:185], v[210:213], v[116:119]
	v_mfma_f32_16x16x32_bf16 v[108:111], v[154:157], v[218:221], v[108:111]
	v_mfma_f32_16x16x32_bf16 v[100:103], v[182:185], v[218:221], v[100:103]
	v_mfma_f32_16x16x32_bf16 v[92:95], v[154:157], v[226:229], v[92:95]
	v_mfma_f32_16x16x32_bf16 v[84:87], v[182:185], v[226:229], v[84:87]
	v_mfma_f32_16x16x32_bf16 v[76:79], v[154:157], v[234:237], v[76:79]
	v_mfma_f32_16x16x32_bf16 v[68:71], v[182:185], v[234:237], v[68:71]
	v_mfma_f32_16x16x32_bf16 v[124:127], v[178:181], v[214:217], v[124:127]
	v_mfma_f32_16x16x32_bf16 v[116:119], v[186:189], v[214:217], v[116:119]
	v_mfma_f32_16x16x32_bf16 v[108:111], v[178:181], v[222:225], v[108:111]
	v_mfma_f32_16x16x32_bf16 v[100:103], v[186:189], v[222:225], v[100:103]
	v_mfma_f32_16x16x32_bf16 v[92:95], v[178:181], v[230:233], v[92:95]
	v_mfma_f32_16x16x32_bf16 v[84:87], v[186:189], v[230:233], v[84:87]
	v_mfma_f32_16x16x32_bf16 v[76:79], v[178:181], v[238:241], v[76:79]
	v_mfma_f32_16x16x32_bf16 v[68:71], v[186:189], v[238:241], v[68:71]
	v_mfma_f32_16x16x32_bf16 v[120:123], v[190:193], v[210:213], v[120:123]
	v_mfma_f32_16x16x32_bf16 v[112:115], v[202:205], v[210:213], v[112:115]
	v_mfma_f32_16x16x32_bf16 v[104:107], v[190:193], v[218:221], v[104:107]
	v_mfma_f32_16x16x32_bf16 v[96:99], v[202:205], v[218:221], v[96:99]
	v_mfma_f32_16x16x32_bf16 v[88:91], v[190:193], v[226:229], v[88:91]
	v_mfma_f32_16x16x32_bf16 v[80:83], v[202:205], v[226:229], v[80:83]
	v_mfma_f32_16x16x32_bf16 v[72:75], v[190:193], v[234:237], v[72:75]
	v_mfma_f32_16x16x32_bf16 v[64:67], v[202:205], v[234:237], v[64:67]
	v_mfma_f32_16x16x32_bf16 v[120:123], v[194:197], v[214:217], v[120:123]
	v_mfma_f32_16x16x32_bf16 v[112:115], v[206:209], v[214:217], v[112:115]
	v_mfma_f32_16x16x32_bf16 v[104:107], v[194:197], v[222:225], v[104:107]
	v_mfma_f32_16x16x32_bf16 v[96:99], v[206:209], v[222:225], v[96:99]
	v_mfma_f32_16x16x32_bf16 v[88:91], v[194:197], v[230:233], v[88:91]
	v_mfma_f32_16x16x32_bf16 v[80:83], v[206:209], v[230:233], v[80:83]
	v_mfma_f32_16x16x32_bf16 v[72:75], v[194:197], v[238:241], v[72:75]
	v_mfma_f32_16x16x32_bf16 v[64:67], v[206:209], v[238:241], v[64:67]
	s_barrier
	ds_read_b128 v[210:213], v172 offset:16384
	ds_read_b128 v[214:217], v172 offset:17408
	ds_read_b128 v[218:221], v172 offset:18432
	ds_read_b128 v[222:225], v172 offset:19456
	ds_read_b128 v[226:229], v172 offset:20480
	ds_read_b128 v[230:233], v172 offset:21504
	ds_read_b128 v[234:237], v172 offset:22528
	ds_read_b128 v[238:241], v172 offset:23552
	s_mov_b32 m0, s45
	s_nop 0
	global_load_lds_dwordx4 v161, s[38:39]
	s_add_u32 s72, s38, 0x80000
	s_mov_b32 m0, s46
	s_nop 0
	global_load_lds_dwordx4 v165, s[38:39]
	s_addc_u32 s73, s39, 0
	s_mov_b32 m0, s47
	s_nop 0
	global_load_lds_dwordx4 v161, s[72:73]
	s_nop 0
	s_mov_b32 m0, s48
	s_nop 0
	global_load_lds_dwordx4 v165, s[72:73]
	s_nop 0
	s_mov_b32 m0, s31
	s_nop 0
	global_load_lds_dwordx4 v159, s[40:41]
	s_nop 0
	s_mov_b32 m0, s49
	s_nop 0
	global_load_lds_dwordx4 v163, s[40:41]
	s_waitcnt vmcnt(8)
	s_waitcnt lgkmcnt(0)
	s_barrier
; #define PG8_STAGE(bufoff, gbase, voff) do { const unsigned long long gb_ = (unsigned long long)(gbase); _Pragma("unroll") for (int _i = 0; _i < 2; ++_i) { unsigned keep_; \
;         asm volatile("s_mov_b32 m0, %2\n\ts_nop 0\n\tglobal_load_lds_dwordx4 %0, %1" : : "v"((voff)[_i]), "s"(gb_), "s"((unsigned)(size_t)(lds + (bufoff) + ldsw + _i * 8192)) : "memory", "m0"); (void)keep_; } } while (0)
; #define PG8_LDA(dst, b, h) do { _Pragma("unroll") for (int m = 0; m < 4; ++m) _Pragma("unroll") for (int k = 0; k < 2; ++k) dst[m][k] = *(const PG8_LAS bf16x8*)(lds + PG8_SA(b, h) + aoff + m * 2048 + k * 1024); } while (0)
; #define PG8_LDB(dst, b, h) do { _Pragma("unroll") for (int n = 0; n < 2; ++n) _Pragma("unroll") for (int k = 0; k < 2; ++k) dst[n][k] = *(const PG8_LAS bf16x8*)(lds + PG8_SB(b, h) + boff + n * 2048 + k * 1024); } while (0)
; #define PG8_MMA(ai, bj, At, Bt) do { __builtin_amdgcn_s_setprio(1); _Pragma("unroll") for (int m = 0; m < 4; ++m) _Pragma("unroll") for (int n = 0; n < 2; ++n) _Pragma("unroll") for (int k = 0; k < 2; ++k) \
;         acc[ai][bj][m][n] = __builtin_amdgcn_mfma_f32_16x16x32_bf16(Bt[n][k], At[m][k], acc[ai][bj][m][n], 0, 0, 0); __builtin_amdgcn_s_setprio(0); } while (0)
; #define PG8_WAIT_V(n) asm volatile("s_waitcnt vmcnt(" #n ")" ::: "memory")
; #define PG8_WAIT_L(n) asm volatile("s_waitcnt lgkmcnt(" #n ")" ::: "memory")
; #define PG8_BAR __builtin_amdgcn_s_barrier()
; #define PG8_SCHED __builtin_amdgcn_sched_barrier(0)
; template <class Epi, class Sched, bool ALIGN_EPI = false, bool SP2 = false>
; __device__ __forceinline__ void gemm_phase(PG8_LAS unsigned char* lds, const Gemm g, const Sched& S, const Epi& E) {
;     ...
;             PG8_WAIT_V(8); PG8_WAIT_L(0); PG8_BAR; PG8_MMA(1, 0, At, B0); PG8_MMA(1, 1, At, B1); PG8_BAR; PG8_SCHED;
;             PG8_LDB(B0, 1, 0); PG8_LDB(B1, 1, 1); PG8_SCHED; PG8_LDA(At, 1, 0); PG8_STAGE(PG8_SA(0, 1), a2 + hstepA, voffA);
;             PG8_WAIT_V(8); PG8_WAIT_L(0); PG8_BAR; PG8_MMA(0, 0, At, B0); PG8_MMA(0, 1, At, B1); PG8_BAR; PG8_SCHED;
;             PG8_LDA(At, 1, 1); PG8_STAGE(PG8_SB(1, 0), b3, voffB); PG8_STAGE(PG8_SB(1, 1), b3 + hstepB, voffB); PG8_STAGE(PG8_SA(1, 0), a3, voffA);
;             PG8_WAIT_V(8); PG8_WAIT_L(0); PG8_BAR; PG8_MMA(1, 0, At, B0); PG8_MMA(1, 1, At, B1); PG8_BAR; PG8_SCHED;
	v_mfma_f32_16x16x32_bf16 v[60:63], v[154:157], v[210:213], v[60:63]
	v_mfma_f32_16x16x32_bf16 v[52:55], v[182:185], v[210:213], v[52:55]
	v_mfma_f32_16x16x32_bf16 v[44:47], v[154:157], v[218:221], v[44:47]
	v_mfma_f32_16x16x32_bf16 v[36:39], v[182:185], v[218:221], v[36:39]
	v_mfma_f32_16x16x32_bf16 v[28:31], v[154:157], v[226:229], v[28:31]
	v_mfma_f32_16x16x32_bf16 v[20:23], v[182:185], v[226:229], v[20:23]
	v_mfma_f32_16x16x32_bf16 v[12:15], v[154:157], v[234:237], v[12:15]
	v_mfma_f32_16x16x32_bf16 v[4:7], v[182:185], v[234:237], v[4:7]
	v_mfma_f32_16x16x32_bf16 v[60:63], v[178:181], v[214:217], v[60:63]
	v_mfma_f32_16x16x32_bf16 v[52:55], v[186:189], v[214:217], v[52:55]
	v_mfma_f32_16x16x32_bf16 v[44:47], v[178:181], v[222:225], v[44:47]
	v_mfma_f32_16x16x32_bf16 v[36:39], v[186:189], v[222:225], v[36:39]
	v_mfma_f32_16x16x32_bf16 v[28:31], v[178:181], v[230:233], v[28:31]
	v_mfma_f32_16x16x32_bf16 v[20:23], v[186:189], v[230:233], v[20:23]
	v_mfma_f32_16x16x32_bf16 v[12:15], v[178:181], v[238:241], v[12:15]
	v_mfma_f32_16x16x32_bf16 v[4:7], v[186:189], v[238:241], v[4:7]
	v_mfma_f32_16x16x32_bf16 v[56:59], v[190:193], v[210:213], v[56:59]
	v_mfma_f32_16x16x32_bf16 v[48:51], v[202:205], v[210:213], v[48:51]
	v_mfma_f32_16x16x32_bf16 v[40:43], v[190:193], v[218:221], v[40:43]
	v_mfma_f32_16x16x32_bf16 v[32:35], v[202:205], v[218:221], v[32:35]
	v_mfma_f32_16x16x32_bf16 v[24:27], v[190:193], v[226:229], v[24:27]
	v_mfma_f32_16x16x32_bf16 v[16:19], v[202:205], v[226:229], v[16:19]
	v_mfma_f32_16x16x32_bf16 v[8:11], v[190:193], v[234:237], v[8:11]
	v_mfma_f32_16x16x32_bf16 v[0:3], v[202:205], v[234:237], v[0:3]
	v_mfma_f32_16x16x32_bf16 v[56:59], v[194:197], v[214:217], v[56:59]
	v_mfma_f32_16x16x32_bf16 v[48:51], v[206:209], v[214:217], v[48:51]
	v_mfma_f32_16x16x32_bf16 v[40:43], v[194:197], v[222:225], v[40:43]
	v_mfma_f32_16x16x32_bf16 v[32:35], v[206:209], v[222:225], v[32:35]
	v_mfma_f32_16x16x32_bf16 v[24:27], v[194:197], v[230:233], v[24:27]
	v_mfma_f32_16x16x32_bf16 v[16:19], v[206:209], v[230:233], v[16:19]
	v_mfma_f32_16x16x32_bf16 v[8:11], v[194:197], v[238:241], v[8:11]
	v_mfma_f32_16x16x32_bf16 v[0:3], v[206:209], v[238:241], v[0:3]
	s_barrier
	ds_read_b128 v[154:157], v173
	ds_read_b128 v[178:181], v173 offset:1024
	ds_read_b128 v[182:185], v173 offset:2048
	ds_read_b128 v[186:189], v173 offset:3072
	ds_read_b128 v[190:193], v174
	ds_read_b128 v[194:197], v174 offset:1024
	ds_read_b128 v[202:205], v174 offset:2048
	ds_read_b128 v[206:209], v174 offset:3072
	ds_read_b128 v[210:213], v172 offset:32768
	ds_read_b128 v[214:217], v172 offset:33792
	ds_read_b128 v[218:221], v172 offset:34816
	ds_read_b128 v[222:225], v172 offset:35840
	ds_read_b128 v[226:229], v172 offset:36864
	ds_read_b128 v[230:233], v172 offset:37888
	ds_read_b128 v[234:237], v172 offset:38912
	ds_read_b128 v[238:241], v172 offset:39936
	s_add_u32 s40, s40, 0x10000
	s_addc_u32 s41, s41, 0
	s_mov_b32 m0, s50
	s_nop 0
	global_load_lds_dwordx4 v159, s[40:41]
	s_nop 0
	s_mov_b32 m0, s51
	s_nop 0
	global_load_lds_dwordx4 v163, s[40:41]
	s_waitcnt vmcnt(8)
	s_waitcnt lgkmcnt(0)
	s_barrier
	v_mfma_f32_16x16x32_bf16 v[124:127], v[154:157], v[210:213], v[124:127]
	v_mfma_f32_16x16x32_bf16 v[116:119], v[182:185], v[210:213], v[116:119]
	v_mfma_f32_16x16x32_bf16 v[108:111], v[154:157], v[218:221], v[108:111]
	v_mfma_f32_16x16x32_bf16 v[100:103], v[182:185], v[218:221], v[100:103]
	v_mfma_f32_16x16x32_bf16 v[92:95], v[154:157], v[226:229], v[92:95]
	v_mfma_f32_16x16x32_bf16 v[84:87], v[182:185], v[226:229], v[84:87]
	v_mfma_f32_16x16x32_bf16 v[76:79], v[154:157], v[234:237], v[76:79]
	v_mfma_f32_16x16x32_bf16 v[68:71], v[182:185], v[234:237], v[68:71]
	v_mfma_f32_16x16x32_bf16 v[124:127], v[178:181], v[214:217], v[124:127]
	v_mfma_f32_16x16x32_bf16 v[116:119], v[186:189], v[214:217], v[116:119]
	v_mfma_f32_16x16x32_bf16 v[108:111], v[178:181], v[222:225], v[108:111]
	v_mfma_f32_16x16x32_bf16 v[100:103], v[186:189], v[222:225], v[100:103]
	v_mfma_f32_16x16x32_bf16 v[92:95], v[178:181], v[230:233], v[92:95]
	v_mfma_f32_16x16x32_bf16 v[84:87], v[186:189], v[230:233], v[84:87]
	v_mfma_f32_16x16x32_bf16 v[76:79], v[178:181], v[238:241], v[76:79]
	v_mfma_f32_16x16x32_bf16 v[68:71], v[186:189], v[238:241], v[68:71]
	v_mfma_f32_16x16x32_bf16 v[120:123], v[190:193], v[210:213], v[120:123]
	v_mfma_f32_16x16x32_bf16 v[112:115], v[202:205], v[210:213], v[112:115]
	v_mfma_f32_16x16x32_bf16 v[104:107], v[190:193], v[218:221], v[104:107]
	v_mfma_f32_16x16x32_bf16 v[96:99], v[202:205], v[218:221], v[96:99]
	v_mfma_f32_16x16x32_bf16 v[88:91], v[190:193], v[226:229], v[88:91]
	v_mfma_f32_16x16x32_bf16 v[80:83], v[202:205], v[226:229], v[80:83]
	v_mfma_f32_16x16x32_bf16 v[72:75], v[190:193], v[234:237], v[72:75]
	v_mfma_f32_16x16x32_bf16 v[64:67], v[202:205], v[234:237], v[64:67]
	v_mfma_f32_16x16x32_bf16 v[120:123], v[194:197], v[214:217], v[120:123]
	v_mfma_f32_16x16x32_bf16 v[112:115], v[206:209], v[214:217], v[112:115]
	v_mfma_f32_16x16x32_bf16 v[104:107], v[194:197], v[222:225], v[104:107]
	v_mfma_f32_16x16x32_bf16 v[96:99], v[206:209], v[222:225], v[96:99]
	v_mfma_f32_16x16x32_bf16 v[88:91], v[194:197], v[230:233], v[88:91]
	v_mfma_f32_16x16x32_bf16 v[80:83], v[206:209], v[230:233], v[80:83]
	v_mfma_f32_16x16x32_bf16 v[72:75], v[194:197], v[238:241], v[72:75]
	v_mfma_f32_16x16x32_bf16 v[64:67], v[206:209], v[238:241], v[64:67]
	s_barrier
; #define PG8_STAGE(bufoff, gbase, voff) do { const unsigned long long gb_ = (unsigned long long)(gbase); _Pragma("unroll") for (int _i = 0; _i < 2; ++_i) { unsigned keep_; \
;         asm volatile("s_mov_b32 m0, %2\n\ts_nop 0\n\tglobal_load_lds_dwordx4 %0, %1" : : "v"((voff)[_i]), "s"(gb_), "s"((unsigned)(size_t)(lds + (bufoff) + ldsw + _i * 8192)) : "memory", "m0"); (void)keep_; } } while (0)
; #define PG8_LDA(dst, b, h) do { _Pragma("unroll") for (int m = 0; m < 4; ++m) _Pragma("unroll") for (int k = 0; k < 2; ++k) dst[m][k] = *(const PG8_LAS bf16x8*)(lds + PG8_SA(b, h) + aoff + m * 2048 + k * 1024); } while (0)
; #define PG8_MMA(ai, bj, At, Bt) do { __builtin_amdgcn_s_setprio(1); _Pragma("unroll") for (int m = 0; m < 4; ++m) _Pragma("unroll") for (int n = 0; n < 2; ++n) _Pragma("unroll") for (int k = 0; k < 2; ++k) \
;         acc[ai][bj][m][n] = __builtin_amdgcn_mfma_f32_16x16x32_bf16(Bt[n][k], At[m][k], acc[ai][bj][m][n], 0, 0, 0); __builtin_amdgcn_s_setprio(0); } while (0)
; #define PG8_WAIT_V(n) asm volatile("s_waitcnt vmcnt(" #n ")" ::: "memory")
; #define PG8_WAIT_L(n) asm volatile("s_waitcnt lgkmcnt(" #n ")" ::: "memory")
; #define PG8_BAR __builtin_amdgcn_s_barrier()
; #define PG8_SCHED __builtin_amdgcn_sched_barrier(0)
; template <class Epi, class Sched, bool ALIGN_EPI = false, bool SP2 = false>
; __device__ __forceinline__ void gemm_phase(PG8_LAS unsigned char* lds, const Gemm g, const Sched& S, const Epi& E) {
;     ...
;         for (int t = 0; t < nt; t += 2) {
;     ...
;             PG8_LDA(At, 1, 1); PG8_STAGE(PG8_SB(1, 0), b3, voffB); PG8_STAGE(PG8_SB(1, 1), b3 + hstepB, voffB); PG8_STAGE(PG8_SA(1, 0), a3, voffA);
;             PG8_WAIT_V(8); PG8_WAIT_L(0); PG8_BAR; PG8_MMA(1, 0, At, B0); PG8_MMA(1, 1, At, B1); PG8_BAR; PG8_SCHED;
	ds_read_b128 v[210:213], v172 offset:49152
	ds_read_b128 v[214:217], v172 offset:50176
	ds_read_b128 v[218:221], v172 offset:51200
	ds_read_b128 v[222:225], v172 offset:52224
	ds_read_b128 v[226:229], v172 offset:53248
	ds_read_b128 v[230:233], v172 offset:54272
	ds_read_b128 v[234:237], v172 offset:55296
	ds_read_b128 v[238:241], v172 offset:56320
	s_add_u32 s40, s38, 0x80
	s_addc_u32 s41, s39, 0
	s_mov_b32 m0, s55
	s_nop 0
	global_load_lds_dwordx4 v161, s[40:41]
	s_add_u32 s38, s38, 0x80080
	s_mov_b32 m0, s56
	s_nop 0
	global_load_lds_dwordx4 v165, s[40:41]
	s_addc_u32 s39, s39, 0
	s_mov_b32 m0, s59
	s_nop 0
	global_load_lds_dwordx4 v161, s[38:39]
	s_nop 0
	s_mov_b32 m0, s60
	s_nop 0
	global_load_lds_dwordx4 v165, s[38:39]
	s_nop 0
	s_mov_b32 m0, s57
	s_nop 0
	global_load_lds_dwordx4 v159, s[34:35]
	s_nop 0
	s_mov_b32 m0, s58
	s_nop 0
	global_load_lds_dwordx4 v163, s[34:35]
	s_waitcnt vmcnt(8)
	s_waitcnt lgkmcnt(0)
	s_barrier
	v_mfma_f32_16x16x32_bf16 v[60:63], v[154:157], v[210:213], v[60:63]
	v_mfma_f32_16x16x32_bf16 v[52:55], v[182:185], v[210:213], v[52:55]
	v_mfma_f32_16x16x32_bf16 v[44:47], v[154:157], v[218:221], v[44:47]
	v_mfma_f32_16x16x32_bf16 v[36:39], v[182:185], v[218:221], v[36:39]
	v_mfma_f32_16x16x32_bf16 v[28:31], v[154:157], v[226:229], v[28:31]
	v_mfma_f32_16x16x32_bf16 v[20:23], v[182:185], v[226:229], v[20:23]
	v_mfma_f32_16x16x32_bf16 v[12:15], v[154:157], v[234:237], v[12:15]
	v_mfma_f32_16x16x32_bf16 v[4:7], v[182:185], v[234:237], v[4:7]
	v_mfma_f32_16x16x32_bf16 v[60:63], v[178:181], v[214:217], v[60:63]
	v_mfma_f32_16x16x32_bf16 v[52:55], v[186:189], v[214:217], v[52:55]
	v_mfma_f32_16x16x32_bf16 v[44:47], v[178:181], v[222:225], v[44:47]
	v_mfma_f32_16x16x32_bf16 v[36:39], v[186:189], v[222:225], v[36:39]
	v_mfma_f32_16x16x32_bf16 v[28:31], v[178:181], v[230:233], v[28:31]
	v_mfma_f32_16x16x32_bf16 v[20:23], v[186:189], v[230:233], v[20:23]
	v_mfma_f32_16x16x32_bf16 v[12:15], v[178:181], v[238:241], v[12:15]
	v_mfma_f32_16x16x32_bf16 v[4:7], v[186:189], v[238:241], v[4:7]
	v_mfma_f32_16x16x32_bf16 v[56:59], v[190:193], v[210:213], v[56:59]
	v_mfma_f32_16x16x32_bf16 v[48:51], v[202:205], v[210:213], v[48:51]
	v_mfma_f32_16x16x32_bf16 v[40:43], v[190:193], v[218:221], v[40:43]
	v_mfma_f32_16x16x32_bf16 v[32:35], v[202:205], v[218:221], v[32:35]
	v_mfma_f32_16x16x32_bf16 v[24:27], v[190:193], v[226:229], v[24:27]
	v_mfma_f32_16x16x32_bf16 v[16:19], v[202:205], v[226:229], v[16:19]
	v_mfma_f32_16x16x32_bf16 v[8:11], v[190:193], v[234:237], v[8:11]
	v_mfma_f32_16x16x32_bf16 v[0:3], v[202:205], v[234:237], v[0:3]
	v_mfma_f32_16x16x32_bf16 v[56:59], v[194:197], v[214:217], v[56:59]
	v_mfma_f32_16x16x32_bf16 v[48:51], v[206:209], v[214:217], v[48:51]
	v_mfma_f32_16x16x32_bf16 v[40:43], v[194:197], v[222:225], v[40:43]
	v_mfma_f32_16x16x32_bf16 v[32:35], v[206:209], v[222:225], v[32:35]
	v_mfma_f32_16x16x32_bf16 v[24:27], v[194:197], v[230:233], v[24:27]
	v_mfma_f32_16x16x32_bf16 v[16:19], v[206:209], v[230:233], v[16:19]
	v_mfma_f32_16x16x32_bf16 v[8:11], v[194:197], v[238:241], v[8:11]
	v_mfma_f32_16x16x32_bf16 v[0:3], v[206:209], v[238:241], v[0:3]
	s_barrier
	s_add_i32 s70, s70, 2
	s_add_i32 s71, s71, 0x10000
	s_cmp_gt_u32 s70, 29
	s_mov_b64 s[34:35], s[36:37]
	s_cbranch_scc0 .LBB0_1380
	s_and_b64 vcc, exec, s[18:19]
	s_cbranch_vccz .LBB0_1383
	s_barrier

; #define PG8_STAGE(bufoff, gbase, voff) do { const unsigned long long gb_ = (unsigned long long)(gbase); _Pragma("unroll") for (int _i = 0; _i < 2; ++_i) { unsigned keep_; \
;         asm volatile("s_mov_b32 m0, %2\n\ts_nop 0\n\tglobal_load_lds_dwordx4 %0, %1" : : "v"((voff)[_i]), "s"(gb_), "s"((unsigned)(size_t)(lds + (bufoff) + ldsw + _i * 8192)) : "memory", "m0"); (void)keep_; } } while (0)
; #define PG8_LDA(dst, b, h) do { _Pragma("unroll") for (int m = 0; m < 4; ++m) _Pragma("unroll") for (int k = 0; k < 2; ++k) dst[m][k] = *(const PG8_LAS bf16x8*)(lds + PG8_SA(b, h) + aoff + m * 2048 + k * 1024); } while (0)
; #define PG8_WAIT_V(n) asm volatile("s_waitcnt vmcnt(" #n ")" ::: "memory")
; template <class Epi, class Sched, bool ALIGN_EPI = false, bool SP2 = false>
; __device__ __forceinline__ void gemm_phase(PG8_LAS unsigned char* lds, const Gemm g, const Sched& S, const Epi& E) {
;     ...
;         for (int t = 0; t < nt; t += 2) {
;             const bool last = (t == nt - 2);
;     ...
;             const char* a1 = cA + PG8_KOFFA(t + 1);
;             const char* a2 = last ? nA : cA + PG8_KOFFA(t + 2); const char* b2 = last ? nB : cB + (size_t)(t + 2) * kstep;
;             const char* a3 = last ? nA + kstep : cA + PG8_KOFFA(t + 3); const char* b3 = b2 + kstep;
;     ...
;             if (last && has_next) S.a_ready(nxt);
;             if constexpr (SP2) {
;             PG8_LDB(B0, 0, 0); PG8_LDB(B1, 0, 1); PG8_SCHED; PG8_LDA(At, 0, 0); PG8_STAGE(PG8_SA(1, 1), a1 + hstepA, voffA);
;             PG8_WAIT_V(8); PG8_WAIT_L(0); PG8_BAR; PG8_MMA(0, 0, At, B0); PG8_MMA(0, 1, At, B1); PG8_BAR; PG8_SCHED;
;             PG8_LDA(At, 0, 1); PG8_STAGE(PG8_SB(0, 0), b2, voffB); PG8_STAGE(PG8_SB(0, 1), b2 + hstepB, voffB); PG8_STAGE(PG8_SA(0, 0), a2, voffA);
;             PG8_WAIT_V(8); PG8_WAIT_L(0); PG8_BAR; PG8_MMA(1, 0, At, B0); PG8_MMA(1, 1, At, B1); PG8_BAR; PG8_SCHED;
;             PG8_LDB(B0, 1, 0); PG8_LDB(B1, 1, 1); PG8_SCHED; PG8_LDA(At, 1, 0); PG8_STAGE(PG8_SA(0, 1), a2 + hstepA, voffA);
;             PG8_WAIT_V(8); PG8_WAIT_L(0); PG8_BAR; PG8_MMA(0, 0, At, B0); PG8_MMA(0, 1, At, B1); PG8_BAR; PG8_SCHED;
;             PG8_LDA(At, 1, 1); PG8_STAGE(PG8_SB(1, 0), b3, voffB); PG8_STAGE(PG8_SB(1, 1), b3 + hstepB, voffB); PG8_STAGE(PG8_SA(1, 0), a3, voffA);
;             PG8_WAIT_V(8); PG8_WAIT_L(0); PG8_BAR; PG8_MMA(1, 0, At, B0); PG8_MMA(1, 1, At, B1); PG8_BAR; PG8_SCHED;
.LBB0_1630:
	s_add_i32 s78, s46, 2
	s_lshr_b32 s20, s78, 2
	s_lshl_b64 s[48:49], s[20:21], 17
	s_add_i32 s20, s44, 0xffffff00
	s_and_b32 s20, s20, 0x100
	s_add_u32 s47, s42, s48
	s_addc_u32 s48, s43, s49
	s_add_u32 s79, s47, s20
	s_addc_u32 s81, s48, 0
	s_add_i32 s20, s46, 4
	s_lshr_b32 s20, s20, 2
	s_lshl_b64 s[48:49], s[20:21], 17
	s_and_b32 s20, s44, 0x100
	s_add_u32 s47, s42, s48
	s_addc_u32 s48, s43, s49
	s_add_u32 s47, s47, s20
	s_addc_u32 s50, s48, 0
	s_add_u32 s80, s40, s44
	ds_read_b128 v[128:131], v173
	ds_read_b128 v[132:135], v173 offset:1024
	ds_read_b128 v[136:139], v173 offset:2048
	ds_read_b128 v[140:143], v173 offset:3072
	ds_read_b128 v[156:159], v174
	ds_read_b128 v[162:165], v174 offset:1024
	ds_read_b128 v[180:183], v174 offset:2048
	ds_read_b128 v[184:187], v174 offset:3072
	s_addc_u32 s82, s41, s45
	s_add_i32 s20, s46, 5
	s_lshr_b32 s20, s20, 2
	s_lshl_b64 s[48:49], s[20:21], 17
	s_add_i32 s20, s44, 0x80
	s_and_b32 s20, s20, 0x180
	s_add_u32 s48, s42, s48
	s_addc_u32 s49, s43, s49
	s_add_u32 s20, s48, s20
	s_addc_u32 s83, s49, 0
	s_cmp_eq_u32 s46, 28
	s_cselect_b32 s46, s31, s20
	s_cselect_b32 s51, s0, s50
	s_cselect_b32 s50, s1, s47
	s_cselect_b32 s49, s9, s82
	s_cselect_b32 s48, s29, s80
	s_cselect_b32 s47, s77, s83
	ds_read_b128 v[188:191], v175
	ds_read_b128 v[192:195], v175 offset:1024
	ds_read_b128 v[196:199], v175 offset:2048
	ds_read_b128 v[202:205], v175 offset:3072
	ds_read_b128 v[206:209], v175 offset:4096
	ds_read_b128 v[210:213], v175 offset:5120
	ds_read_b128 v[214:217], v175 offset:6144
	ds_read_b128 v[218:221], v175 offset:7168
	s_add_u32 s80, s79, 0x10080
	s_addc_u32 s81, s81, 0
	s_mov_b32 m0, s68
	s_nop 0
	global_load_lds_dwordx4 v149, s[80:81]
	s_nop 0
	s_mov_b32 m0, s69
	s_nop 0
	global_load_lds_dwordx4 v167, s[80:81]
	s_waitcnt vmcnt(8)
	s_waitcnt lgkmcnt(0)
	s_barrier
	v_mfma_f32_16x16x32_bf16 v[124:127], v[128:131], v[188:191], v[124:127]
	v_mfma_f32_16x16x32_bf16 v[120:123], v[136:139], v[188:191], v[120:123]
	v_mfma_f32_16x16x32_bf16 v[112:115], v[128:131], v[196:199], v[112:115]
	v_mfma_f32_16x16x32_bf16 v[104:107], v[136:139], v[196:199], v[104:107]
	v_mfma_f32_16x16x32_bf16 v[96:99], v[128:131], v[206:209], v[96:99]
	v_mfma_f32_16x16x32_bf16 v[88:91], v[136:139], v[206:209], v[88:91]
	v_mfma_f32_16x16x32_bf16 v[80:83], v[128:131], v[214:217], v[80:83]
	v_mfma_f32_16x16x32_bf16 v[72:75], v[136:139], v[214:217], v[72:75]
	v_mfma_f32_16x16x32_bf16 v[124:127], v[132:135], v[192:195], v[124:127]
	v_mfma_f32_16x16x32_bf16 v[120:123], v[140:143], v[192:195], v[120:123]
	v_mfma_f32_16x16x32_bf16 v[112:115], v[132:135], v[202:205], v[112:115]
	v_mfma_f32_16x16x32_bf16 v[104:107], v[140:143], v[202:205], v[104:107]
	v_mfma_f32_16x16x32_bf16 v[96:99], v[132:135], v[210:213], v[96:99]
	v_mfma_f32_16x16x32_bf16 v[88:91], v[140:143], v[210:213], v[88:91]
	v_mfma_f32_16x16x32_bf16 v[80:83], v[132:135], v[218:221], v[80:83]
	v_mfma_f32_16x16x32_bf16 v[72:75], v[140:143], v[218:221], v[72:75]
	v_mfma_f32_16x16x32_bf16 v[116:119], v[156:159], v[188:191], v[116:119]
	v_mfma_f32_16x16x32_bf16 v[108:111], v[180:183], v[188:191], v[108:111]
	v_mfma_f32_16x16x32_bf16 v[100:103], v[156:159], v[196:199], v[100:103]
	v_mfma_f32_16x16x32_bf16 v[92:95], v[180:183], v[196:199], v[92:95]
	v_mfma_f32_16x16x32_bf16 v[84:87], v[156:159], v[206:209], v[84:87]
	v_mfma_f32_16x16x32_bf16 v[76:79], v[180:183], v[206:209], v[76:79]
	v_mfma_f32_16x16x32_bf16 v[68:71], v[156:159], v[214:217], v[68:71]
	v_mfma_f32_16x16x32_bf16 v[64:67], v[180:183], v[214:217], v[64:67]
	v_mfma_f32_16x16x32_bf16 v[116:119], v[162:165], v[192:195], v[116:119]
	v_mfma_f32_16x16x32_bf16 v[108:111], v[184:187], v[192:195], v[108:111]
	v_mfma_f32_16x16x32_bf16 v[100:103], v[162:165], v[202:205], v[100:103]
	v_mfma_f32_16x16x32_bf16 v[92:95], v[184:187], v[202:205], v[92:95]
	v_mfma_f32_16x16x32_bf16 v[84:87], v[162:165], v[210:213], v[84:87]
	v_mfma_f32_16x16x32_bf16 v[76:79], v[184:187], v[210:213], v[76:79]
	v_mfma_f32_16x16x32_bf16 v[68:71], v[162:165], v[218:221], v[68:71]
	v_mfma_f32_16x16x32_bf16 v[64:67], v[184:187], v[218:221], v[64:67]
	s_barrier
	ds_read_b128 v[188:191], v175 offset:16384
	ds_read_b128 v[192:195], v175 offset:17408
	ds_read_b128 v[196:199], v175 offset:18432
	ds_read_b128 v[202:205], v175 offset:19456
	ds_read_b128 v[206:209], v175 offset:20480
	ds_read_b128 v[210:213], v175 offset:21504
	ds_read_b128 v[214:217], v175 offset:22528
	ds_read_b128 v[218:221], v175 offset:23552
	s_mov_b32 m0, s55
	s_nop 0
	global_load_lds_dwordx4 v161, s[48:49]
	s_add_u32 s80, s48, 0x80000
	s_mov_b32 m0, s56
	s_nop 0
	global_load_lds_dwordx4 v169, s[48:49]
	s_addc_u32 s81, s49, 0
	s_mov_b32 m0, s57
	s_nop 0
	global_load_lds_dwordx4 v161, s[80:81]
	s_nop 0
	s_mov_b32 m0, s58
	s_nop 0
	global_load_lds_dwordx4 v169, s[80:81]
	s_nop 0
	s_mov_b32 m0, s39
	s_nop 0
	global_load_lds_dwordx4 v149, s[50:51]
	s_nop 0
	s_mov_b32 m0, s59
	s_nop 0
	global_load_lds_dwordx4 v167, s[50:51]
	s_waitcnt vmcnt(8)
	s_waitcnt lgkmcnt(0)
	s_barrier
; #define PG8_STAGE(bufoff, gbase, voff) do { const unsigned long long gb_ = (unsigned long long)(gbase); _Pragma("unroll") for (int _i = 0; _i < 2; ++_i) { unsigned keep_; \
;         asm volatile("s_mov_b32 m0, %2\n\ts_nop 0\n\tglobal_load_lds_dwordx4 %0, %1" : : "v"((voff)[_i]), "s"(gb_), "s"((unsigned)(size_t)(lds + (bufoff) + ldsw + _i * 8192)) : "memory", "m0"); (void)keep_; } } while (0)
; #define PG8_LDA(dst, b, h) do { _Pragma("unroll") for (int m = 0; m < 4; ++m) _Pragma("unroll") for (int k = 0; k < 2; ++k) dst[m][k] = *(const PG8_LAS bf16x8*)(lds + PG8_SA(b, h) + aoff + m * 2048 + k * 1024); } while (0)
; #define PG8_LDB(dst, b, h) do { _Pragma("unroll") for (int n = 0; n < 2; ++n) _Pragma("unroll") for (int k = 0; k < 2; ++k) dst[n][k] = *(const PG8_LAS bf16x8*)(lds + PG8_SB(b, h) + boff + n * 2048 + k * 1024); } while (0)
; #define PG8_MMA(ai, bj, At, Bt) do { __builtin_amdgcn_s_setprio(1); _Pragma("unroll") for (int m = 0; m < 4; ++m) _Pragma("unroll") for (int n = 0; n < 2; ++n) _Pragma("unroll") for (int k = 0; k < 2; ++k) \
;         acc[ai][bj][m][n] = __builtin_amdgcn_mfma_f32_16x16x32_bf16(Bt[n][k], At[m][k], acc[ai][bj][m][n], 0, 0, 0); __builtin_amdgcn_s_setprio(0); } while (0)
; #define PG8_WAIT_V(n) asm volatile("s_waitcnt vmcnt(" #n ")" ::: "memory")
; #define PG8_WAIT_L(n) asm volatile("s_waitcnt lgkmcnt(" #n ")" ::: "memory")
; #define PG8_BAR __builtin_amdgcn_s_barrier()
; #define PG8_SCHED __builtin_amdgcn_sched_barrier(0)
; template <class Epi, class Sched, bool ALIGN_EPI = false, bool SP2 = false>
; __device__ __forceinline__ void gemm_phase(PG8_LAS unsigned char* lds, const Gemm g, const Sched& S, const Epi& E) {
;     ...
;             PG8_WAIT_V(8); PG8_WAIT_L(0); PG8_BAR; PG8_MMA(1, 0, At, B0); PG8_MMA(1, 1, At, B1); PG8_BAR; PG8_SCHED;
;             PG8_LDB(B0, 1, 0); PG8_LDB(B1, 1, 1); PG8_SCHED; PG8_LDA(At, 1, 0); PG8_STAGE(PG8_SA(0, 1), a2 + hstepA, voffA);
;             PG8_WAIT_V(8); PG8_WAIT_L(0); PG8_BAR; PG8_MMA(0, 0, At, B0); PG8_MMA(0, 1, At, B1); PG8_BAR; PG8_SCHED;
;             PG8_LDA(At, 1, 1); PG8_STAGE(PG8_SB(1, 0), b3, voffB); PG8_STAGE(PG8_SB(1, 1), b3 + hstepB, voffB); PG8_STAGE(PG8_SA(1, 0), a3, voffA);
;             PG8_WAIT_V(8); PG8_WAIT_L(0); PG8_BAR; PG8_MMA(1, 0, At, B0); PG8_MMA(1, 1, At, B1); PG8_BAR; PG8_SCHED;
	v_mfma_f32_16x16x32_bf16 v[60:63], v[128:131], v[188:191], v[60:63]
	v_mfma_f32_16x16x32_bf16 v[56:59], v[136:139], v[188:191], v[56:59]
	v_mfma_f32_16x16x32_bf16 v[48:51], v[128:131], v[196:199], v[48:51]
	v_mfma_f32_16x16x32_bf16 v[40:43], v[136:139], v[196:199], v[40:43]
	v_mfma_f32_16x16x32_bf16 v[32:35], v[128:131], v[206:209], v[32:35]
	v_mfma_f32_16x16x32_bf16 v[24:27], v[136:139], v[206:209], v[24:27]
	v_mfma_f32_16x16x32_bf16 v[16:19], v[128:131], v[214:217], v[16:19]
	v_mfma_f32_16x16x32_bf16 v[8:11], v[136:139], v[214:217], v[8:11]
	v_mfma_f32_16x16x32_bf16 v[60:63], v[132:135], v[192:195], v[60:63]
	v_mfma_f32_16x16x32_bf16 v[56:59], v[140:143], v[192:195], v[56:59]
	v_mfma_f32_16x16x32_bf16 v[48:51], v[132:135], v[202:205], v[48:51]
	v_mfma_f32_16x16x32_bf16 v[40:43], v[140:143], v[202:205], v[40:43]
	v_mfma_f32_16x16x32_bf16 v[32:35], v[132:135], v[210:213], v[32:35]
	v_mfma_f32_16x16x32_bf16 v[24:27], v[140:143], v[210:213], v[24:27]
	v_mfma_f32_16x16x32_bf16 v[16:19], v[132:135], v[218:221], v[16:19]
	v_mfma_f32_16x16x32_bf16 v[8:11], v[140:143], v[218:221], v[8:11]
	v_mfma_f32_16x16x32_bf16 v[52:55], v[156:159], v[188:191], v[52:55]
	v_mfma_f32_16x16x32_bf16 v[44:47], v[180:183], v[188:191], v[44:47]
	v_mfma_f32_16x16x32_bf16 v[36:39], v[156:159], v[196:199], v[36:39]
	v_mfma_f32_16x16x32_bf16 v[28:31], v[180:183], v[196:199], v[28:31]
	v_mfma_f32_16x16x32_bf16 v[20:23], v[156:159], v[206:209], v[20:23]
	v_mfma_f32_16x16x32_bf16 v[12:15], v[180:183], v[206:209], v[12:15]
	v_mfma_f32_16x16x32_bf16 v[4:7], v[156:159], v[214:217], v[4:7]
	v_mfma_f32_16x16x32_bf16 v[0:3], v[180:183], v[214:217], v[0:3]
	v_mfma_f32_16x16x32_bf16 v[52:55], v[162:165], v[192:195], v[52:55]
	v_mfma_f32_16x16x32_bf16 v[44:47], v[184:187], v[192:195], v[44:47]
	v_mfma_f32_16x16x32_bf16 v[36:39], v[162:165], v[202:205], v[36:39]
	v_mfma_f32_16x16x32_bf16 v[28:31], v[184:187], v[202:205], v[28:31]
	v_mfma_f32_16x16x32_bf16 v[20:23], v[162:165], v[210:213], v[20:23]
	v_mfma_f32_16x16x32_bf16 v[12:15], v[184:187], v[210:213], v[12:15]
	v_mfma_f32_16x16x32_bf16 v[4:7], v[162:165], v[218:221], v[4:7]
	v_mfma_f32_16x16x32_bf16 v[0:3], v[184:187], v[218:221], v[0:3]
	s_barrier
	ds_read_b128 v[128:131], v176
	ds_read_b128 v[132:135], v176 offset:1024
	ds_read_b128 v[136:139], v176 offset:2048
	ds_read_b128 v[140:143], v176 offset:3072
	ds_read_b128 v[156:159], v177
	ds_read_b128 v[162:165], v177 offset:1024
	ds_read_b128 v[180:183], v177 offset:2048
	ds_read_b128 v[184:187], v177 offset:3072
	ds_read_b128 v[188:191], v175 offset:32768
	ds_read_b128 v[192:195], v175 offset:33792
	ds_read_b128 v[196:199], v175 offset:34816
	ds_read_b128 v[202:205], v175 offset:35840
	ds_read_b128 v[206:209], v175 offset:36864
	ds_read_b128 v[210:213], v175 offset:37888
	ds_read_b128 v[214:217], v175 offset:38912
	ds_read_b128 v[218:221], v175 offset:39936
	s_add_u32 s50, s50, 0x10000
	s_addc_u32 s51, s51, 0
	s_mov_b32 m0, s60
	s_nop 0
	global_load_lds_dwordx4 v149, s[50:51]
	s_nop 0
	s_mov_b32 m0, s61
	s_nop 0
	global_load_lds_dwordx4 v167, s[50:51]
	s_waitcnt vmcnt(8)
	s_waitcnt lgkmcnt(0)
	s_barrier
	v_mfma_f32_16x16x32_bf16 v[124:127], v[128:131], v[188:191], v[124:127]
	v_mfma_f32_16x16x32_bf16 v[120:123], v[136:139], v[188:191], v[120:123]
	v_mfma_f32_16x16x32_bf16 v[112:115], v[128:131], v[196:199], v[112:115]
	v_mfma_f32_16x16x32_bf16 v[104:107], v[136:139], v[196:199], v[104:107]
	v_mfma_f32_16x16x32_bf16 v[96:99], v[128:131], v[206:209], v[96:99]
	v_mfma_f32_16x16x32_bf16 v[88:91], v[136:139], v[206:209], v[88:91]
	v_mfma_f32_16x16x32_bf16 v[80:83], v[128:131], v[214:217], v[80:83]
	v_mfma_f32_16x16x32_bf16 v[72:75], v[136:139], v[214:217], v[72:75]
	v_mfma_f32_16x16x32_bf16 v[124:127], v[132:135], v[192:195], v[124:127]
	v_mfma_f32_16x16x32_bf16 v[120:123], v[140:143], v[192:195], v[120:123]
	v_mfma_f32_16x16x32_bf16 v[112:115], v[132:135], v[202:205], v[112:115]
	v_mfma_f32_16x16x32_bf16 v[104:107], v[140:143], v[202:205], v[104:107]
	v_mfma_f32_16x16x32_bf16 v[96:99], v[132:135], v[210:213], v[96:99]
	v_mfma_f32_16x16x32_bf16 v[88:91], v[140:143], v[210:213], v[88:91]
	v_mfma_f32_16x16x32_bf16 v[80:83], v[132:135], v[218:221], v[80:83]
	v_mfma_f32_16x16x32_bf16 v[72:75], v[140:143], v[218:221], v[72:75]
	v_mfma_f32_16x16x32_bf16 v[116:119], v[156:159], v[188:191], v[116:119]
	v_mfma_f32_16x16x32_bf16 v[108:111], v[180:183], v[188:191], v[108:111]
	v_mfma_f32_16x16x32_bf16 v[100:103], v[156:159], v[196:199], v[100:103]
	v_mfma_f32_16x16x32_bf16 v[92:95], v[180:183], v[196:199], v[92:95]
	v_mfma_f32_16x16x32_bf16 v[84:87], v[156:159], v[206:209], v[84:87]
	v_mfma_f32_16x16x32_bf16 v[76:79], v[180:183], v[206:209], v[76:79]
	v_mfma_f32_16x16x32_bf16 v[68:71], v[156:159], v[214:217], v[68:71]
	v_mfma_f32_16x16x32_bf16 v[64:67], v[180:183], v[214:217], v[64:67]
	v_mfma_f32_16x16x32_bf16 v[116:119], v[162:165], v[192:195], v[116:119]
	v_mfma_f32_16x16x32_bf16 v[108:111], v[184:187], v[192:195], v[108:111]
	v_mfma_f32_16x16x32_bf16 v[100:103], v[162:165], v[202:205], v[100:103]
	v_mfma_f32_16x16x32_bf16 v[92:95], v[184:187], v[202:205], v[92:95]
	v_mfma_f32_16x16x32_bf16 v[84:87], v[162:165], v[210:213], v[84:87]
	v_mfma_f32_16x16x32_bf16 v[76:79], v[184:187], v[210:213], v[76:79]
	v_mfma_f32_16x16x32_bf16 v[68:71], v[162:165], v[218:221], v[68:71]
	v_mfma_f32_16x16x32_bf16 v[64:67], v[184:187], v[218:221], v[64:67]
	s_barrier
; #define PG8_STAGE(bufoff, gbase, voff) do { const unsigned long long gb_ = (unsigned long long)(gbase); _Pragma("unroll") for (int _i = 0; _i < 2; ++_i) { unsigned keep_; \
;         asm volatile("s_mov_b32 m0, %2\n\ts_nop 0\n\tglobal_load_lds_dwordx4 %0, %1" : : "v"((voff)[_i]), "s"(gb_), "s"((unsigned)(size_t)(lds + (bufoff) + ldsw + _i * 8192)) : "memory", "m0"); (void)keep_; } } while (0)
; #define PG8_LDA(dst, b, h) do { _Pragma("unroll") for (int m = 0; m < 4; ++m) _Pragma("unroll") for (int k = 0; k < 2; ++k) dst[m][k] = *(const PG8_LAS bf16x8*)(lds + PG8_SA(b, h) + aoff + m * 2048 + k * 1024); } while (0)
; #define PG8_MMA(ai, bj, At, Bt) do { __builtin_amdgcn_s_setprio(1); _Pragma("unroll") for (int m = 0; m < 4; ++m) _Pragma("unroll") for (int n = 0; n < 2; ++n) _Pragma("unroll") for (int k = 0; k < 2; ++k) \
;         acc[ai][bj][m][n] = __builtin_amdgcn_mfma_f32_16x16x32_bf16(Bt[n][k], At[m][k], acc[ai][bj][m][n], 0, 0, 0); __builtin_amdgcn_s_setprio(0); } while (0)
; #define PG8_WAIT_V(n) asm volatile("s_waitcnt vmcnt(" #n ")" ::: "memory")
; #define PG8_WAIT_L(n) asm volatile("s_waitcnt lgkmcnt(" #n ")" ::: "memory")
; #define PG8_BAR __builtin_amdgcn_s_barrier()
; #define PG8_SCHED __builtin_amdgcn_sched_barrier(0)
; template <class Epi, class Sched, bool ALIGN_EPI = false, bool SP2 = false>
; __device__ __forceinline__ void gemm_phase(PG8_LAS unsigned char* lds, const Gemm g, const Sched& S, const Epi& E) {
;     ...
;         for (int t = 0; t < nt; t += 2) {
;     ...
;             PG8_LDA(At, 1, 1); PG8_STAGE(PG8_SB(1, 0), b3, voffB); PG8_STAGE(PG8_SB(1, 1), b3 + hstepB, voffB); PG8_STAGE(PG8_SA(1, 0), a3, voffA);
;             PG8_WAIT_V(8); PG8_WAIT_L(0); PG8_BAR; PG8_MMA(1, 0, At, B0); PG8_MMA(1, 1, At, B1); PG8_BAR; PG8_SCHED;
	ds_read_b128 v[188:191], v175 offset:49152
	ds_read_b128 v[192:195], v175 offset:50176
	ds_read_b128 v[196:199], v175 offset:51200
	ds_read_b128 v[202:205], v175 offset:52224
	ds_read_b128 v[206:209], v175 offset:53248
	ds_read_b128 v[210:213], v175 offset:54272
	ds_read_b128 v[214:217], v175 offset:55296
	ds_read_b128 v[218:221], v175 offset:56320
	s_add_u32 s50, s48, 0x80
	s_addc_u32 s51, s49, 0
	s_mov_b32 m0, s62
	s_nop 0
	global_load_lds_dwordx4 v161, s[50:51]
	s_add_u32 s48, s48, 0x80080
	s_mov_b32 m0, s63
	s_nop 0
	global_load_lds_dwordx4 v169, s[50:51]
	s_addc_u32 s49, s49, 0
	s_mov_b32 m0, s66
	s_nop 0
	global_load_lds_dwordx4 v161, s[48:49]
	s_nop 0
	s_mov_b32 m0, s67
	s_nop 0
	global_load_lds_dwordx4 v169, s[48:49]
	s_nop 0
	s_mov_b32 m0, s64
	s_nop 0
	global_load_lds_dwordx4 v149, s[46:47]
	s_nop 0
	s_mov_b32 m0, s65
	s_nop 0
	global_load_lds_dwordx4 v167, s[46:47]
	s_waitcnt vmcnt(8)
	s_waitcnt lgkmcnt(0)
	s_barrier
	v_mfma_f32_16x16x32_bf16 v[60:63], v[128:131], v[188:191], v[60:63]
	v_mfma_f32_16x16x32_bf16 v[56:59], v[136:139], v[188:191], v[56:59]
	v_mfma_f32_16x16x32_bf16 v[48:51], v[128:131], v[196:199], v[48:51]
	v_mfma_f32_16x16x32_bf16 v[40:43], v[136:139], v[196:199], v[40:43]
	v_mfma_f32_16x16x32_bf16 v[32:35], v[128:131], v[206:209], v[32:35]
	v_mfma_f32_16x16x32_bf16 v[24:27], v[136:139], v[206:209], v[24:27]
	v_mfma_f32_16x16x32_bf16 v[16:19], v[128:131], v[214:217], v[16:19]
	v_mfma_f32_16x16x32_bf16 v[8:11], v[136:139], v[214:217], v[8:11]
	v_mfma_f32_16x16x32_bf16 v[60:63], v[132:135], v[192:195], v[60:63]
	v_mfma_f32_16x16x32_bf16 v[56:59], v[140:143], v[192:195], v[56:59]
	v_mfma_f32_16x16x32_bf16 v[48:51], v[132:135], v[202:205], v[48:51]
	v_mfma_f32_16x16x32_bf16 v[40:43], v[140:143], v[202:205], v[40:43]
	v_mfma_f32_16x16x32_bf16 v[32:35], v[132:135], v[210:213], v[32:35]
	v_mfma_f32_16x16x32_bf16 v[24:27], v[140:143], v[210:213], v[24:27]
	v_mfma_f32_16x16x32_bf16 v[16:19], v[132:135], v[218:221], v[16:19]
	v_mfma_f32_16x16x32_bf16 v[8:11], v[140:143], v[218:221], v[8:11]
	v_mfma_f32_16x16x32_bf16 v[52:55], v[156:159], v[188:191], v[52:55]
	v_mfma_f32_16x16x32_bf16 v[44:47], v[180:183], v[188:191], v[44:47]
	v_mfma_f32_16x16x32_bf16 v[36:39], v[156:159], v[196:199], v[36:39]
	v_mfma_f32_16x16x32_bf16 v[28:31], v[180:183], v[196:199], v[28:31]
	v_mfma_f32_16x16x32_bf16 v[20:23], v[156:159], v[206:209], v[20:23]
	v_mfma_f32_16x16x32_bf16 v[12:15], v[180:183], v[206:209], v[12:15]
	v_mfma_f32_16x16x32_bf16 v[4:7], v[156:159], v[214:217], v[4:7]
	v_mfma_f32_16x16x32_bf16 v[0:3], v[180:183], v[214:217], v[0:3]
	v_mfma_f32_16x16x32_bf16 v[52:55], v[162:165], v[192:195], v[52:55]
	v_mfma_f32_16x16x32_bf16 v[44:47], v[184:187], v[192:195], v[44:47]
	v_mfma_f32_16x16x32_bf16 v[36:39], v[162:165], v[202:205], v[36:39]
	v_mfma_f32_16x16x32_bf16 v[28:31], v[184:187], v[202:205], v[28:31]
	v_mfma_f32_16x16x32_bf16 v[20:23], v[162:165], v[210:213], v[20:23]
	v_mfma_f32_16x16x32_bf16 v[12:15], v[184:187], v[210:213], v[12:15]
	v_mfma_f32_16x16x32_bf16 v[4:7], v[162:165], v[218:221], v[4:7]
	v_mfma_f32_16x16x32_bf16 v[0:3], v[184:187], v[218:221], v[0:3]
	s_barrier
	s_add_u32 s44, s44, 0x100
	s_addc_u32 s45, s45, 0
	s_cmp_gt_u32 s78, 29
	s_mov_b32 s46, s78
	s_cbranch_scc0 .LBB0_1630
	s_and_b64 vcc, exec, s[24:25]
	s_cbranch_vccz .LBB0_1633
	s_barrier

; #define PG8_STAGE(bufoff, gbase, voff) do { const unsigned long long gb_ = (unsigned long long)(gbase); _Pragma("unroll") for (int _i = 0; _i < 2; ++_i) { unsigned keep_; \
;         asm volatile("s_mov_b32 m0, %2\n\ts_nop 0\n\tglobal_load_lds_dwordx4 %0, %1" : : "v"((voff)[_i]), "s"(gb_), "s"((unsigned)(size_t)(lds + (bufoff) + ldsw + _i * 8192)) : "memory", "m0"); (void)keep_; } } while (0)
; #define PG8_LDA(dst, b, h) do { _Pragma("unroll") for (int m = 0; m < 4; ++m) _Pragma("unroll") for (int k = 0; k < 2; ++k) dst[m][k] = *(const PG8_LAS bf16x8*)(lds + PG8_SA(b, h) + aoff + m * 2048 + k * 1024); } while (0)
; #define PG8_WAIT_V(n) asm volatile("s_waitcnt vmcnt(" #n ")" ::: "memory")
; template <class Epi, class Sched, bool ALIGN_EPI = false, bool SP2 = false>
; __device__ __forceinline__ void gemm_phase(PG8_LAS unsigned char* lds, const Gemm g, const Sched& S, const Epi& E) {
;     ...
;         for (int t = 0; t < nt; t += 2) {
;             const bool last = (t == nt - 2);
;     ...
;             const char* a1 = cA + PG8_KOFFA(t + 1);
;             const char* a2 = last ? nA : cA + PG8_KOFFA(t + 2); const char* b2 = last ? nB : cB + (size_t)(t + 2) * kstep;
;             const char* a3 = last ? nA + kstep : cA + PG8_KOFFA(t + 3); const char* b3 = b2 + kstep;
;     ...
;             if (last && has_next) S.a_ready(nxt);
;             if constexpr (SP2) {
;             PG8_LDB(B0, 0, 0); PG8_LDB(B1, 0, 1); PG8_SCHED; PG8_LDA(At, 0, 0); PG8_STAGE(PG8_SA(1, 1), a1 + hstepA, voffA);
;             PG8_WAIT_V(8); PG8_WAIT_L(0); PG8_BAR; PG8_MMA(0, 0, At, B0); PG8_MMA(0, 1, At, B1); PG8_BAR; PG8_SCHED;
;             PG8_LDA(At, 0, 1); PG8_STAGE(PG8_SB(0, 0), b2, voffB); PG8_STAGE(PG8_SB(0, 1), b2 + hstepB, voffB); PG8_STAGE(PG8_SA(0, 0), a2, voffA);
;             PG8_WAIT_V(8); PG8_WAIT_L(0); PG8_BAR; PG8_MMA(1, 0, At, B0); PG8_MMA(1, 1, At, B1); PG8_BAR; PG8_SCHED;
;             PG8_LDB(B0, 1, 0); PG8_LDB(B1, 1, 1); PG8_SCHED; PG8_LDA(At, 1, 0); PG8_STAGE(PG8_SA(0, 1), a2 + hstepA, voffA);
;             PG8_WAIT_V(8); PG8_WAIT_L(0); PG8_BAR; PG8_MMA(0, 0, At, B0); PG8_MMA(0, 1, At, B1); PG8_BAR; PG8_SCHED;
;             PG8_LDA(At, 1, 1); PG8_STAGE(PG8_SB(1, 0), b3, voffB); PG8_STAGE(PG8_SB(1, 1), b3 + hstepB, voffB); PG8_STAGE(PG8_SA(1, 0), a3, voffA);
;             PG8_WAIT_V(8); PG8_WAIT_L(0); PG8_BAR; PG8_MMA(1, 0, At, B0); PG8_MMA(1, 1, At, B1); PG8_BAR; PG8_SCHED;
.LBB0_1825:
	ds_read_b128 v[88:91], v203
	ds_read_b128 v[92:95], v203 offset:1024
	ds_read_b128 v[96:99], v203 offset:2048
	ds_read_b128 v[100:103], v203 offset:3072
	ds_read_b128 v[128:131], v232
	ds_read_b128 v[136:139], v232 offset:1024
	ds_read_b128 v[152:155], v232 offset:2048
	ds_read_b128 v[156:159], v232 offset:3072
	s_cmp_eq_u32 s79, 28
	s_cselect_b32 s49, s0, s78
	s_cselect_b32 s48, s1, s77
	s_cselect_b32 s47, s16, s76
	s_cselect_b32 s46, s31, s73
	s_cselect_b32 s45, s70, s72
	s_cselect_b32 s44, s35, s71
	ds_read_b128 v[160:163], v233
	ds_read_b128 v[164:167], v233 offset:1024
	ds_read_b128 v[168:171], v233 offset:2048
	ds_read_b128 v[172:175], v233 offset:3072
	ds_read_b128 v[176:179], v233 offset:4096
	ds_read_b128 v[180:183], v233 offset:5120
	ds_read_b128 v[184:187], v233 offset:6144
	ds_read_b128 v[188:191], v233 offset:7168
	s_mov_b32 m0, s65
	s_nop 0
	global_load_lds_dwordx4 v201, s[10:11]
	s_nop 0
	s_mov_b32 m0, s66
	s_nop 0
	global_load_lds_dwordx4 v230, s[10:11]
	s_waitcnt vmcnt(8)
	s_waitcnt lgkmcnt(0)
	s_barrier
	v_mfma_f32_16x16x32_bf16 v[148:151], v[88:91], v[160:163], v[148:151]
	v_mfma_f32_16x16x32_bf16 v[144:147], v[96:99], v[160:163], v[144:147]
	v_mfma_f32_16x16x32_bf16 v[124:127], v[88:91], v[168:171], v[124:127]
	v_mfma_f32_16x16x32_bf16 v[120:123], v[96:99], v[168:171], v[120:123]
	v_mfma_f32_16x16x32_bf16 v[108:111], v[88:91], v[176:179], v[108:111]
	v_mfma_f32_16x16x32_bf16 v[104:107], v[96:99], v[176:179], v[104:107]
	v_mfma_f32_16x16x32_bf16 v[76:79], v[88:91], v[184:187], v[76:79]
	v_mfma_f32_16x16x32_bf16 v[72:75], v[96:99], v[184:187], v[72:75]
	v_mfma_f32_16x16x32_bf16 v[148:151], v[92:95], v[164:167], v[148:151]
	v_mfma_f32_16x16x32_bf16 v[144:147], v[100:103], v[164:167], v[144:147]
	v_mfma_f32_16x16x32_bf16 v[124:127], v[92:95], v[172:175], v[124:127]
	v_mfma_f32_16x16x32_bf16 v[120:123], v[100:103], v[172:175], v[120:123]
	v_mfma_f32_16x16x32_bf16 v[108:111], v[92:95], v[180:183], v[108:111]
	v_mfma_f32_16x16x32_bf16 v[104:107], v[100:103], v[180:183], v[104:107]
	v_mfma_f32_16x16x32_bf16 v[76:79], v[92:95], v[188:191], v[76:79]
	v_mfma_f32_16x16x32_bf16 v[72:75], v[100:103], v[188:191], v[72:75]
	v_mfma_f32_16x16x32_bf16 v[140:143], v[128:131], v[160:163], v[140:143]
	v_mfma_f32_16x16x32_bf16 v[132:135], v[152:155], v[160:163], v[132:135]
	v_mfma_f32_16x16x32_bf16 v[116:119], v[128:131], v[168:171], v[116:119]
	v_mfma_f32_16x16x32_bf16 v[112:115], v[152:155], v[168:171], v[112:115]
	v_mfma_f32_16x16x32_bf16 v[84:87], v[128:131], v[176:179], v[84:87]
	v_mfma_f32_16x16x32_bf16 v[80:83], v[152:155], v[176:179], v[80:83]
	v_mfma_f32_16x16x32_bf16 v[68:71], v[128:131], v[184:187], v[68:71]
	v_mfma_f32_16x16x32_bf16 v[64:67], v[152:155], v[184:187], v[64:67]
	v_mfma_f32_16x16x32_bf16 v[140:143], v[136:139], v[164:167], v[140:143]
	v_mfma_f32_16x16x32_bf16 v[132:135], v[156:159], v[164:167], v[132:135]
	v_mfma_f32_16x16x32_bf16 v[116:119], v[136:139], v[172:175], v[116:119]
	v_mfma_f32_16x16x32_bf16 v[112:115], v[156:159], v[172:175], v[112:115]
	v_mfma_f32_16x16x32_bf16 v[84:87], v[136:139], v[180:183], v[84:87]
	v_mfma_f32_16x16x32_bf16 v[80:83], v[156:159], v[180:183], v[80:83]
	v_mfma_f32_16x16x32_bf16 v[68:71], v[136:139], v[188:191], v[68:71]
	v_mfma_f32_16x16x32_bf16 v[64:67], v[156:159], v[188:191], v[64:67]
	s_barrier
	ds_read_b128 v[160:163], v233 offset:16384
	ds_read_b128 v[164:167], v233 offset:17408
	ds_read_b128 v[168:171], v233 offset:18432
	ds_read_b128 v[172:175], v233 offset:19456
	ds_read_b128 v[176:179], v233 offset:20480
	ds_read_b128 v[180:183], v233 offset:21504
	ds_read_b128 v[184:187], v233 offset:22528
	ds_read_b128 v[188:191], v233 offset:23552
	s_mov_b32 m0, s43
	s_nop 0
	global_load_lds_dwordx4 v205, s[46:47]
	s_add_u32 s80, s46, 0x80000
	s_mov_b32 m0, s52
	s_nop 0
	global_load_lds_dwordx4 v231, s[46:47]
	s_addc_u32 s81, s47, 0
	s_mov_b32 m0, s53
	s_nop 0
	global_load_lds_dwordx4 v205, s[80:81]
	s_nop 0
	s_mov_b32 m0, s54
	s_nop 0
	global_load_lds_dwordx4 v231, s[80:81]
	s_nop 0
	s_mov_b32 m0, s41
	s_nop 0
	global_load_lds_dwordx4 v201, s[48:49]
	s_nop 0
	s_mov_b32 m0, s55
	s_nop 0
	global_load_lds_dwordx4 v230, s[48:49]
	s_waitcnt vmcnt(8)
	s_waitcnt lgkmcnt(0)
	s_barrier
	v_mfma_f32_16x16x32_bf16 v[60:63], v[88:91], v[160:163], v[60:63]
	v_mfma_f32_16x16x32_bf16 v[56:59], v[96:99], v[160:163], v[56:59]
	v_mfma_f32_16x16x32_bf16 v[44:47], v[88:91], v[168:171], v[44:47]
	v_mfma_f32_16x16x32_bf16 v[40:43], v[96:99], v[168:171], v[40:43]
	v_mfma_f32_16x16x32_bf16 v[28:31], v[88:91], v[176:179], v[28:31]
	v_mfma_f32_16x16x32_bf16 v[24:27], v[96:99], v[176:179], v[24:27]
	v_mfma_f32_16x16x32_bf16 v[12:15], v[88:91], v[184:187], v[12:15]
	v_mfma_f32_16x16x32_bf16 v[8:11], v[96:99], v[184:187], v[8:11]
	v_mfma_f32_16x16x32_bf16 v[60:63], v[92:95], v[164:167], v[60:63]
	v_mfma_f32_16x16x32_bf16 v[56:59], v[100:103], v[164:167], v[56:59]
	v_mfma_f32_16x16x32_bf16 v[44:47], v[92:95], v[172:175], v[44:47]
	v_mfma_f32_16x16x32_bf16 v[40:43], v[100:103], v[172:175], v[40:43]
	v_mfma_f32_16x16x32_bf16 v[28:31], v[92:95], v[180:183], v[28:31]
	v_mfma_f32_16x16x32_bf16 v[24:27], v[100:103], v[180:183], v[24:27]
	v_mfma_f32_16x16x32_bf16 v[12:15], v[92:95], v[188:191], v[12:15]
	v_mfma_f32_16x16x32_bf16 v[8:11], v[100:103], v[188:191], v[8:11]
	v_mfma_f32_16x16x32_bf16 v[52:55], v[128:131], v[160:163], v[52:55]
	v_mfma_f32_16x16x32_bf16 v[48:51], v[152:155], v[160:163], v[48:51]
	v_mfma_f32_16x16x32_bf16 v[36:39], v[128:131], v[168:171], v[36:39]
	v_mfma_f32_16x16x32_bf16 v[32:35], v[152:155], v[168:171], v[32:35]
	v_mfma_f32_16x16x32_bf16 v[20:23], v[128:131], v[176:179], v[20:23]
	v_mfma_f32_16x16x32_bf16 v[16:19], v[152:155], v[176:179], v[16:19]
	v_mfma_f32_16x16x32_bf16 v[4:7], v[128:131], v[184:187], v[4:7]
	v_mfma_f32_16x16x32_bf16 v[0:3], v[152:155], v[184:187], v[0:3]
	v_mfma_f32_16x16x32_bf16 v[52:55], v[136:139], v[164:167], v[52:55]
	v_mfma_f32_16x16x32_bf16 v[48:51], v[156:159], v[164:167], v[48:51]
	v_mfma_f32_16x16x32_bf16 v[36:39], v[136:139], v[172:175], v[36:39]
	v_mfma_f32_16x16x32_bf16 v[32:35], v[156:159], v[172:175], v[32:35]
	v_mfma_f32_16x16x32_bf16 v[20:23], v[136:139], v[180:183], v[20:23]
	v_mfma_f32_16x16x32_bf16 v[16:19], v[156:159], v[180:183], v[16:19]
	v_mfma_f32_16x16x32_bf16 v[4:7], v[136:139], v[188:191], v[4:7]
	v_mfma_f32_16x16x32_bf16 v[0:3], v[156:159], v[188:191], v[0:3]
	s_barrier
; #define PG8_STAGE(bufoff, gbase, voff) do { const unsigned long long gb_ = (unsigned long long)(gbase); _Pragma("unroll") for (int _i = 0; _i < 2; ++_i) { unsigned keep_; \
;         asm volatile("s_mov_b32 m0, %2\n\ts_nop 0\n\tglobal_load_lds_dwordx4 %0, %1" : : "v"((voff)[_i]), "s"(gb_), "s"((unsigned)(size_t)(lds + (bufoff) + ldsw + _i * 8192)) : "memory", "m0"); (void)keep_; } } while (0)
; #define PG8_LDA(dst, b, h) do { _Pragma("unroll") for (int m = 0; m < 4; ++m) _Pragma("unroll") for (int k = 0; k < 2; ++k) dst[m][k] = *(const PG8_LAS bf16x8*)(lds + PG8_SA(b, h) + aoff + m * 2048 + k * 1024); } while (0)
; #define PG8_LDB(dst, b, h) do { _Pragma("unroll") for (int n = 0; n < 2; ++n) _Pragma("unroll") for (int k = 0; k < 2; ++k) dst[n][k] = *(const PG8_LAS bf16x8*)(lds + PG8_SB(b, h) + boff + n * 2048 + k * 1024); } while (0)
; #define PG8_MMA(ai, bj, At, Bt) do { __builtin_amdgcn_s_setprio(1); _Pragma("unroll") for (int m = 0; m < 4; ++m) _Pragma("unroll") for (int n = 0; n < 2; ++n) _Pragma("unroll") for (int k = 0; k < 2; ++k) \
;         acc[ai][bj][m][n] = __builtin_amdgcn_mfma_f32_16x16x32_bf16(Bt[n][k], At[m][k], acc[ai][bj][m][n], 0, 0, 0); __builtin_amdgcn_s_setprio(0); } while (0)
; #define PG8_WAIT_V(n) asm volatile("s_waitcnt vmcnt(" #n ")" ::: "memory")
; #define PG8_WAIT_L(n) asm volatile("s_waitcnt lgkmcnt(" #n ")" ::: "memory")
; #define PG8_BAR __builtin_amdgcn_s_barrier()
; #define PG8_SCHED __builtin_amdgcn_sched_barrier(0)
; template <class Epi, class Sched, bool ALIGN_EPI = false, bool SP2 = false>
; __device__ __forceinline__ void gemm_phase(PG8_LAS unsigned char* lds, const Gemm g, const Sched& S, const Epi& E) {
;     ...
;         for (int t = 0; t < nt; t += 2) {
;     ...
;             PG8_LDB(B0, 1, 0); PG8_LDB(B1, 1, 1); PG8_SCHED; PG8_LDA(At, 1, 0); PG8_STAGE(PG8_SA(0, 1), a2 + hstepA, voffA);
;             PG8_WAIT_V(8); PG8_WAIT_L(0); PG8_BAR; PG8_MMA(0, 0, At, B0); PG8_MMA(0, 1, At, B1); PG8_BAR; PG8_SCHED;
;             PG8_LDA(At, 1, 1); PG8_STAGE(PG8_SB(1, 0), b3, voffB); PG8_STAGE(PG8_SB(1, 1), b3 + hstepB, voffB); PG8_STAGE(PG8_SA(1, 0), a3, voffA);
;             PG8_WAIT_V(8); PG8_WAIT_L(0); PG8_BAR; PG8_MMA(1, 0, At, B0); PG8_MMA(1, 1, At, B1); PG8_BAR; PG8_SCHED;
	ds_read_b128 v[88:91], v234
	ds_read_b128 v[92:95], v234 offset:1024
	ds_read_b128 v[96:99], v234 offset:2048
	ds_read_b128 v[100:103], v234 offset:3072
	ds_read_b128 v[128:131], v235
	ds_read_b128 v[136:139], v235 offset:1024
	ds_read_b128 v[152:155], v235 offset:2048
	ds_read_b128 v[156:159], v235 offset:3072
	ds_read_b128 v[160:163], v233 offset:32768
	ds_read_b128 v[164:167], v233 offset:33792
	ds_read_b128 v[168:171], v233 offset:34816
	ds_read_b128 v[172:175], v233 offset:35840
	ds_read_b128 v[176:179], v233 offset:36864
	ds_read_b128 v[180:183], v233 offset:37888
	ds_read_b128 v[184:187], v233 offset:38912
	ds_read_b128 v[188:191], v233 offset:39936
	s_add_u32 s48, s48, 0x80000
	s_addc_u32 s49, s49, 0
	s_mov_b32 m0, s56
	s_nop 0
	global_load_lds_dwordx4 v201, s[48:49]
	s_nop 0
	s_mov_b32 m0, s57
	s_nop 0
	global_load_lds_dwordx4 v230, s[48:49]
	s_waitcnt vmcnt(8)
	s_waitcnt lgkmcnt(0)
	s_barrier
	v_mfma_f32_16x16x32_bf16 v[148:151], v[88:91], v[160:163], v[148:151]
	v_mfma_f32_16x16x32_bf16 v[144:147], v[96:99], v[160:163], v[144:147]
	v_mfma_f32_16x16x32_bf16 v[124:127], v[88:91], v[168:171], v[124:127]
	v_mfma_f32_16x16x32_bf16 v[120:123], v[96:99], v[168:171], v[120:123]
	v_mfma_f32_16x16x32_bf16 v[108:111], v[88:91], v[176:179], v[108:111]
	v_mfma_f32_16x16x32_bf16 v[104:107], v[96:99], v[176:179], v[104:107]
	v_mfma_f32_16x16x32_bf16 v[76:79], v[88:91], v[184:187], v[76:79]
	v_mfma_f32_16x16x32_bf16 v[72:75], v[96:99], v[184:187], v[72:75]
	v_mfma_f32_16x16x32_bf16 v[148:151], v[92:95], v[164:167], v[148:151]
	v_mfma_f32_16x16x32_bf16 v[144:147], v[100:103], v[164:167], v[144:147]
	v_mfma_f32_16x16x32_bf16 v[124:127], v[92:95], v[172:175], v[124:127]
	v_mfma_f32_16x16x32_bf16 v[120:123], v[100:103], v[172:175], v[120:123]
	v_mfma_f32_16x16x32_bf16 v[108:111], v[92:95], v[180:183], v[108:111]
	v_mfma_f32_16x16x32_bf16 v[104:107], v[100:103], v[180:183], v[104:107]
	v_mfma_f32_16x16x32_bf16 v[76:79], v[92:95], v[188:191], v[76:79]
	v_mfma_f32_16x16x32_bf16 v[72:75], v[100:103], v[188:191], v[72:75]
	v_mfma_f32_16x16x32_bf16 v[140:143], v[128:131], v[160:163], v[140:143]
	v_mfma_f32_16x16x32_bf16 v[132:135], v[152:155], v[160:163], v[132:135]
	v_mfma_f32_16x16x32_bf16 v[116:119], v[128:131], v[168:171], v[116:119]
	v_mfma_f32_16x16x32_bf16 v[112:115], v[152:155], v[168:171], v[112:115]
	v_mfma_f32_16x16x32_bf16 v[84:87], v[128:131], v[176:179], v[84:87]
	v_mfma_f32_16x16x32_bf16 v[80:83], v[152:155], v[176:179], v[80:83]
	v_mfma_f32_16x16x32_bf16 v[68:71], v[128:131], v[184:187], v[68:71]
	v_mfma_f32_16x16x32_bf16 v[64:67], v[152:155], v[184:187], v[64:67]
	v_mfma_f32_16x16x32_bf16 v[140:143], v[136:139], v[164:167], v[140:143]
	v_mfma_f32_16x16x32_bf16 v[132:135], v[156:159], v[164:167], v[132:135]
	v_mfma_f32_16x16x32_bf16 v[116:119], v[136:139], v[172:175], v[116:119]
	v_mfma_f32_16x16x32_bf16 v[112:115], v[156:159], v[172:175], v[112:115]
	v_mfma_f32_16x16x32_bf16 v[84:87], v[136:139], v[180:183], v[84:87]
	v_mfma_f32_16x16x32_bf16 v[80:83], v[156:159], v[180:183], v[80:83]
	v_mfma_f32_16x16x32_bf16 v[68:71], v[136:139], v[188:191], v[68:71]
	v_mfma_f32_16x16x32_bf16 v[64:67], v[156:159], v[188:191], v[64:67]
	s_barrier
	ds_read_b128 v[160:163], v233 offset:49152
	ds_read_b128 v[164:167], v233 offset:50176
	ds_read_b128 v[168:171], v233 offset:51200
	ds_read_b128 v[172:175], v233 offset:52224
	ds_read_b128 v[176:179], v233 offset:53248
	ds_read_b128 v[180:183], v233 offset:54272
	ds_read_b128 v[184:187], v233 offset:55296
	ds_read_b128 v[188:191], v233 offset:56320
	s_add_u32 s48, s46, 0x80
	s_addc_u32 s49, s47, 0
	s_mov_b32 m0, s59
	s_nop 0
	global_load_lds_dwordx4 v205, s[48:49]
	s_add_u32 s46, s46, 0x80080
	s_mov_b32 m0, s60
	s_nop 0
	global_load_lds_dwordx4 v231, s[48:49]
	s_addc_u32 s47, s47, 0
	s_mov_b32 m0, s63
	s_nop 0
	global_load_lds_dwordx4 v205, s[46:47]
	s_nop 0
	s_mov_b32 m0, s64
	s_nop 0
	global_load_lds_dwordx4 v231, s[46:47]
	s_nop 0
	s_mov_b32 m0, s61
	s_nop 0
	global_load_lds_dwordx4 v201, s[44:45]
	s_nop 0
	s_mov_b32 m0, s62
	s_nop 0
	global_load_lds_dwordx4 v230, s[44:45]
	s_waitcnt vmcnt(8)
	s_waitcnt lgkmcnt(0)
	s_barrier
	v_mfma_f32_16x16x32_bf16 v[60:63], v[88:91], v[160:163], v[60:63]
	v_mfma_f32_16x16x32_bf16 v[56:59], v[96:99], v[160:163], v[56:59]
	v_mfma_f32_16x16x32_bf16 v[44:47], v[88:91], v[168:171], v[44:47]
	v_mfma_f32_16x16x32_bf16 v[40:43], v[96:99], v[168:171], v[40:43]
	v_mfma_f32_16x16x32_bf16 v[28:31], v[88:91], v[176:179], v[28:31]
	v_mfma_f32_16x16x32_bf16 v[24:27], v[96:99], v[176:179], v[24:27]
	v_mfma_f32_16x16x32_bf16 v[12:15], v[88:91], v[184:187], v[12:15]
	v_mfma_f32_16x16x32_bf16 v[8:11], v[96:99], v[184:187], v[8:11]
	v_mfma_f32_16x16x32_bf16 v[60:63], v[92:95], v[164:167], v[60:63]
	v_mfma_f32_16x16x32_bf16 v[56:59], v[100:103], v[164:167], v[56:59]
	v_mfma_f32_16x16x32_bf16 v[44:47], v[92:95], v[172:175], v[44:47]
	v_mfma_f32_16x16x32_bf16 v[40:43], v[100:103], v[172:175], v[40:43]
	v_mfma_f32_16x16x32_bf16 v[28:31], v[92:95], v[180:183], v[28:31]
	v_mfma_f32_16x16x32_bf16 v[24:27], v[100:103], v[180:183], v[24:27]
	v_mfma_f32_16x16x32_bf16 v[12:15], v[92:95], v[188:191], v[12:15]
	v_mfma_f32_16x16x32_bf16 v[8:11], v[100:103], v[188:191], v[8:11]
	v_mfma_f32_16x16x32_bf16 v[52:55], v[128:131], v[160:163], v[52:55]
	v_mfma_f32_16x16x32_bf16 v[48:51], v[152:155], v[160:163], v[48:51]
	v_mfma_f32_16x16x32_bf16 v[36:39], v[128:131], v[168:171], v[36:39]
	v_mfma_f32_16x16x32_bf16 v[32:35], v[152:155], v[168:171], v[32:35]
	v_mfma_f32_16x16x32_bf16 v[20:23], v[128:131], v[176:179], v[20:23]
	v_mfma_f32_16x16x32_bf16 v[16:19], v[152:155], v[176:179], v[16:19]
	v_mfma_f32_16x16x32_bf16 v[4:7], v[128:131], v[184:187], v[4:7]
	v_mfma_f32_16x16x32_bf16 v[0:3], v[152:155], v[184:187], v[0:3]
	v_mfma_f32_16x16x32_bf16 v[52:55], v[136:139], v[164:167], v[52:55]
	v_mfma_f32_16x16x32_bf16 v[48:51], v[156:159], v[164:167], v[48:51]
	v_mfma_f32_16x16x32_bf16 v[36:39], v[136:139], v[172:175], v[36:39]
	v_mfma_f32_16x16x32_bf16 v[32:35], v[156:159], v[172:175], v[32:35]
	v_mfma_f32_16x16x32_bf16 v[20:23], v[136:139], v[180:183], v[20:23]
	v_mfma_f32_16x16x32_bf16 v[16:19], v[156:159], v[180:183], v[16:19]
	v_mfma_f32_16x16x32_bf16 v[4:7], v[136:139], v[188:191], v[4:7]
	v_mfma_f32_16x16x32_bf16 v[0:3], v[156:159], v[188:191], v[0:3]
	s_barrier
	s_add_i32 s79, s79, 2
	s_add_u32 s71, s71, 0x100
	s_addc_u32 s72, s72, 0
	s_add_u32 s73, s73, 0x100
	s_addc_u32 s76, s76, 0
	s_add_u32 s77, s77, 0x100
	s_addc_u32 s78, s78, 0
	s_add_u32 s10, s10, 0x100
	s_addc_u32 s11, s11, 0
	s_cmp_gt_u32 s79, 29
	s_cbranch_scc0 .LBB0_1825
	s_and_b64 vcc, exec, s[26:27]
	s_cbranch_vccz .LBB0_1828
	s_barrier

; #define PG8_STAGE(bufoff, gbase, voff) do { const unsigned long long gb_ = (unsigned long long)(gbase); _Pragma("unroll") for (int _i = 0; _i < 2; ++_i) { unsigned keep_; \
;         asm volatile("s_mov_b32 m0, %2\n\ts_nop 0\n\tglobal_load_lds_dwordx4 %0, %1" : : "v"((voff)[_i]), "s"(gb_), "s"((unsigned)(size_t)(lds + (bufoff) + ldsw + _i * 8192)) : "memory", "m0"); (void)keep_; } } while (0)
; #define PG8_LDA(dst, b, h) do { _Pragma("unroll") for (int m = 0; m < 4; ++m) _Pragma("unroll") for (int k = 0; k < 2; ++k) dst[m][k] = *(const PG8_LAS bf16x8*)(lds + PG8_SA(b, h) + aoff + m * 2048 + k * 1024); } while (0)
; #define PG8_WAIT_V(n) asm volatile("s_waitcnt vmcnt(" #n ")" ::: "memory")
; template <class Epi, class Sched, bool ALIGN_EPI = false, bool SP2 = false>
; __device__ __forceinline__ void gemm_phase(PG8_LAS unsigned char* lds, const Gemm g, const Sched& S, const Epi& E) {
;     ...
;         for (int t = 0; t < nt; t += 2) {
;             const bool last = (t == nt - 2);
;     ...
;             const char* a1 = cA + PG8_KOFFA(t + 1);
;             const char* a2 = last ? nA : cA + PG8_KOFFA(t + 2); const char* b2 = last ? nB : cB + (size_t)(t + 2) * kstep;
;             const char* a3 = last ? nA + kstep : cA + PG8_KOFFA(t + 3); const char* b3 = b2 + kstep;
;     ...
;             if (last && has_next) S.a_ready(nxt);
;             if constexpr (SP2) {
;             PG8_LDB(B0, 0, 0); PG8_LDB(B1, 0, 1); PG8_SCHED; PG8_LDA(At, 0, 0); PG8_STAGE(PG8_SA(1, 1), a1 + hstepA, voffA);
;             PG8_WAIT_V(8); PG8_WAIT_L(0); PG8_BAR; PG8_MMA(0, 0, At, B0); PG8_MMA(0, 1, At, B1); PG8_BAR; PG8_SCHED;
;             PG8_LDA(At, 0, 1); PG8_STAGE(PG8_SB(0, 0), b2, voffB); PG8_STAGE(PG8_SB(0, 1), b2 + hstepB, voffB); PG8_STAGE(PG8_SA(0, 0), a2, voffA);
;             PG8_WAIT_V(8); PG8_WAIT_L(0); PG8_BAR; PG8_MMA(1, 0, At, B0); PG8_MMA(1, 1, At, B1); PG8_BAR; PG8_SCHED;
;             PG8_LDB(B0, 1, 0); PG8_LDB(B1, 1, 1); PG8_SCHED; PG8_LDA(At, 1, 0); PG8_STAGE(PG8_SA(0, 1), a2 + hstepA, voffA);
;             PG8_WAIT_V(8); PG8_WAIT_L(0); PG8_BAR; PG8_MMA(0, 0, At, B0); PG8_MMA(0, 1, At, B1); PG8_BAR; PG8_SCHED;
;             PG8_LDA(At, 1, 1); PG8_STAGE(PG8_SB(1, 0), b3, voffB); PG8_STAGE(PG8_SB(1, 1), b3 + hstepB, voffB); PG8_STAGE(PG8_SA(1, 0), a3, voffA);
;             PG8_WAIT_V(8); PG8_WAIT_L(0); PG8_BAR; PG8_MMA(1, 0, At, B0); PG8_MMA(1, 1, At, B1); PG8_BAR; PG8_SCHED;
.LBB0_2228:
	s_add_i32 s43, s77, 0xfffe8000
	s_and_b32 s42, s40, 0x100
	s_and_b32 s43, s43, 0xe0000
	s_or_b32 s42, s42, s43
	s_add_u32 s78, s10, s42
	s_addc_u32 s79, s11, 0
	s_add_u32 s42, s40, 0x100
	s_addc_u32 s43, s41, 0
	s_add_i32 s45, s77, 0xffff8000
	s_and_b32 s44, s42, 0x100
	s_and_b32 s45, s45, 0x1e0000
	s_or_b32 s44, s45, s44
	ds_read_b128 v[128:131], v177
	ds_read_b128 v[132:135], v177 offset:1024
	ds_read_b128 v[162:165], v177 offset:2048
	ds_read_b128 v[166:169], v177 offset:3072
	ds_read_b128 v[184:187], v178
	ds_read_b128 v[188:191], v178 offset:1024
	ds_read_b128 v[192:195], v178 offset:2048
	ds_read_b128 v[196:199], v178 offset:3072
	s_add_u32 s44, s10, s44
	s_addc_u32 s45, s11, 0
	s_add_u32 s80, s39, s40
	s_addc_u32 s41, s73, s41
	s_add_i32 s46, s40, 0x180
	s_and_b32 s46, s46, 0x180
	s_and_b32 s47, s77, 0x1e0000
	s_or_b32 s46, s47, s46
	s_add_u32 s81, s10, s46
	s_addc_u32 s82, s11, 0
	s_cmpk_eq_i32 s40, 0xf00
	s_cselect_b32 s47, s0, s45
	s_cselect_b32 s45, s4, s41
	s_cselect_b32 s41, s31, s82
	s_cselect_b32 s40, s29, s81
	s_cselect_b32 s46, s1, s44
	s_cselect_b32 s44, s5, s80
	ds_read_b128 v[202:205], v179
	ds_read_b128 v[206:209], v179 offset:1024
	ds_read_b128 v[210:213], v179 offset:2048
	ds_read_b128 v[214:217], v179 offset:3072
	ds_read_b128 v[218:221], v179 offset:4096
	ds_read_b128 v[222:225], v179 offset:5120
	ds_read_b128 v[226:229], v179 offset:6144
	ds_read_b128 v[230:233], v179 offset:7168
	s_add_u32 s78, s78, 0x10080
	s_addc_u32 s79, s79, 0
	s_mov_b32 m0, s68
	s_nop 0
	global_load_lds_dwordx4 v172, s[78:79]
	s_nop 0
	s_mov_b32 m0, s69
	s_nop 0
	global_load_lds_dwordx4 v174, s[78:79]
	s_waitcnt vmcnt(8)
	s_waitcnt lgkmcnt(0)
	s_barrier
	v_mfma_f32_16x16x32_bf16 v[124:127], v[128:131], v[202:205], v[124:127]
	v_mfma_f32_16x16x32_bf16 v[120:123], v[162:165], v[202:205], v[120:123]
	v_mfma_f32_16x16x32_bf16 v[108:111], v[128:131], v[210:213], v[108:111]
	v_mfma_f32_16x16x32_bf16 v[104:107], v[162:165], v[210:213], v[104:107]
	v_mfma_f32_16x16x32_bf16 v[92:95], v[128:131], v[218:221], v[92:95]
	v_mfma_f32_16x16x32_bf16 v[88:91], v[162:165], v[218:221], v[88:91]
	v_mfma_f32_16x16x32_bf16 v[76:79], v[128:131], v[226:229], v[76:79]
	v_mfma_f32_16x16x32_bf16 v[72:75], v[162:165], v[226:229], v[72:75]
	v_mfma_f32_16x16x32_bf16 v[124:127], v[132:135], v[206:209], v[124:127]
	v_mfma_f32_16x16x32_bf16 v[120:123], v[166:169], v[206:209], v[120:123]
	v_mfma_f32_16x16x32_bf16 v[108:111], v[132:135], v[214:217], v[108:111]
	v_mfma_f32_16x16x32_bf16 v[104:107], v[166:169], v[214:217], v[104:107]
	v_mfma_f32_16x16x32_bf16 v[92:95], v[132:135], v[222:225], v[92:95]
	v_mfma_f32_16x16x32_bf16 v[88:91], v[166:169], v[222:225], v[88:91]
	v_mfma_f32_16x16x32_bf16 v[76:79], v[132:135], v[230:233], v[76:79]
	v_mfma_f32_16x16x32_bf16 v[72:75], v[166:169], v[230:233], v[72:75]
	v_mfma_f32_16x16x32_bf16 v[116:119], v[184:187], v[202:205], v[116:119]
	v_mfma_f32_16x16x32_bf16 v[112:115], v[192:195], v[202:205], v[112:115]
	v_mfma_f32_16x16x32_bf16 v[100:103], v[184:187], v[210:213], v[100:103]
	v_mfma_f32_16x16x32_bf16 v[96:99], v[192:195], v[210:213], v[96:99]
	v_mfma_f32_16x16x32_bf16 v[84:87], v[184:187], v[218:221], v[84:87]
	v_mfma_f32_16x16x32_bf16 v[80:83], v[192:195], v[218:221], v[80:83]
	v_mfma_f32_16x16x32_bf16 v[68:71], v[184:187], v[226:229], v[68:71]
	v_mfma_f32_16x16x32_bf16 v[64:67], v[192:195], v[226:229], v[64:67]
	v_mfma_f32_16x16x32_bf16 v[116:119], v[188:191], v[206:209], v[116:119]
	v_mfma_f32_16x16x32_bf16 v[112:115], v[196:199], v[206:209], v[112:115]
	v_mfma_f32_16x16x32_bf16 v[100:103], v[188:191], v[214:217], v[100:103]
	v_mfma_f32_16x16x32_bf16 v[96:99], v[196:199], v[214:217], v[96:99]
	v_mfma_f32_16x16x32_bf16 v[84:87], v[188:191], v[222:225], v[84:87]
	v_mfma_f32_16x16x32_bf16 v[80:83], v[196:199], v[222:225], v[80:83]
	v_mfma_f32_16x16x32_bf16 v[68:71], v[188:191], v[230:233], v[68:71]
	v_mfma_f32_16x16x32_bf16 v[64:67], v[196:199], v[230:233], v[64:67]
	s_barrier
	ds_read_b128 v[202:205], v179 offset:16384
	ds_read_b128 v[206:209], v179 offset:17408
	ds_read_b128 v[210:213], v179 offset:18432
	ds_read_b128 v[214:217], v179 offset:19456
	ds_read_b128 v[218:221], v179 offset:20480
	ds_read_b128 v[222:225], v179 offset:21504
	ds_read_b128 v[226:229], v179 offset:22528
	ds_read_b128 v[230:233], v179 offset:23552
	s_mov_b32 m0, s54
	s_nop 0
	global_load_lds_dwordx4 v173, s[44:45]
	s_add_u32 s78, s44, 0x80000
	s_mov_b32 m0, s55
	s_nop 0
	global_load_lds_dwordx4 v175, s[44:45]
	s_addc_u32 s79, s45, 0
	s_mov_b32 m0, s56
	s_nop 0
	global_load_lds_dwordx4 v173, s[78:79]
	s_nop 0
	s_mov_b32 m0, s57
	s_nop 0
	global_load_lds_dwordx4 v175, s[78:79]
	s_nop 0
	s_mov_b32 m0, s53
	s_nop 0
	global_load_lds_dwordx4 v172, s[46:47]
	s_nop 0
	s_mov_b32 m0, s58
	s_nop 0
	global_load_lds_dwordx4 v174, s[46:47]
	s_waitcnt vmcnt(8)
	s_waitcnt lgkmcnt(0)
	s_barrier
; #define PG8_STAGE(bufoff, gbase, voff) do { const unsigned long long gb_ = (unsigned long long)(gbase); _Pragma("unroll") for (int _i = 0; _i < 2; ++_i) { unsigned keep_; \
;         asm volatile("s_mov_b32 m0, %2\n\ts_nop 0\n\tglobal_load_lds_dwordx4 %0, %1" : : "v"((voff)[_i]), "s"(gb_), "s"((unsigned)(size_t)(lds + (bufoff) + ldsw + _i * 8192)) : "memory", "m0"); (void)keep_; } } while (0)
; #define PG8_LDA(dst, b, h) do { _Pragma("unroll") for (int m = 0; m < 4; ++m) _Pragma("unroll") for (int k = 0; k < 2; ++k) dst[m][k] = *(const PG8_LAS bf16x8*)(lds + PG8_SA(b, h) + aoff + m * 2048 + k * 1024); } while (0)
; #define PG8_LDB(dst, b, h) do { _Pragma("unroll") for (int n = 0; n < 2; ++n) _Pragma("unroll") for (int k = 0; k < 2; ++k) dst[n][k] = *(const PG8_LAS bf16x8*)(lds + PG8_SB(b, h) + boff + n * 2048 + k * 1024); } while (0)
; #define PG8_MMA(ai, bj, At, Bt) do { __builtin_amdgcn_s_setprio(1); _Pragma("unroll") for (int m = 0; m < 4; ++m) _Pragma("unroll") for (int n = 0; n < 2; ++n) _Pragma("unroll") for (int k = 0; k < 2; ++k) \
;         acc[ai][bj][m][n] = __builtin_amdgcn_mfma_f32_16x16x32_bf16(Bt[n][k], At[m][k], acc[ai][bj][m][n], 0, 0, 0); __builtin_amdgcn_s_setprio(0); } while (0)
; #define PG8_WAIT_V(n) asm volatile("s_waitcnt vmcnt(" #n ")" ::: "memory")
; #define PG8_WAIT_L(n) asm volatile("s_waitcnt lgkmcnt(" #n ")" ::: "memory")
; #define PG8_BAR __builtin_amdgcn_s_barrier()
; #define PG8_SCHED __builtin_amdgcn_sched_barrier(0)
; template <class Epi, class Sched, bool ALIGN_EPI = false, bool SP2 = false>
; __device__ __forceinline__ void gemm_phase(PG8_LAS unsigned char* lds, const Gemm g, const Sched& S, const Epi& E) {
;     ...
;             PG8_WAIT_V(8); PG8_WAIT_L(0); PG8_BAR; PG8_MMA(1, 0, At, B0); PG8_MMA(1, 1, At, B1); PG8_BAR; PG8_SCHED;
;             PG8_LDB(B0, 1, 0); PG8_LDB(B1, 1, 1); PG8_SCHED; PG8_LDA(At, 1, 0); PG8_STAGE(PG8_SA(0, 1), a2 + hstepA, voffA);
;             PG8_WAIT_V(8); PG8_WAIT_L(0); PG8_BAR; PG8_MMA(0, 0, At, B0); PG8_MMA(0, 1, At, B1); PG8_BAR; PG8_SCHED;
;             PG8_LDA(At, 1, 1); PG8_STAGE(PG8_SB(1, 0), b3, voffB); PG8_STAGE(PG8_SB(1, 1), b3 + hstepB, voffB); PG8_STAGE(PG8_SA(1, 0), a3, voffA);
;             PG8_WAIT_V(8); PG8_WAIT_L(0); PG8_BAR; PG8_MMA(1, 0, At, B0); PG8_MMA(1, 1, At, B1); PG8_BAR; PG8_SCHED;
	v_mfma_f32_16x16x32_bf16 v[60:63], v[128:131], v[202:205], v[60:63]
	v_mfma_f32_16x16x32_bf16 v[56:59], v[162:165], v[202:205], v[56:59]
	v_mfma_f32_16x16x32_bf16 v[44:47], v[128:131], v[210:213], v[44:47]
	v_mfma_f32_16x16x32_bf16 v[40:43], v[162:165], v[210:213], v[40:43]
	v_mfma_f32_16x16x32_bf16 v[28:31], v[128:131], v[218:221], v[28:31]
	v_mfma_f32_16x16x32_bf16 v[24:27], v[162:165], v[218:221], v[24:27]
	v_mfma_f32_16x16x32_bf16 v[12:15], v[128:131], v[226:229], v[12:15]
	v_mfma_f32_16x16x32_bf16 v[8:11], v[162:165], v[226:229], v[8:11]
	v_mfma_f32_16x16x32_bf16 v[60:63], v[132:135], v[206:209], v[60:63]
	v_mfma_f32_16x16x32_bf16 v[56:59], v[166:169], v[206:209], v[56:59]
	v_mfma_f32_16x16x32_bf16 v[44:47], v[132:135], v[214:217], v[44:47]
	v_mfma_f32_16x16x32_bf16 v[40:43], v[166:169], v[214:217], v[40:43]
	v_mfma_f32_16x16x32_bf16 v[28:31], v[132:135], v[222:225], v[28:31]
	v_mfma_f32_16x16x32_bf16 v[24:27], v[166:169], v[222:225], v[24:27]
	v_mfma_f32_16x16x32_bf16 v[12:15], v[132:135], v[230:233], v[12:15]
	v_mfma_f32_16x16x32_bf16 v[8:11], v[166:169], v[230:233], v[8:11]
	v_mfma_f32_16x16x32_bf16 v[52:55], v[184:187], v[202:205], v[52:55]
	v_mfma_f32_16x16x32_bf16 v[48:51], v[192:195], v[202:205], v[48:51]
	v_mfma_f32_16x16x32_bf16 v[36:39], v[184:187], v[210:213], v[36:39]
	v_mfma_f32_16x16x32_bf16 v[32:35], v[192:195], v[210:213], v[32:35]
	v_mfma_f32_16x16x32_bf16 v[20:23], v[184:187], v[218:221], v[20:23]
	v_mfma_f32_16x16x32_bf16 v[16:19], v[192:195], v[218:221], v[16:19]
	v_mfma_f32_16x16x32_bf16 v[4:7], v[184:187], v[226:229], v[4:7]
	v_mfma_f32_16x16x32_bf16 v[0:3], v[192:195], v[226:229], v[0:3]
	v_mfma_f32_16x16x32_bf16 v[52:55], v[188:191], v[206:209], v[52:55]
	v_mfma_f32_16x16x32_bf16 v[48:51], v[196:199], v[206:209], v[48:51]
	v_mfma_f32_16x16x32_bf16 v[36:39], v[188:191], v[214:217], v[36:39]
	v_mfma_f32_16x16x32_bf16 v[32:35], v[196:199], v[214:217], v[32:35]
	v_mfma_f32_16x16x32_bf16 v[20:23], v[188:191], v[222:225], v[20:23]
	v_mfma_f32_16x16x32_bf16 v[16:19], v[196:199], v[222:225], v[16:19]
	v_mfma_f32_16x16x32_bf16 v[4:7], v[188:191], v[230:233], v[4:7]
	v_mfma_f32_16x16x32_bf16 v[0:3], v[196:199], v[230:233], v[0:3]
	s_barrier
	ds_read_b128 v[128:131], v180
	ds_read_b128 v[132:135], v180 offset:1024
	ds_read_b128 v[162:165], v180 offset:2048
	ds_read_b128 v[166:169], v180 offset:3072
	ds_read_b128 v[184:187], v181
	ds_read_b128 v[188:191], v181 offset:1024
	ds_read_b128 v[192:195], v181 offset:2048
	ds_read_b128 v[196:199], v181 offset:3072
	ds_read_b128 v[202:205], v179 offset:32768
	ds_read_b128 v[206:209], v179 offset:33792
	ds_read_b128 v[210:213], v179 offset:34816
	ds_read_b128 v[214:217], v179 offset:35840
	ds_read_b128 v[218:221], v179 offset:36864
	ds_read_b128 v[222:225], v179 offset:37888
	ds_read_b128 v[226:229], v179 offset:38912
	ds_read_b128 v[230:233], v179 offset:39936
	s_add_u32 s46, s46, 0x10000
	s_addc_u32 s47, s47, 0
	s_mov_b32 m0, s59
	s_nop 0
	global_load_lds_dwordx4 v172, s[46:47]
	s_nop 0
	s_mov_b32 m0, s60
	s_nop 0
	global_load_lds_dwordx4 v174, s[46:47]
	s_waitcnt vmcnt(8)
	s_waitcnt lgkmcnt(0)
	s_barrier
	v_mfma_f32_16x16x32_bf16 v[124:127], v[128:131], v[202:205], v[124:127]
	v_mfma_f32_16x16x32_bf16 v[120:123], v[162:165], v[202:205], v[120:123]
	v_mfma_f32_16x16x32_bf16 v[108:111], v[128:131], v[210:213], v[108:111]
	v_mfma_f32_16x16x32_bf16 v[104:107], v[162:165], v[210:213], v[104:107]
	v_mfma_f32_16x16x32_bf16 v[92:95], v[128:131], v[218:221], v[92:95]
	v_mfma_f32_16x16x32_bf16 v[88:91], v[162:165], v[218:221], v[88:91]
	v_mfma_f32_16x16x32_bf16 v[76:79], v[128:131], v[226:229], v[76:79]
	v_mfma_f32_16x16x32_bf16 v[72:75], v[162:165], v[226:229], v[72:75]
	v_mfma_f32_16x16x32_bf16 v[124:127], v[132:135], v[206:209], v[124:127]
	v_mfma_f32_16x16x32_bf16 v[120:123], v[166:169], v[206:209], v[120:123]
	v_mfma_f32_16x16x32_bf16 v[108:111], v[132:135], v[214:217], v[108:111]
	v_mfma_f32_16x16x32_bf16 v[104:107], v[166:169], v[214:217], v[104:107]
	v_mfma_f32_16x16x32_bf16 v[92:95], v[132:135], v[222:225], v[92:95]
	v_mfma_f32_16x16x32_bf16 v[88:91], v[166:169], v[222:225], v[88:91]
	v_mfma_f32_16x16x32_bf16 v[76:79], v[132:135], v[230:233], v[76:79]
	v_mfma_f32_16x16x32_bf16 v[72:75], v[166:169], v[230:233], v[72:75]
	v_mfma_f32_16x16x32_bf16 v[116:119], v[184:187], v[202:205], v[116:119]
	v_mfma_f32_16x16x32_bf16 v[112:115], v[192:195], v[202:205], v[112:115]
	v_mfma_f32_16x16x32_bf16 v[100:103], v[184:187], v[210:213], v[100:103]
	v_mfma_f32_16x16x32_bf16 v[96:99], v[192:195], v[210:213], v[96:99]
	v_mfma_f32_16x16x32_bf16 v[84:87], v[184:187], v[218:221], v[84:87]
	v_mfma_f32_16x16x32_bf16 v[80:83], v[192:195], v[218:221], v[80:83]
	v_mfma_f32_16x16x32_bf16 v[68:71], v[184:187], v[226:229], v[68:71]
	v_mfma_f32_16x16x32_bf16 v[64:67], v[192:195], v[226:229], v[64:67]
	v_mfma_f32_16x16x32_bf16 v[116:119], v[188:191], v[206:209], v[116:119]
	v_mfma_f32_16x16x32_bf16 v[112:115], v[196:199], v[206:209], v[112:115]
	v_mfma_f32_16x16x32_bf16 v[100:103], v[188:191], v[214:217], v[100:103]
	v_mfma_f32_16x16x32_bf16 v[96:99], v[196:199], v[214:217], v[96:99]
	v_mfma_f32_16x16x32_bf16 v[84:87], v[188:191], v[222:225], v[84:87]
	v_mfma_f32_16x16x32_bf16 v[80:83], v[196:199], v[222:225], v[80:83]
	v_mfma_f32_16x16x32_bf16 v[68:71], v[188:191], v[230:233], v[68:71]
	v_mfma_f32_16x16x32_bf16 v[64:67], v[196:199], v[230:233], v[64:67]
	s_barrier
; #define PG8_STAGE(bufoff, gbase, voff) do { const unsigned long long gb_ = (unsigned long long)(gbase); _Pragma("unroll") for (int _i = 0; _i < 2; ++_i) { unsigned keep_; \
;         asm volatile("s_mov_b32 m0, %2\n\ts_nop 0\n\tglobal_load_lds_dwordx4 %0, %1" : : "v"((voff)[_i]), "s"(gb_), "s"((unsigned)(size_t)(lds + (bufoff) + ldsw + _i * 8192)) : "memory", "m0"); (void)keep_; } } while (0)
; #define PG8_LDA(dst, b, h) do { _Pragma("unroll") for (int m = 0; m < 4; ++m) _Pragma("unroll") for (int k = 0; k < 2; ++k) dst[m][k] = *(const PG8_LAS bf16x8*)(lds + PG8_SA(b, h) + aoff + m * 2048 + k * 1024); } while (0)
; #define PG8_MMA(ai, bj, At, Bt) do { __builtin_amdgcn_s_setprio(1); _Pragma("unroll") for (int m = 0; m < 4; ++m) _Pragma("unroll") for (int n = 0; n < 2; ++n) _Pragma("unroll") for (int k = 0; k < 2; ++k) \
;         acc[ai][bj][m][n] = __builtin_amdgcn_mfma_f32_16x16x32_bf16(Bt[n][k], At[m][k], acc[ai][bj][m][n], 0, 0, 0); __builtin_amdgcn_s_setprio(0); } while (0)
; #define PG8_WAIT_V(n) asm volatile("s_waitcnt vmcnt(" #n ")" ::: "memory")
; #define PG8_WAIT_L(n) asm volatile("s_waitcnt lgkmcnt(" #n ")" ::: "memory")
; #define PG8_BAR __builtin_amdgcn_s_barrier()
; #define PG8_SCHED __builtin_amdgcn_sched_barrier(0)
; template <class Epi, class Sched, bool ALIGN_EPI = false, bool SP2 = false>
; __device__ __forceinline__ void gemm_phase(PG8_LAS unsigned char* lds, const Gemm g, const Sched& S, const Epi& E) {
;     ...
;         for (int t = 0; t < nt; t += 2) {
;     ...
;             PG8_LDA(At, 1, 1); PG8_STAGE(PG8_SB(1, 0), b3, voffB); PG8_STAGE(PG8_SB(1, 1), b3 + hstepB, voffB); PG8_STAGE(PG8_SA(1, 0), a3, voffA);
;             PG8_WAIT_V(8); PG8_WAIT_L(0); PG8_BAR; PG8_MMA(1, 0, At, B0); PG8_MMA(1, 1, At, B1); PG8_BAR; PG8_SCHED;
	ds_read_b128 v[202:205], v179 offset:49152
	ds_read_b128 v[206:209], v179 offset:50176
	ds_read_b128 v[210:213], v179 offset:51200
	ds_read_b128 v[214:217], v179 offset:52224
	ds_read_b128 v[218:221], v179 offset:53248
	ds_read_b128 v[222:225], v179 offset:54272
	ds_read_b128 v[226:229], v179 offset:55296
	ds_read_b128 v[230:233], v179 offset:56320
	s_add_u32 s46, s44, 0x80
	s_addc_u32 s47, s45, 0
	s_mov_b32 m0, s62
	s_nop 0
	global_load_lds_dwordx4 v173, s[46:47]
	s_add_u32 s44, s44, 0x80080
	s_mov_b32 m0, s63
	s_nop 0
	global_load_lds_dwordx4 v175, s[46:47]
	s_addc_u32 s45, s45, 0
	s_mov_b32 m0, s66
	s_nop 0
	global_load_lds_dwordx4 v173, s[44:45]
	s_nop 0
	s_mov_b32 m0, s67
	s_nop 0
	global_load_lds_dwordx4 v175, s[44:45]
	s_nop 0
	s_mov_b32 m0, s64
	s_nop 0
	global_load_lds_dwordx4 v172, s[40:41]
	s_nop 0
	s_mov_b32 m0, s65
	s_nop 0
	global_load_lds_dwordx4 v174, s[40:41]
	s_waitcnt vmcnt(8)
	s_waitcnt lgkmcnt(0)
	s_barrier
	v_mfma_f32_16x16x32_bf16 v[60:63], v[128:131], v[202:205], v[60:63]
	v_mfma_f32_16x16x32_bf16 v[56:59], v[162:165], v[202:205], v[56:59]
	v_mfma_f32_16x16x32_bf16 v[44:47], v[128:131], v[210:213], v[44:47]
	v_mfma_f32_16x16x32_bf16 v[40:43], v[162:165], v[210:213], v[40:43]
	v_mfma_f32_16x16x32_bf16 v[28:31], v[128:131], v[218:221], v[28:31]
	v_mfma_f32_16x16x32_bf16 v[24:27], v[162:165], v[218:221], v[24:27]
	v_mfma_f32_16x16x32_bf16 v[12:15], v[128:131], v[226:229], v[12:15]
	v_mfma_f32_16x16x32_bf16 v[8:11], v[162:165], v[226:229], v[8:11]
	v_mfma_f32_16x16x32_bf16 v[60:63], v[132:135], v[206:209], v[60:63]
	v_mfma_f32_16x16x32_bf16 v[56:59], v[166:169], v[206:209], v[56:59]
	v_mfma_f32_16x16x32_bf16 v[44:47], v[132:135], v[214:217], v[44:47]
	v_mfma_f32_16x16x32_bf16 v[40:43], v[166:169], v[214:217], v[40:43]
	v_mfma_f32_16x16x32_bf16 v[28:31], v[132:135], v[222:225], v[28:31]
	v_mfma_f32_16x16x32_bf16 v[24:27], v[166:169], v[222:225], v[24:27]
	v_mfma_f32_16x16x32_bf16 v[12:15], v[132:135], v[230:233], v[12:15]
	v_mfma_f32_16x16x32_bf16 v[8:11], v[166:169], v[230:233], v[8:11]
	v_mfma_f32_16x16x32_bf16 v[52:55], v[184:187], v[202:205], v[52:55]
	v_mfma_f32_16x16x32_bf16 v[48:51], v[192:195], v[202:205], v[48:51]
	v_mfma_f32_16x16x32_bf16 v[36:39], v[184:187], v[210:213], v[36:39]
	v_mfma_f32_16x16x32_bf16 v[32:35], v[192:195], v[210:213], v[32:35]
	v_mfma_f32_16x16x32_bf16 v[20:23], v[184:187], v[218:221], v[20:23]
	v_mfma_f32_16x16x32_bf16 v[16:19], v[192:195], v[218:221], v[16:19]
	v_mfma_f32_16x16x32_bf16 v[4:7], v[184:187], v[226:229], v[4:7]
	v_mfma_f32_16x16x32_bf16 v[0:3], v[192:195], v[226:229], v[0:3]
	v_mfma_f32_16x16x32_bf16 v[52:55], v[188:191], v[206:209], v[52:55]
	v_mfma_f32_16x16x32_bf16 v[48:51], v[196:199], v[206:209], v[48:51]
	v_mfma_f32_16x16x32_bf16 v[36:39], v[188:191], v[214:217], v[36:39]
	v_mfma_f32_16x16x32_bf16 v[32:35], v[196:199], v[214:217], v[32:35]
	v_mfma_f32_16x16x32_bf16 v[20:23], v[188:191], v[222:225], v[20:23]
	v_mfma_f32_16x16x32_bf16 v[16:19], v[196:199], v[222:225], v[16:19]
	v_mfma_f32_16x16x32_bf16 v[4:7], v[188:191], v[230:233], v[4:7]
	v_mfma_f32_16x16x32_bf16 v[0:3], v[196:199], v[230:233], v[0:3]
	s_barrier
	s_add_i32 s76, s76, 2
	s_add_i32 s77, s77, 0x10000
	s_cmp_gt_u32 s76, 29
	s_mov_b64 s[40:41], s[42:43]
	s_cbranch_scc0 .LBB0_2228
	s_and_b64 vcc, exec, s[26:27]
	s_cbranch_vccz .LBB0_2231
	s_barrier
